# attention: the unit's Q rows staged once per workgroup in LDS too (Q fragments via ds_read), on top of the shared-LDS branch 0
# speedup vs baseline: 1.0146x; 1.0146x over previous
.Latt_entry:
	s_mov_b64 exec, -1
	v_readlane_b32 s4, v254, 0
	v_readlane_b32 s5, v254, 1
	v_readlane_b32 s6, v254, 42
	v_readlane_b32 s7, v254, 43
	v_readlane_b32 s8, v254, 46
	v_readlane_b32 s10, v254, 53
	v_readfirstlane_b32 s0, v145
	s_movk_i32 s78, 0x90
	s_movk_i32 s79, 0x110
	s_mov_b32 s80, 0x12100
	s_movk_i32 s82, 0x4000
	s_movk_i32 s83, 0x1000
	s_mov_b32 s84, 0xc000
	s_mov_b32 s85, 0x7ffff000
	s_lshr_b32 s0, s0, 6
	s_mul_i32 s1, s0, 0x1200
	s_add_i32 s1, s1, 0x12500
	s_mov_b32 s37, 0
	v_and_b32_e32 v142, 63, v145
	v_and_b32_e32 v160, 15, v145
	v_bfe_u32 v134, v145, 4, 2
	v_lshlrev_b32_e32 v161, 4, v134
	v_lshlrev_b32_e32 v169, 2, v134
	v_and_b32_e32 v135, 7, v145
	v_lshlrev_b32_e32 v162, 4, v135
	v_bfe_u32 v164, v145, 3, 3
	v_mad_u32_u24 v165, v164, s78, v162
	v_add_u32_e32 v165, s1, v165
	v_bfe_u32 v134, v145, 2, 2
	v_add_u32_e32 v134, v134, v169
	v_and_b32_e32 v135, 3, v145
	v_lshlrev_b32_e32 v135, 3, v135
	v_mad_u32_u24 v166, v134, s78, v135
	v_add_u32_e32 v166, s1, v166
	v_xor_b32_e32 v134, 16, v142
	v_lshlrev_b32_e32 v167, 2, v134
	v_xor_b32_e32 v134, 32, v142
	v_lshlrev_b32_e32 v168, 2, v134
	v_sub_u32_e32 v134, v169, v160
	v_cmp_ge_i32_e64 s[54:55], v134, 0
	v_cmp_le_i32_e64 s[62:63], v134, 0
	v_cmp_ge_i32_e64 s[56:57], v134, -1
	v_cmp_le_i32_e64 s[64:65], v134, -1
	v_cmp_ge_i32_e64 s[58:59], v134, -2
	v_cmp_le_i32_e64 s[66:67], v134, -2
	v_cmp_ge_i32_e64 s[60:61], v134, -3
	v_cmp_le_i32_e64 s[68:69], v134, -3
	v_lshrrev_b32_e32 v134, 1, v145
	v_lshrrev_b32_e32 v135, 4, v134
	v_add_u32_e32 v135, v135, v134
	v_and_b32_e32 v136, 1, v145
	v_lshlrev_b32_e32 v137, 7, v136
	v_mad_u32_u24 v170, v135, s79, v137
	v_lshl_add_u32 v171, v134, 2, s80
	v_lshlrev_b32_e32 v135, 11, v134
	v_lshl_add_u32 v172, v136, 6, v135
	s_lshl_b32 s2, s0, 5
	v_add_u32_e32 v134, s2, v160
	v_mad_u32_u24 v149, v134, s78, v161
	v_bfe_u32 v134, v145, 2, 2
	v_add_u32_e32 v134, v134, v169
	v_add_u32_e32 v134, s2, v134
	v_and_b32_e32 v135, 3, v145
	v_lshlrev_b32_e32 v135, 3, v135
	v_mad_u32_u24 v151, v134, s78, v135
	v_add_u32_e32 v151, 0xd800, v151
	s_mul_i32 s2, s0, 48
	v_add_u32_e32 v134, s2, v164
	v_mad_u32_u24 v253, v134, s78, v162
	v_mov_b32_e32 v130, 0
	v_mov_b32_e32 v131, 0
	v_mov_b32_e32 v184, 0
	v_mov_b32_e32 v185, 0
	s_lshr_b32 s2, s10, 3
	s_and_b32 s3, s10, 7
	s_and_b32 s30, s2, 31
	s_lshl_b32 s31, s3, 5
	s_or_b32 s31, s31, s30
	s_lshr_b32 s30, s10, 8
	s_cmp_eq_u32 s8, 0x100
	s_cselect_b32 s2, s31, s2
	s_cselect_b32 s17, s30, s3
	s_lshl_b32 s16, s2, 8
	s_cmp_lt_u32 s2, 0x80
	s_cselect_b32 s12, s82, s83
	s_cselect_b32 s13, 12, 10
	s_cselect_b32 s3, s84, s85
	s_and_b32 s3, s16, s3
	s_sub_i32 s15, s16, s3
	s_lshr_b32 s30, s12, 4
	s_add_i32 s14, s30, -1
	s_lshl_b32 s30, s17, 23
	s_lshl_b32 s3, s3, 7
	s_add_u32 s30, s30, s3
	s_add_u32 s18, s4, s30
	s_addc_u32 s19, s5, 0
	s_add_u32 s20, s18, 0x4000000
	s_addc_u32 s21, s19, 0
	s_add_u32 s22, s18, 0x8000000
	s_addc_u32 s23, s19, 0
	s_lshl_b32 s2, s0, 5
	s_add_i32 s42, s15, s2
	s_mov_b32 s43, 0
	v_add_u32_e32 v134, s42, v160
	v_add_u32_e32 v134, s43, v134
	v_subrev_u32_e32 v135, s15, v134
	v_lshrrev_b32_e32 v136, 4, v135
	v_add_u32_e32 v136, v136, v135
	v_mad_u32_u24 v176, v136, s79, v161
	v_lshl_add_u32 v177, v135, 2, s80
	s_sub_i32 s2, s42, 64
	v_add_u32_e32 v178, s2, v169
	v_and_b32_e32 v135, 3, v134
	v_lshlrev_b32_e32 v135, s13, v135
	v_lshrrev_b32_e32 v136, 2, v134
	v_add_u32_e32 v135, v135, v136
	v_lshl_add_u32 v135, v135, 7, v161
	v_add_u32_e32 v137, 16, v134
	v_and_b32_e32 v135, 3, v137
	v_lshlrev_b32_e32 v135, s13, v135
	v_lshrrev_b32_e32 v136, 2, v137
	v_add_u32_e32 v135, v135, v136
	v_lshl_add_u32 v135, v135, 7, v161
	s_mul_i32 s2, s0, 48
	s_add_i32 s2, s2, s15
	s_add_i32 s2, s2, -64
	v_add_u32_e32 v138, s2, v164
	v_and_b32_e32 v139, 3, v138
	v_lshlrev_b32_e32 v139, s13, v139
	v_bfe_u32 v140, v138, 2, 2
	v_add_u32_e32 v139, v139, v140
	v_lshl_add_u32 v139, v139, 7, v162
	v_ashrrev_i32_e32 v138, 4, v138
	v_med3_i32 v138, v138, 0, s14
	v_lshl_add_u32 v138, v138, 9, v139
	global_load_dwordx4 v[0:3], v138, s[20:21]
	s_mul_i32 s2, s0, 48
	s_add_i32 s2, s2, s15
	s_add_i32 s2, s2, -56
	v_add_u32_e32 v138, s2, v164
	v_and_b32_e32 v139, 3, v138
	v_lshlrev_b32_e32 v139, s13, v139
	v_bfe_u32 v140, v138, 2, 2
	v_add_u32_e32 v139, v139, v140
	v_lshl_add_u32 v139, v139, 7, v162
	v_ashrrev_i32_e32 v138, 4, v138
	v_med3_i32 v138, v138, 0, s14
	v_lshl_add_u32 v138, v138, 9, v139
	global_load_dwordx4 v[4:7], v138, s[20:21]
	s_mul_i32 s2, s0, 48
	s_add_i32 s2, s2, s15
	s_add_i32 s2, s2, -48
	v_add_u32_e32 v138, s2, v164
	v_and_b32_e32 v139, 3, v138
	v_lshlrev_b32_e32 v139, s13, v139
	v_bfe_u32 v140, v138, 2, 2
	v_add_u32_e32 v139, v139, v140
	v_lshl_add_u32 v139, v139, 7, v162
	v_ashrrev_i32_e32 v138, 4, v138
	v_med3_i32 v138, v138, 0, s14
	v_lshl_add_u32 v138, v138, 9, v139
	global_load_dwordx4 v[8:11], v138, s[20:21]
	s_mul_i32 s2, s0, 48
	s_add_i32 s2, s2, s15
	s_add_i32 s2, s2, -40
	v_add_u32_e32 v138, s2, v164
	v_and_b32_e32 v139, 3, v138
	v_lshlrev_b32_e32 v139, s13, v139
	v_bfe_u32 v140, v138, 2, 2
	v_add_u32_e32 v139, v139, v140
	v_lshl_add_u32 v139, v139, 7, v162
	v_ashrrev_i32_e32 v138, 4, v138
	v_med3_i32 v138, v138, 0, s14
	v_lshl_add_u32 v138, v138, 9, v139
	global_load_dwordx4 v[12:15], v138, s[20:21]
	s_mul_i32 s2, s0, 48
	s_add_i32 s2, s2, s15
	s_add_i32 s2, s2, -32
	v_add_u32_e32 v138, s2, v164
	v_and_b32_e32 v139, 3, v138
	v_lshlrev_b32_e32 v139, s13, v139
	v_bfe_u32 v140, v138, 2, 2
	v_add_u32_e32 v139, v139, v140
	v_lshl_add_u32 v139, v139, 7, v162
	v_ashrrev_i32_e32 v138, 4, v138
	v_med3_i32 v138, v138, 0, s14
	v_lshl_add_u32 v138, v138, 9, v139
	global_load_dwordx4 v[16:19], v138, s[20:21]
	s_mul_i32 s2, s0, 48
	s_add_i32 s2, s2, s15
	s_add_i32 s2, s2, -24
	v_add_u32_e32 v138, s2, v164
	v_and_b32_e32 v139, 3, v138
	v_lshlrev_b32_e32 v139, s13, v139
	v_bfe_u32 v140, v138, 2, 2
	v_add_u32_e32 v139, v139, v140
	v_lshl_add_u32 v139, v139, 7, v162
	v_ashrrev_i32_e32 v138, 4, v138
	v_med3_i32 v138, v138, 0, s14
	v_lshl_add_u32 v138, v138, 9, v139
	global_load_dwordx4 v[20:23], v138, s[20:21]
	s_mul_i32 s2, s0, 48
	s_add_i32 s2, s2, s15
	s_add_i32 s2, s2, -64
	v_add_u32_e32 v138, s2, v164
	v_and_b32_e32 v139, 3, v138
	v_lshlrev_b32_e32 v139, s13, v139
	v_bfe_u32 v140, v138, 2, 2
	v_add_u32_e32 v139, v139, v140
	v_lshl_add_u32 v139, v139, 7, v162
	v_ashrrev_i32_e32 v138, 4, v138
	v_med3_i32 v138, v138, 0, s14
	v_lshl_add_u32 v138, v138, 9, v139
	global_load_dwordx4 v[24:27], v138, s[22:23]
	s_mul_i32 s2, s0, 48
	s_add_i32 s2, s2, s15
	s_add_i32 s2, s2, -56
	v_add_u32_e32 v138, s2, v164
	v_and_b32_e32 v139, 3, v138
	v_lshlrev_b32_e32 v139, s13, v139
	v_bfe_u32 v140, v138, 2, 2
	v_add_u32_e32 v139, v139, v140
	v_lshl_add_u32 v139, v139, 7, v162
	v_ashrrev_i32_e32 v138, 4, v138
	v_med3_i32 v138, v138, 0, s14
	v_lshl_add_u32 v138, v138, 9, v139
	global_load_dwordx4 v[28:31], v138, s[22:23]
	s_mul_i32 s2, s0, 48
	s_add_i32 s2, s2, s15
	s_add_i32 s2, s2, -48
	v_add_u32_e32 v138, s2, v164
	v_and_b32_e32 v139, 3, v138
	v_lshlrev_b32_e32 v139, s13, v139
	v_bfe_u32 v140, v138, 2, 2
	v_add_u32_e32 v139, v139, v140
	v_lshl_add_u32 v139, v139, 7, v162
	v_ashrrev_i32_e32 v138, 4, v138
	v_med3_i32 v138, v138, 0, s14
	v_lshl_add_u32 v138, v138, 9, v139
	global_load_dwordx4 v[32:35], v138, s[22:23]
	s_mul_i32 s2, s0, 48
	s_add_i32 s2, s2, s15
	s_add_i32 s2, s2, -40
	v_add_u32_e32 v138, s2, v164
	v_and_b32_e32 v139, 3, v138
	v_lshlrev_b32_e32 v139, s13, v139
	v_bfe_u32 v140, v138, 2, 2
	v_add_u32_e32 v139, v139, v140
	v_lshl_add_u32 v139, v139, 7, v162
	v_ashrrev_i32_e32 v138, 4, v138
	v_med3_i32 v138, v138, 0, s14
	v_lshl_add_u32 v138, v138, 9, v139
	global_load_dwordx4 v[36:39], v138, s[22:23]
	s_mul_i32 s2, s0, 48
	s_add_i32 s2, s2, s15
	s_add_i32 s2, s2, -32
	v_add_u32_e32 v138, s2, v164
	v_and_b32_e32 v139, 3, v138
	v_lshlrev_b32_e32 v139, s13, v139
	v_bfe_u32 v140, v138, 2, 2
	v_add_u32_e32 v139, v139, v140
	v_lshl_add_u32 v139, v139, 7, v162
	v_ashrrev_i32_e32 v138, 4, v138
	v_med3_i32 v138, v138, 0, s14
	v_lshl_add_u32 v138, v138, 9, v139
	global_load_dwordx4 v[40:43], v138, s[22:23]
	s_mul_i32 s2, s0, 48
	s_add_i32 s2, s2, s15
	s_add_i32 s2, s2, -24
	v_add_u32_e32 v138, s2, v164
	v_and_b32_e32 v139, 3, v138
	v_lshlrev_b32_e32 v139, s13, v139
	v_bfe_u32 v140, v138, 2, 2
	v_add_u32_e32 v139, v139, v140
	v_lshl_add_u32 v139, v139, 7, v162
	v_ashrrev_i32_e32 v138, 4, v138
	v_med3_i32 v138, v138, 0, s14
	v_lshl_add_u32 v138, v138, 9, v139
	global_load_dwordx4 v[44:47], v138, s[22:23]
	s_lshl_b32 s2, s0, 5
	s_add_i32 s2, s2, s15
	s_add_i32 s2, s2, 0
	v_add_u32_e32 v138, s2, v164
	v_and_b32_e32 v139, 3, v138
	v_lshlrev_b32_e32 v139, s13, v139
	v_lshrrev_b32_e32 v140, 2, v138
	v_add_u32_e32 v139, v139, v140
	v_lshl_add_u32 v139, v139, 7, v162
	global_load_dwordx4 v[48:51], v139, s[18:19]
	s_lshl_b32 s2, s0, 5
	s_add_i32 s2, s2, s15
	s_add_i32 s2, s2, 8
	v_add_u32_e32 v138, s2, v164
	v_and_b32_e32 v139, 3, v138
	v_lshlrev_b32_e32 v139, s13, v139
	v_lshrrev_b32_e32 v140, 2, v138
	v_add_u32_e32 v139, v139, v140
	v_lshl_add_u32 v139, v139, 7, v162
	global_load_dwordx4 v[52:55], v139, s[18:19]
	s_lshl_b32 s2, s0, 5
	s_add_i32 s2, s2, s15
	s_add_i32 s2, s2, 16
	v_add_u32_e32 v138, s2, v164
	v_and_b32_e32 v139, 3, v138
	v_lshlrev_b32_e32 v139, s13, v139
	v_lshrrev_b32_e32 v140, 2, v138
	v_add_u32_e32 v139, v139, v140
	v_lshl_add_u32 v139, v139, 7, v162
	global_load_dwordx4 v[56:59], v139, s[18:19]
	s_lshl_b32 s2, s0, 5
	s_add_i32 s2, s2, s15
	s_add_i32 s2, s2, 24
	v_add_u32_e32 v138, s2, v164
	v_and_b32_e32 v139, 3, v138
	v_lshlrev_b32_e32 v139, s13, v139
	v_lshrrev_b32_e32 v140, 2, v138
	v_add_u32_e32 v139, v139, v140
	v_lshl_add_u32 v139, v139, 7, v162
	global_load_dwordx4 v[60:63], v139, s[18:19]
	s_waitcnt vmcnt(0)
.Latt_unit:
	s_mov_b32 s33, s12
	s_mov_b32 s34, s15
	s_mov_b32 s35, s16
	s_mov_b32 s36, s17
	s_mov_b32 s38, s14
	s_mov_b32 s39, s13
	s_mov_b32 s24, s20
	s_mov_b32 s25, s21
	s_mov_b32 s26, s22
	s_mov_b32 s27, s23
	s_mov_b32 s40, s42
	s_mov_b32 s41, s43
	v_mov_b32_e32 v173, v176
	v_mov_b32_e32 v174, v177
	v_mov_b32_e32 v175, v178
	v_mov_b32_e32 v179, v183
	v_mov_b32_e32 v182, v252
	s_lshr_b32 s44, s33, 0
	s_lshr_b32 s2, s0, 2
	s_lshl_b32 s2, s2, 5
	s_lshr_b32 s3, s15, 2
	s_add_i32 s42, s3, s2
	s_and_b32 s43, s0, 3
	s_waitcnt vmcnt(4)
	ds_write_b128 v253, v[0:3]
	ds_write_b128 v253, v[4:7] offset:1152
	ds_write_b128 v253, v[8:11] offset:2304
	ds_write_b128 v253, v[12:15] offset:3456
	ds_write_b128 v253, v[16:19] offset:4608
	ds_write_b128 v253, v[20:23] offset:5760
	ds_write_b128 v253, v[24:27] offset:55296
	ds_write_b128 v253, v[28:31] offset:56448
	ds_write_b128 v253, v[32:35] offset:57600
	ds_write_b128 v253, v[36:39] offset:58752
	ds_write_b128 v253, v[40:43] offset:59904
	ds_write_b128 v253, v[44:47] offset:61056
	s_lshl_b32 s2, s0, 12
	s_add_i32 s2, s2, 0x1b500
	v_and_b32_e32 v141, 63, v145
	v_lshl_add_u32 v141, v141, 4, s2
	ds_write_b128 v141, v[48:51]
	ds_write_b128 v141, v[52:55] offset:1024
	ds_write_b128 v141, v[56:59] offset:2048
	ds_write_b128 v141, v[60:63] offset:3072
	s_waitcnt lgkmcnt(0)
	s_barrier
	v_add_u32_e32 v134, s42, v160
	v_lshlrev_b32_e32 v134, 2, v134
	v_add_u32_e32 v134, s43, v134
	v_subrev_u32_e32 v135, s15, v134
	v_lshrrev_b32_e32 v136, 4, v135
	v_add_u32_e32 v136, v136, v135
	v_mad_u32_u24 v176, v136, s79, v161
	v_lshl_add_u32 v177, v135, 2, s80
	s_sub_i32 s2, s42, 64
	v_add_u32_e32 v178, s2, v169
	v_subrev_u32_e32 v134, 0x100, v134
	v_and_b32_e32 v137, 3, v134
	v_lshlrev_b32_e32 v137, s13, v137
	v_bfe_u32 v135, v134, 2, 2
	v_add_u32_e32 v137, v137, v135
	v_lshl_add_u32 v183, v137, 7, v161
	v_ashrrev_i32_e32 v252, 4, v134
	v_med3_i32 v136, v252, 0, s14
	v_lshl_add_u32 v136, v136, 9, v183
	global_load_dwordx4 v[0:3], v136, s[20:21]
	global_load_dwordx4 v[4:7], v136, s[20:21] offset:64
	v_add_u32_e32 v135, 4, v252
	v_med3_i32 v135, v135, 0, s14
	v_lshl_add_u32 v135, v135, 9, v183
	global_load_dwordx4 v[8:11], v135, s[20:21]
	global_load_dwordx4 v[12:15], v135, s[20:21] offset:64
	v_add_u32_e32 v136, 8, v252
	v_med3_i32 v136, v136, 0, s14
	v_lshl_add_u32 v136, v136, 9, v183
	global_load_dwordx4 v[16:19], v136, s[20:21]
	global_load_dwordx4 v[20:23], v136, s[20:21] offset:64
	v_add_u32_e32 v135, 12, v252
	v_med3_i32 v135, v135, 0, s14
	v_lshl_add_u32 v135, v135, 9, v183
	global_load_dwordx4 v[24:27], v135, s[20:21]
	global_load_dwordx4 v[28:31], v135, s[20:21] offset:64
	v_add_u32_e32 v136, 16, v252
	v_med3_i32 v136, v136, 0, s14
	v_lshl_add_u32 v136, v136, 9, v183
	global_load_dwordx4 v[32:35], v136, s[20:21]
	global_load_dwordx4 v[36:39], v136, s[20:21] offset:64
	v_add_u32_e32 v135, 20, v252
	v_med3_i32 v135, v135, 0, s14
	v_lshl_add_u32 v135, v135, 9, v183
	global_load_dwordx4 v[40:43], v135, s[20:21]
	global_load_dwordx4 v[44:47], v135, s[20:21] offset:64
	s_add_i32 s2, s42, -64
	v_add_u32_e32 v138, s2, v164
	v_lshlrev_b32_e32 v138, 2, v138
	v_add_u32_e32 v138, s43, v138
	v_and_b32_e32 v139, 3, v138
	v_lshlrev_b32_e32 v139, s13, v139
	v_bfe_u32 v140, v138, 2, 2
	v_add_u32_e32 v139, v139, v140
	v_lshl_add_u32 v139, v139, 7, v162
	v_ashrrev_i32_e32 v138, 4, v138
	v_med3_i32 v138, v138, 0, s14
	v_lshl_add_u32 v138, v138, 9, v139
	global_load_dwordx4 v[64:67], v138, s[22:23]
	s_add_i32 s2, s42, -56
	v_add_u32_e32 v138, s2, v164
	v_lshlrev_b32_e32 v138, 2, v138
	v_add_u32_e32 v138, s43, v138
	v_and_b32_e32 v139, 3, v138
	v_lshlrev_b32_e32 v139, s13, v139
	v_bfe_u32 v140, v138, 2, 2
	v_add_u32_e32 v139, v139, v140
	v_lshl_add_u32 v139, v139, 7, v162
	v_ashrrev_i32_e32 v138, 4, v138
	v_med3_i32 v138, v138, 0, s14
	v_lshl_add_u32 v138, v138, 9, v139
	global_load_dwordx4 v[68:71], v138, s[22:23]
	s_add_i32 s2, s42, -48
	v_add_u32_e32 v138, s2, v164
	v_lshlrev_b32_e32 v138, 2, v138
	v_add_u32_e32 v138, s43, v138
	v_and_b32_e32 v139, 3, v138
	v_lshlrev_b32_e32 v139, s13, v139
	v_bfe_u32 v140, v138, 2, 2
	v_add_u32_e32 v139, v139, v140
	v_lshl_add_u32 v139, v139, 7, v162
	v_ashrrev_i32_e32 v138, 4, v138
	v_med3_i32 v138, v138, 0, s14
	v_lshl_add_u32 v138, v138, 9, v139
	global_load_dwordx4 v[72:75], v138, s[22:23]
	s_add_i32 s2, s42, -40
	v_add_u32_e32 v138, s2, v164
	v_lshlrev_b32_e32 v138, 2, v138
	v_add_u32_e32 v138, s43, v138
	v_and_b32_e32 v139, 3, v138
	v_lshlrev_b32_e32 v139, s13, v139
	v_bfe_u32 v140, v138, 2, 2
	v_add_u32_e32 v139, v139, v140
	v_lshl_add_u32 v139, v139, 7, v162
	v_ashrrev_i32_e32 v138, 4, v138
	v_med3_i32 v138, v138, 0, s14
	v_lshl_add_u32 v138, v138, 9, v139
	global_load_dwordx4 v[76:79], v138, s[22:23]
	s_add_i32 s2, s42, -32
	v_add_u32_e32 v138, s2, v164
	v_lshlrev_b32_e32 v138, 2, v138
	v_add_u32_e32 v138, s43, v138
	v_and_b32_e32 v139, 3, v138
	v_lshlrev_b32_e32 v139, s13, v139
	v_bfe_u32 v140, v138, 2, 2
	v_add_u32_e32 v139, v139, v140
	v_lshl_add_u32 v139, v139, 7, v162
	v_ashrrev_i32_e32 v138, 4, v138
	v_med3_i32 v138, v138, 0, s14
	v_lshl_add_u32 v138, v138, 9, v139
	global_load_dwordx4 v[80:83], v138, s[22:23]
	s_add_i32 s2, s42, -24
	v_add_u32_e32 v138, s2, v164
	v_lshlrev_b32_e32 v138, 2, v138
	v_add_u32_e32 v138, s43, v138
	v_and_b32_e32 v139, 3, v138
	v_lshlrev_b32_e32 v139, s13, v139
	v_bfe_u32 v140, v138, 2, 2
	v_add_u32_e32 v139, v139, v140
	v_lshl_add_u32 v139, v139, 7, v162
	v_ashrrev_i32_e32 v138, 4, v138
	v_med3_i32 v138, v138, 0, s14
	v_lshl_add_u32 v138, v138, 9, v139
	global_load_dwordx4 v[84:87], v138, s[22:23]
	s_add_i32 s2, s42, -16
	v_add_u32_e32 v138, s2, v164
	v_lshlrev_b32_e32 v138, 2, v138
	v_add_u32_e32 v138, s43, v138
	v_and_b32_e32 v139, 3, v138
	v_lshlrev_b32_e32 v139, s13, v139
	v_bfe_u32 v140, v138, 2, 2
	v_add_u32_e32 v139, v139, v140
	v_lshl_add_u32 v139, v139, 7, v162
	v_ashrrev_i32_e32 v138, 4, v138
	v_med3_i32 v138, v138, 0, s14
	v_lshl_add_u32 v138, v138, 9, v139
	global_load_dwordx4 v[88:91], v138, s[22:23]
	s_add_i32 s2, s42, -8
	v_add_u32_e32 v138, s2, v164
	v_lshlrev_b32_e32 v138, 2, v138
	v_add_u32_e32 v138, s43, v138
	v_and_b32_e32 v139, 3, v138
	v_lshlrev_b32_e32 v139, s13, v139
	v_bfe_u32 v140, v138, 2, 2
	v_add_u32_e32 v139, v139, v140
	v_lshl_add_u32 v139, v139, 7, v162
	v_ashrrev_i32_e32 v138, 4, v138
	v_med3_i32 v138, v138, 0, s14
	v_lshl_add_u32 v138, v138, 9, v139
	global_load_dwordx4 v[92:95], v138, s[22:23]
	s_add_i32 s2, s42, 0
	v_add_u32_e32 v138, s2, v164
	v_lshlrev_b32_e32 v138, 2, v138
	v_add_u32_e32 v138, s43, v138
	v_and_b32_e32 v139, 3, v138
	v_lshlrev_b32_e32 v139, s13, v139
	v_bfe_u32 v140, v138, 2, 2
	v_add_u32_e32 v139, v139, v140
	v_lshl_add_u32 v139, v139, 7, v162
	v_ashrrev_i32_e32 v138, 4, v138
	v_med3_i32 v138, v138, 0, s14
	v_lshl_add_u32 v138, v138, 9, v139
	global_load_dwordx4 v[96:99], v138, s[22:23]
	s_add_i32 s2, s42, 8
	v_add_u32_e32 v138, s2, v164
	v_lshlrev_b32_e32 v138, 2, v138
	v_add_u32_e32 v138, s43, v138
	v_and_b32_e32 v139, 3, v138
	v_lshlrev_b32_e32 v139, s13, v139
	v_bfe_u32 v140, v138, 2, 2
	v_add_u32_e32 v139, v139, v140
	v_lshl_add_u32 v139, v139, 7, v162
	v_ashrrev_i32_e32 v138, 4, v138
	v_med3_i32 v138, v138, 0, s14
	v_lshl_add_u32 v138, v138, 9, v139
	global_load_dwordx4 v[100:103], v138, s[22:23]
	s_add_i32 s2, s42, 16
	v_add_u32_e32 v138, s2, v164
	v_lshlrev_b32_e32 v138, 2, v138
	v_add_u32_e32 v138, s43, v138
	v_and_b32_e32 v139, 3, v138
	v_lshlrev_b32_e32 v139, s13, v139
	v_bfe_u32 v140, v138, 2, 2
	v_add_u32_e32 v139, v139, v140
	v_lshl_add_u32 v139, v139, 7, v162
	v_ashrrev_i32_e32 v138, 4, v138
	v_med3_i32 v138, v138, 0, s14
	v_lshl_add_u32 v138, v138, 9, v139
	global_load_dwordx4 v[104:107], v138, s[22:23]
	s_add_i32 s2, s42, 24
	v_add_u32_e32 v138, s2, v164
	v_lshlrev_b32_e32 v138, 2, v138
	v_add_u32_e32 v138, s43, v138
	v_and_b32_e32 v139, 3, v138
	v_lshlrev_b32_e32 v139, s13, v139
	v_bfe_u32 v140, v138, 2, 2
	v_add_u32_e32 v139, v139, v140
	v_lshl_add_u32 v139, v139, 7, v162
	v_ashrrev_i32_e32 v138, 4, v138
	v_med3_i32 v138, v138, 0, s14
	v_lshl_add_u32 v138, v138, 9, v139
	global_load_dwordx4 v[108:111], v138, s[22:23]
	v_subrev_u32_e32 v143, s80, v174
	v_lshl_add_u32 v143, v143, 5, v161
	v_add_u32_e32 v143, 0x1b500, v143
	ds_read_b128 v[48:51], v143
	ds_read_b128 v[52:55], v143 offset:64
	ds_read_b128 v[56:59], v143 offset:2048
	ds_read_b128 v[60:63], v143 offset:2112
	s_waitcnt lgkmcnt(0)
	v_mov_b32_e32 v132, 0
	v_mov_b32_e32 v133, 0
	ds_read_b128 v[204:207], v149
	ds_read_b128 v[208:211], v149 offset:64
	ds_read_b128 v[212:215], v149 offset:2304
	ds_read_b128 v[216:219], v149 offset:2368
	ds_read_b128 v[220:223], v149 offset:4608
	ds_read_b128 v[224:227], v149 offset:4672
	ds_read_b128 v[228:231], v149 offset:6912
	ds_read_b128 v[232:235], v149 offset:6976
	s_waitcnt lgkmcnt(0)
	v_mfma_f32_16x16x32_bf16 v[236:239], v[204:207], v[48:51], 0
	v_mfma_f32_16x16x32_bf16 v[236:239], v[208:211], v[52:55], v[236:239]
	v_mfma_f32_16x16x32_bf16 v[240:243], v[212:215], v[48:51], 0
	v_mfma_f32_16x16x32_bf16 v[240:243], v[216:219], v[52:55], v[240:243]
	v_mfma_f32_16x16x32_bf16 v[248:251], v[212:215], v[56:59], 0
	v_mfma_f32_16x16x32_bf16 v[248:251], v[216:219], v[60:63], v[248:251]
	s_nop 7
	v_min_f32_e32 v152, 0x42a00000, v236
	v_min_f32_e32 v153, 0x42a00000, v237
	v_min_f32_e32 v154, 0x42a00000, v238
	v_min_f32_e32 v155, 0x42a00000, v239
	v_mfma_f32_16x16x32_bf16 v[236:239], v[220:223], v[48:51], 0
	v_mfma_f32_16x16x32_bf16 v[236:239], v[224:227], v[52:55], v[236:239]
	v_mfma_f32_16x16x32_bf16 v[244:247], v[220:223], v[56:59], 0
	v_mfma_f32_16x16x32_bf16 v[244:247], v[224:227], v[60:63], v[244:247]
	ds_read_b128 v[204:207], v149 offset:9216
	ds_read_b128 v[208:211], v149 offset:9280
	v_mul_f32_e32 v152, 0x3fb8aa3b, v152
	v_mul_f32_e32 v153, 0x3fb8aa3b, v153
	v_mul_f32_e32 v154, 0x3fb8aa3b, v154
	v_mul_f32_e32 v155, 0x3fb8aa3b, v155
	v_exp_f32_e32 v152, v152
	v_exp_f32_e32 v153, v153
	v_exp_f32_e32 v154, v154
	v_exp_f32_e32 v155, v155
	v_add_u32_e32 v138, 0, v175
	v_add_u32_e32 v139, 1, v175
	v_add_u32_e32 v140, 2, v175
	v_add_u32_e32 v141, 3, v175
	v_cmp_gt_u32_e64 s[70:71], s44, v138
	v_cmp_gt_u32_e64 s[72:73], s44, v139
	v_cmp_gt_u32_e64 s[74:75], s44, v140
	v_cmp_gt_u32_e64 s[76:77], s44, v141
	v_cndmask_b32_e64 v152, 0, v152, s[54:55]
	v_cndmask_b32_e64 v153, 0, v153, s[56:57]
	v_cndmask_b32_e64 v154, 0, v154, s[58:59]
	v_cndmask_b32_e64 v155, 0, v155, s[60:61]
	v_cndmask_b32_e64 v152, 0, v152, s[70:71]
	v_cndmask_b32_e64 v153, 0, v153, s[72:73]
	v_cndmask_b32_e64 v154, 0, v154, s[74:75]
	v_cndmask_b32_e64 v155, 0, v155, s[76:77]
	v_add_f32_e32 v132, v132, v152
	v_add_f32_e32 v132, v132, v153
	v_add_f32_e32 v132, v132, v154
	v_add_f32_e32 v132, v132, v155
	v_cvt_pk_bf16_f32 v112, v152, v153
	v_cvt_pk_bf16_f32 v113, v154, v155
	v_min_f32_e32 v152, 0x42a00000, v240
	v_min_f32_e32 v153, 0x42a00000, v241
	v_min_f32_e32 v154, 0x42a00000, v242
	v_min_f32_e32 v155, 0x42a00000, v243
	v_min_f32_e32 v156, 0x42a00000, v248
	v_min_f32_e32 v157, 0x42a00000, v249
	v_min_f32_e32 v158, 0x42a00000, v250
	v_min_f32_e32 v159, 0x42a00000, v251
	v_mfma_f32_16x16x32_bf16 v[240:243], v[228:231], v[48:51], 0
	v_mfma_f32_16x16x32_bf16 v[240:243], v[232:235], v[52:55], v[240:243]
	v_mfma_f32_16x16x32_bf16 v[248:251], v[228:231], v[56:59], 0
	v_mfma_f32_16x16x32_bf16 v[248:251], v[232:235], v[60:63], v[248:251]
	ds_read_b128 v[212:215], v149 offset:11520
	ds_read_b128 v[216:219], v149 offset:11584
	v_mul_f32_e32 v152, 0x3fb8aa3b, v152
	v_mul_f32_e32 v153, 0x3fb8aa3b, v153
	v_mul_f32_e32 v154, 0x3fb8aa3b, v154
	v_mul_f32_e32 v155, 0x3fb8aa3b, v155
	v_exp_f32_e32 v152, v152
	v_exp_f32_e32 v153, v153
	v_exp_f32_e32 v154, v154
	v_exp_f32_e32 v155, v155
	v_add_u32_e32 v138, 16, v175
	v_add_u32_e32 v139, 17, v175
	v_add_u32_e32 v140, 18, v175
	v_add_u32_e32 v141, 19, v175
	v_cmp_gt_u32_e64 s[70:71], s44, v138
	v_cmp_gt_u32_e64 s[72:73], s44, v139
	v_cmp_gt_u32_e64 s[74:75], s44, v140
	v_cmp_gt_u32_e64 s[76:77], s44, v141
	v_cndmask_b32_e64 v152, 0, v152, s[70:71]
	v_cndmask_b32_e64 v153, 0, v153, s[72:73]
	v_cndmask_b32_e64 v154, 0, v154, s[74:75]
	v_cndmask_b32_e64 v155, 0, v155, s[76:77]
	v_add_f32_e32 v132, v132, v152
	v_add_f32_e32 v132, v132, v153
	v_add_f32_e32 v132, v132, v154
	v_add_f32_e32 v132, v132, v155
	v_cvt_pk_bf16_f32 v114, v152, v153
	v_cvt_pk_bf16_f32 v115, v154, v155
	v_mul_f32_e32 v156, 0x3fb8aa3b, v156
	v_mul_f32_e32 v157, 0x3fb8aa3b, v157
	v_mul_f32_e32 v158, 0x3fb8aa3b, v158
	v_mul_f32_e32 v159, 0x3fb8aa3b, v159
	v_exp_f32_e32 v156, v156
	v_exp_f32_e32 v157, v157
	v_exp_f32_e32 v158, v158
	v_exp_f32_e32 v159, v159
	v_add_u32_e32 v138, 16, v175
	v_add_u32_e32 v139, 17, v175
	v_add_u32_e32 v140, 18, v175
	v_add_u32_e32 v141, 19, v175
	v_cmp_gt_u32_e64 s[70:71], s44, v138
	v_cmp_gt_u32_e64 s[72:73], s44, v139
	v_cmp_gt_u32_e64 s[74:75], s44, v140
	v_cmp_gt_u32_e64 s[76:77], s44, v141
	v_cndmask_b32_e64 v156, 0, v156, s[54:55]
	v_cndmask_b32_e64 v157, 0, v157, s[56:57]
	v_cndmask_b32_e64 v158, 0, v158, s[58:59]
	v_cndmask_b32_e64 v159, 0, v159, s[60:61]
	v_cndmask_b32_e64 v156, 0, v156, s[70:71]
	v_cndmask_b32_e64 v157, 0, v157, s[72:73]
	v_cndmask_b32_e64 v158, 0, v158, s[74:75]
	v_cndmask_b32_e64 v159, 0, v159, s[76:77]
	v_add_f32_e32 v133, v133, v156
	v_add_f32_e32 v133, v133, v157
	v_add_f32_e32 v133, v133, v158
	v_add_f32_e32 v133, v133, v159
	v_cvt_pk_bf16_f32 v186, v156, v157
	v_cvt_pk_bf16_f32 v187, v158, v159
	v_min_f32_e32 v152, 0x42a00000, v236
	v_min_f32_e32 v153, 0x42a00000, v237
	v_min_f32_e32 v154, 0x42a00000, v238
	v_min_f32_e32 v155, 0x42a00000, v239
	v_min_f32_e32 v156, 0x42a00000, v244
	v_min_f32_e32 v157, 0x42a00000, v245
	v_min_f32_e32 v158, 0x42a00000, v246
	v_min_f32_e32 v159, 0x42a00000, v247
	s_waitcnt lgkmcnt(2)
	v_mfma_f32_16x16x32_bf16 v[236:239], v[204:207], v[48:51], 0
	v_mfma_f32_16x16x32_bf16 v[236:239], v[208:211], v[52:55], v[236:239]
	v_mfma_f32_16x16x32_bf16 v[244:247], v[204:207], v[56:59], 0
	v_mfma_f32_16x16x32_bf16 v[244:247], v[208:211], v[60:63], v[244:247]
	ds_read_b128 v[220:223], v149 offset:13824
	ds_read_b128 v[224:227], v149 offset:13888
	v_mul_f32_e32 v152, 0x3fb8aa3b, v152
	v_mul_f32_e32 v153, 0x3fb8aa3b, v153
	v_mul_f32_e32 v154, 0x3fb8aa3b, v154
	v_mul_f32_e32 v155, 0x3fb8aa3b, v155
	v_exp_f32_e32 v152, v152
	v_exp_f32_e32 v153, v153
	v_exp_f32_e32 v154, v154
	v_exp_f32_e32 v155, v155
	v_add_u32_e32 v138, 32, v175
	v_add_u32_e32 v139, 33, v175
	v_add_u32_e32 v140, 34, v175
	v_add_u32_e32 v141, 35, v175
	v_cmp_gt_u32_e64 s[70:71], s44, v138
	v_cmp_gt_u32_e64 s[72:73], s44, v139
	v_cmp_gt_u32_e64 s[74:75], s44, v140
	v_cmp_gt_u32_e64 s[76:77], s44, v141
	v_cndmask_b32_e64 v152, 0, v152, s[70:71]
	v_cndmask_b32_e64 v153, 0, v153, s[72:73]
	v_cndmask_b32_e64 v154, 0, v154, s[74:75]
	v_cndmask_b32_e64 v155, 0, v155, s[76:77]
	v_add_f32_e32 v132, v132, v152
	v_add_f32_e32 v132, v132, v153
	v_add_f32_e32 v132, v132, v154
	v_add_f32_e32 v132, v132, v155
	v_cvt_pk_bf16_f32 v116, v152, v153
	v_cvt_pk_bf16_f32 v117, v154, v155
	v_mul_f32_e32 v156, 0x3fb8aa3b, v156
	v_mul_f32_e32 v157, 0x3fb8aa3b, v157
	v_mul_f32_e32 v158, 0x3fb8aa3b, v158
	v_mul_f32_e32 v159, 0x3fb8aa3b, v159
	v_exp_f32_e32 v156, v156
	v_exp_f32_e32 v157, v157
	v_exp_f32_e32 v158, v158
	v_exp_f32_e32 v159, v159
	v_add_u32_e32 v138, 32, v175
	v_add_u32_e32 v139, 33, v175
	v_add_u32_e32 v140, 34, v175
	v_add_u32_e32 v141, 35, v175
	v_cmp_gt_u32_e64 s[70:71], s44, v138
	v_cmp_gt_u32_e64 s[72:73], s44, v139
	v_cmp_gt_u32_e64 s[74:75], s44, v140
	v_cmp_gt_u32_e64 s[76:77], s44, v141
	v_cndmask_b32_e64 v156, 0, v156, s[70:71]
	v_cndmask_b32_e64 v157, 0, v157, s[72:73]
	v_cndmask_b32_e64 v158, 0, v158, s[74:75]
	v_cndmask_b32_e64 v159, 0, v159, s[76:77]
	v_add_f32_e32 v133, v133, v156
	v_add_f32_e32 v133, v133, v157
	v_add_f32_e32 v133, v133, v158
	v_add_f32_e32 v133, v133, v159
	v_cvt_pk_bf16_f32 v188, v156, v157
	v_cvt_pk_bf16_f32 v189, v158, v159
	v_min_f32_e32 v152, 0x42a00000, v240
	v_min_f32_e32 v153, 0x42a00000, v241
	v_min_f32_e32 v154, 0x42a00000, v242
	v_min_f32_e32 v155, 0x42a00000, v243
	v_min_f32_e32 v156, 0x42a00000, v248
	v_min_f32_e32 v157, 0x42a00000, v249
	v_min_f32_e32 v158, 0x42a00000, v250
	v_min_f32_e32 v159, 0x42a00000, v251
	s_waitcnt lgkmcnt(2)
	v_mfma_f32_16x16x32_bf16 v[240:243], v[212:215], v[48:51], 0
	v_mfma_f32_16x16x32_bf16 v[240:243], v[216:219], v[52:55], v[240:243]
	v_mfma_f32_16x16x32_bf16 v[248:251], v[212:215], v[56:59], 0
	v_mfma_f32_16x16x32_bf16 v[248:251], v[216:219], v[60:63], v[248:251]
	ds_read_b128 v[228:231], v149 offset:16128
	ds_read_b128 v[232:235], v149 offset:16192
	v_mul_f32_e32 v152, 0x3fb8aa3b, v152
	v_mul_f32_e32 v153, 0x3fb8aa3b, v153
	v_mul_f32_e32 v154, 0x3fb8aa3b, v154
	v_mul_f32_e32 v155, 0x3fb8aa3b, v155
	v_exp_f32_e32 v152, v152
	v_exp_f32_e32 v153, v153
	v_exp_f32_e32 v154, v154
	v_exp_f32_e32 v155, v155
	v_add_u32_e32 v138, 48, v175
	v_add_u32_e32 v139, 49, v175
	v_add_u32_e32 v140, 50, v175
	v_add_u32_e32 v141, 51, v175
	v_cmp_gt_u32_e64 s[70:71], s44, v138
	v_cmp_gt_u32_e64 s[72:73], s44, v139
	v_cmp_gt_u32_e64 s[74:75], s44, v140
	v_cmp_gt_u32_e64 s[76:77], s44, v141
	v_cndmask_b32_e64 v152, 0, v152, s[70:71]
	v_cndmask_b32_e64 v153, 0, v153, s[72:73]
	v_cndmask_b32_e64 v154, 0, v154, s[74:75]
	v_cndmask_b32_e64 v155, 0, v155, s[76:77]
	v_add_f32_e32 v132, v132, v152
	v_add_f32_e32 v132, v132, v153
	v_add_f32_e32 v132, v132, v154
	v_add_f32_e32 v132, v132, v155
	v_cvt_pk_bf16_f32 v118, v152, v153
	v_cvt_pk_bf16_f32 v119, v154, v155
	v_mul_f32_e32 v156, 0x3fb8aa3b, v156
	v_mul_f32_e32 v157, 0x3fb8aa3b, v157
	v_mul_f32_e32 v158, 0x3fb8aa3b, v158
	v_mul_f32_e32 v159, 0x3fb8aa3b, v159
	v_exp_f32_e32 v156, v156
	v_exp_f32_e32 v157, v157
	v_exp_f32_e32 v158, v158
	v_exp_f32_e32 v159, v159
	v_add_u32_e32 v138, 48, v175
	v_add_u32_e32 v139, 49, v175
	v_add_u32_e32 v140, 50, v175
	v_add_u32_e32 v141, 51, v175
	v_cmp_gt_u32_e64 s[70:71], s44, v138
	v_cmp_gt_u32_e64 s[72:73], s44, v139
	v_cmp_gt_u32_e64 s[74:75], s44, v140
	v_cmp_gt_u32_e64 s[76:77], s44, v141
	v_cndmask_b32_e64 v156, 0, v156, s[70:71]
	v_cndmask_b32_e64 v157, 0, v157, s[72:73]
	v_cndmask_b32_e64 v158, 0, v158, s[74:75]
	v_cndmask_b32_e64 v159, 0, v159, s[76:77]
	v_add_f32_e32 v133, v133, v156
	v_add_f32_e32 v133, v133, v157
	v_add_f32_e32 v133, v133, v158
	v_add_f32_e32 v133, v133, v159
	v_cvt_pk_bf16_f32 v190, v156, v157
	v_cvt_pk_bf16_f32 v191, v158, v159
	v_min_f32_e32 v152, 0x42a00000, v236
	v_min_f32_e32 v153, 0x42a00000, v237
	v_min_f32_e32 v154, 0x42a00000, v238
	v_min_f32_e32 v155, 0x42a00000, v239
	v_min_f32_e32 v156, 0x42a00000, v244
	v_min_f32_e32 v157, 0x42a00000, v245
	v_min_f32_e32 v158, 0x42a00000, v246
	v_min_f32_e32 v159, 0x42a00000, v247
	s_waitcnt lgkmcnt(2)
	v_mfma_f32_16x16x32_bf16 v[236:239], v[220:223], v[48:51], 0
	v_mfma_f32_16x16x32_bf16 v[236:239], v[224:227], v[52:55], v[236:239]
	v_mfma_f32_16x16x32_bf16 v[244:247], v[220:223], v[56:59], 0
	v_mfma_f32_16x16x32_bf16 v[244:247], v[224:227], v[60:63], v[244:247]
	ds_read_b128 v[204:207], v149 offset:18432
	ds_read_b128 v[208:211], v149 offset:18496
	v_mul_f32_e32 v152, 0x3fb8aa3b, v152
	v_mul_f32_e32 v153, 0x3fb8aa3b, v153
	v_mul_f32_e32 v154, 0x3fb8aa3b, v154
	v_mul_f32_e32 v155, 0x3fb8aa3b, v155
	v_exp_f32_e32 v152, v152
	v_exp_f32_e32 v153, v153
	v_exp_f32_e32 v154, v154
	v_exp_f32_e32 v155, v155
	v_add_u32_e32 v138, 64, v175
	v_add_u32_e32 v139, 0x41, v175
	v_add_u32_e32 v140, 0x42, v175
	v_add_u32_e32 v141, 0x43, v175
	v_cmp_gt_u32_e64 s[70:71], s44, v138
	v_cmp_gt_u32_e64 s[72:73], s44, v139
	v_cmp_gt_u32_e64 s[74:75], s44, v140
	v_cmp_gt_u32_e64 s[76:77], s44, v141
	v_cndmask_b32_e64 v152, 0, v152, s[70:71]
	v_cndmask_b32_e64 v153, 0, v153, s[72:73]
	v_cndmask_b32_e64 v154, 0, v154, s[74:75]
	v_cndmask_b32_e64 v155, 0, v155, s[76:77]
	v_add_f32_e32 v132, v132, v152
	v_add_f32_e32 v132, v132, v153
	v_add_f32_e32 v132, v132, v154
	v_add_f32_e32 v132, v132, v155
	v_cvt_pk_bf16_f32 v120, v152, v153
	v_cvt_pk_bf16_f32 v121, v154, v155
	v_mul_f32_e32 v156, 0x3fb8aa3b, v156
	v_mul_f32_e32 v157, 0x3fb8aa3b, v157
	v_mul_f32_e32 v158, 0x3fb8aa3b, v158
	v_mul_f32_e32 v159, 0x3fb8aa3b, v159
	v_exp_f32_e32 v156, v156
	v_exp_f32_e32 v157, v157
	v_exp_f32_e32 v158, v158
	v_exp_f32_e32 v159, v159
	v_add_u32_e32 v138, 64, v175
	v_add_u32_e32 v139, 0x41, v175
	v_add_u32_e32 v140, 0x42, v175
	v_add_u32_e32 v141, 0x43, v175
	v_cmp_gt_u32_e64 s[70:71], s44, v138
	v_cmp_gt_u32_e64 s[72:73], s44, v139
	v_cmp_gt_u32_e64 s[74:75], s44, v140
	v_cmp_gt_u32_e64 s[76:77], s44, v141
	v_cndmask_b32_e64 v156, 0, v156, s[70:71]
	v_cndmask_b32_e64 v157, 0, v157, s[72:73]
	v_cndmask_b32_e64 v158, 0, v158, s[74:75]
	v_cndmask_b32_e64 v159, 0, v159, s[76:77]
	v_add_f32_e32 v133, v133, v156
	v_add_f32_e32 v133, v133, v157
	v_add_f32_e32 v133, v133, v158
	v_add_f32_e32 v133, v133, v159
	v_cvt_pk_bf16_f32 v192, v156, v157
	v_cvt_pk_bf16_f32 v193, v158, v159
	v_min_f32_e32 v152, 0x42a00000, v240
	v_min_f32_e32 v153, 0x42a00000, v241
	v_min_f32_e32 v154, 0x42a00000, v242
	v_min_f32_e32 v155, 0x42a00000, v243
	v_min_f32_e32 v156, 0x42a00000, v248
	v_min_f32_e32 v157, 0x42a00000, v249
	v_min_f32_e32 v158, 0x42a00000, v250
	v_min_f32_e32 v159, 0x42a00000, v251
	s_waitcnt lgkmcnt(2)
	v_mfma_f32_16x16x32_bf16 v[240:243], v[228:231], v[48:51], 0
	v_mfma_f32_16x16x32_bf16 v[240:243], v[232:235], v[52:55], v[240:243]
	v_mfma_f32_16x16x32_bf16 v[248:251], v[228:231], v[56:59], 0
	v_mfma_f32_16x16x32_bf16 v[248:251], v[232:235], v[60:63], v[248:251]
	ds_read_b128 v[212:215], v149 offset:20736
	ds_read_b128 v[216:219], v149 offset:20800
	v_mul_f32_e32 v152, 0x3fb8aa3b, v152
	v_mul_f32_e32 v153, 0x3fb8aa3b, v153
	v_mul_f32_e32 v154, 0x3fb8aa3b, v154
	v_mul_f32_e32 v155, 0x3fb8aa3b, v155
	v_exp_f32_e32 v152, v152
	v_exp_f32_e32 v153, v153
	v_exp_f32_e32 v154, v154
	v_exp_f32_e32 v155, v155
	v_add_u32_e32 v138, 0x50, v175
	v_add_u32_e32 v139, 0x51, v175
	v_add_u32_e32 v140, 0x52, v175
	v_add_u32_e32 v141, 0x53, v175
	v_cmp_gt_u32_e64 s[70:71], s44, v138
	v_cmp_gt_u32_e64 s[72:73], s44, v139
	v_cmp_gt_u32_e64 s[74:75], s44, v140
	v_cmp_gt_u32_e64 s[76:77], s44, v141
	v_cndmask_b32_e64 v152, 0, v152, s[70:71]
	v_cndmask_b32_e64 v153, 0, v153, s[72:73]
	v_cndmask_b32_e64 v154, 0, v154, s[74:75]
	v_cndmask_b32_e64 v155, 0, v155, s[76:77]
	v_add_f32_e32 v132, v132, v152
	v_add_f32_e32 v132, v132, v153
	v_add_f32_e32 v132, v132, v154
	v_add_f32_e32 v132, v132, v155
	v_cvt_pk_bf16_f32 v122, v152, v153
	v_cvt_pk_bf16_f32 v123, v154, v155
	v_mul_f32_e32 v156, 0x3fb8aa3b, v156
	v_mul_f32_e32 v157, 0x3fb8aa3b, v157
	v_mul_f32_e32 v158, 0x3fb8aa3b, v158
	v_mul_f32_e32 v159, 0x3fb8aa3b, v159
	v_exp_f32_e32 v156, v156
	v_exp_f32_e32 v157, v157
	v_exp_f32_e32 v158, v158
	v_exp_f32_e32 v159, v159
	v_add_u32_e32 v138, 0x50, v175
	v_add_u32_e32 v139, 0x51, v175
	v_add_u32_e32 v140, 0x52, v175
	v_add_u32_e32 v141, 0x53, v175
	v_cmp_gt_u32_e64 s[70:71], s44, v138
	v_cmp_gt_u32_e64 s[72:73], s44, v139
	v_cmp_gt_u32_e64 s[74:75], s44, v140
	v_cmp_gt_u32_e64 s[76:77], s44, v141
	v_cndmask_b32_e64 v156, 0, v156, s[70:71]
	v_cndmask_b32_e64 v157, 0, v157, s[72:73]
	v_cndmask_b32_e64 v158, 0, v158, s[74:75]
	v_cndmask_b32_e64 v159, 0, v159, s[76:77]
	v_add_f32_e32 v133, v133, v156
	v_add_f32_e32 v133, v133, v157
	v_add_f32_e32 v133, v133, v158
	v_add_f32_e32 v133, v133, v159
	v_cvt_pk_bf16_f32 v194, v156, v157
	v_cvt_pk_bf16_f32 v195, v158, v159
	v_min_f32_e32 v152, 0x42a00000, v236
	v_min_f32_e32 v153, 0x42a00000, v237
	v_min_f32_e32 v154, 0x42a00000, v238
	v_min_f32_e32 v155, 0x42a00000, v239
	v_min_f32_e32 v156, 0x42a00000, v244
	v_min_f32_e32 v157, 0x42a00000, v245
	v_min_f32_e32 v158, 0x42a00000, v246
	v_min_f32_e32 v159, 0x42a00000, v247
	s_waitcnt lgkmcnt(2)
	v_mfma_f32_16x16x32_bf16 v[236:239], v[204:207], v[48:51], 0
	v_mfma_f32_16x16x32_bf16 v[236:239], v[208:211], v[52:55], v[236:239]
	v_mfma_f32_16x16x32_bf16 v[244:247], v[204:207], v[56:59], 0
	v_mfma_f32_16x16x32_bf16 v[244:247], v[208:211], v[60:63], v[244:247]
	v_mul_f32_e32 v152, 0x3fb8aa3b, v152
	v_mul_f32_e32 v153, 0x3fb8aa3b, v153
	v_mul_f32_e32 v154, 0x3fb8aa3b, v154
	v_mul_f32_e32 v155, 0x3fb8aa3b, v155
	v_exp_f32_e32 v152, v152
	v_exp_f32_e32 v153, v153
	v_exp_f32_e32 v154, v154
	v_exp_f32_e32 v155, v155
	v_add_u32_e32 v138, 0x60, v175
	v_add_u32_e32 v139, 0x61, v175
	v_add_u32_e32 v140, 0x62, v175
	v_add_u32_e32 v141, 0x63, v175
	v_cmp_gt_u32_e64 s[70:71], s44, v138
	v_cmp_gt_u32_e64 s[72:73], s44, v139
	v_cmp_gt_u32_e64 s[74:75], s44, v140
	v_cmp_gt_u32_e64 s[76:77], s44, v141
	v_cndmask_b32_e64 v152, 0, v152, s[70:71]
	v_cndmask_b32_e64 v153, 0, v153, s[72:73]
	v_cndmask_b32_e64 v154, 0, v154, s[74:75]
	v_cndmask_b32_e64 v155, 0, v155, s[76:77]
	v_add_f32_e32 v132, v132, v152
	v_add_f32_e32 v132, v132, v153
	v_add_f32_e32 v132, v132, v154
	v_add_f32_e32 v132, v132, v155
	v_cvt_pk_bf16_f32 v124, v152, v153
	v_cvt_pk_bf16_f32 v125, v154, v155
	v_mul_f32_e32 v156, 0x3fb8aa3b, v156
	v_mul_f32_e32 v157, 0x3fb8aa3b, v157
	v_mul_f32_e32 v158, 0x3fb8aa3b, v158
	v_mul_f32_e32 v159, 0x3fb8aa3b, v159
	v_exp_f32_e32 v156, v156
	v_exp_f32_e32 v157, v157
	v_exp_f32_e32 v158, v158
	v_exp_f32_e32 v159, v159
	v_add_u32_e32 v138, 0x60, v175
	v_add_u32_e32 v139, 0x61, v175
	v_add_u32_e32 v140, 0x62, v175
	v_add_u32_e32 v141, 0x63, v175
	v_cmp_gt_u32_e64 s[70:71], s44, v138
	v_cmp_gt_u32_e64 s[72:73], s44, v139
	v_cmp_gt_u32_e64 s[74:75], s44, v140
	v_cmp_gt_u32_e64 s[76:77], s44, v141
	v_cndmask_b32_e64 v156, 0, v156, s[70:71]
	v_cndmask_b32_e64 v157, 0, v157, s[72:73]
	v_cndmask_b32_e64 v158, 0, v158, s[74:75]
	v_cndmask_b32_e64 v159, 0, v159, s[76:77]
	v_add_f32_e32 v133, v133, v156
	v_add_f32_e32 v133, v133, v157
	v_add_f32_e32 v133, v133, v158
	v_add_f32_e32 v133, v133, v159
	v_cvt_pk_bf16_f32 v196, v156, v157
	v_cvt_pk_bf16_f32 v197, v158, v159
	v_min_f32_e32 v152, 0x42a00000, v240
	v_min_f32_e32 v153, 0x42a00000, v241
	v_min_f32_e32 v154, 0x42a00000, v242
	v_min_f32_e32 v155, 0x42a00000, v243
	v_min_f32_e32 v156, 0x42a00000, v248
	v_min_f32_e32 v157, 0x42a00000, v249
	v_min_f32_e32 v158, 0x42a00000, v250
	v_min_f32_e32 v159, 0x42a00000, v251
	s_waitcnt lgkmcnt(0)
	v_mfma_f32_16x16x32_bf16 v[248:251], v[212:215], v[56:59], 0
	v_mfma_f32_16x16x32_bf16 v[248:251], v[216:219], v[60:63], v[248:251]
	v_mul_f32_e32 v152, 0x3fb8aa3b, v152
	v_mul_f32_e32 v153, 0x3fb8aa3b, v153
	v_mul_f32_e32 v154, 0x3fb8aa3b, v154
	v_mul_f32_e32 v155, 0x3fb8aa3b, v155
	v_exp_f32_e32 v152, v152
	v_exp_f32_e32 v153, v153
	v_exp_f32_e32 v154, v154
	v_exp_f32_e32 v155, v155
	v_add_u32_e32 v138, 0x70, v175
	v_add_u32_e32 v139, 0x71, v175
	v_add_u32_e32 v140, 0x72, v175
	v_add_u32_e32 v141, 0x73, v175
	v_cmp_gt_u32_e64 s[70:71], s44, v138
	v_cmp_gt_u32_e64 s[72:73], s44, v139
	v_cmp_gt_u32_e64 s[74:75], s44, v140
	v_cmp_gt_u32_e64 s[76:77], s44, v141
	v_cndmask_b32_e64 v152, 0, v152, s[70:71]
	v_cndmask_b32_e64 v153, 0, v153, s[72:73]
	v_cndmask_b32_e64 v154, 0, v154, s[74:75]
	v_cndmask_b32_e64 v155, 0, v155, s[76:77]
	v_add_f32_e32 v132, v132, v152
	v_add_f32_e32 v132, v132, v153
	v_add_f32_e32 v132, v132, v154
	v_add_f32_e32 v132, v132, v155
	v_cvt_pk_bf16_f32 v126, v152, v153
	v_cvt_pk_bf16_f32 v127, v154, v155
	v_mul_f32_e32 v156, 0x3fb8aa3b, v156
	v_mul_f32_e32 v157, 0x3fb8aa3b, v157
	v_mul_f32_e32 v158, 0x3fb8aa3b, v158
	v_mul_f32_e32 v159, 0x3fb8aa3b, v159
	v_exp_f32_e32 v156, v156
	v_exp_f32_e32 v157, v157
	v_exp_f32_e32 v158, v158
	v_exp_f32_e32 v159, v159
	v_add_u32_e32 v138, 0x70, v175
	v_add_u32_e32 v139, 0x71, v175
	v_add_u32_e32 v140, 0x72, v175
	v_add_u32_e32 v141, 0x73, v175
	v_cmp_gt_u32_e64 s[70:71], s44, v138
	v_cmp_gt_u32_e64 s[72:73], s44, v139
	v_cmp_gt_u32_e64 s[74:75], s44, v140
	v_cmp_gt_u32_e64 s[76:77], s44, v141
	v_cndmask_b32_e64 v156, 0, v156, s[70:71]
	v_cndmask_b32_e64 v157, 0, v157, s[72:73]
	v_cndmask_b32_e64 v158, 0, v158, s[74:75]
	v_cndmask_b32_e64 v159, 0, v159, s[76:77]
	v_add_f32_e32 v133, v133, v156
	v_add_f32_e32 v133, v133, v157
	v_add_f32_e32 v133, v133, v158
	v_add_f32_e32 v133, v133, v159
	v_cvt_pk_bf16_f32 v198, v156, v157
	v_cvt_pk_bf16_f32 v199, v158, v159
	v_min_f32_e32 v152, 0x42a00000, v236
	v_min_f32_e32 v153, 0x42a00000, v237
	v_min_f32_e32 v154, 0x42a00000, v238
	v_min_f32_e32 v155, 0x42a00000, v239
	v_min_f32_e32 v156, 0x42a00000, v244
	v_min_f32_e32 v157, 0x42a00000, v245
	v_min_f32_e32 v158, 0x42a00000, v246
	v_min_f32_e32 v159, 0x42a00000, v247
	v_mul_f32_e32 v152, 0x3fb8aa3b, v152
	v_mul_f32_e32 v153, 0x3fb8aa3b, v153
	v_mul_f32_e32 v154, 0x3fb8aa3b, v154
	v_mul_f32_e32 v155, 0x3fb8aa3b, v155
	v_exp_f32_e32 v152, v152
	v_exp_f32_e32 v153, v153
	v_exp_f32_e32 v154, v154
	v_exp_f32_e32 v155, v155
	v_add_u32_e32 v138, 0x80, v175
	v_add_u32_e32 v139, 0x81, v175
	v_add_u32_e32 v140, 0x82, v175
	v_add_u32_e32 v141, 0x83, v175
	v_cmp_gt_u32_e64 s[70:71], s44, v138
	v_cmp_gt_u32_e64 s[72:73], s44, v139
	v_cmp_gt_u32_e64 s[74:75], s44, v140
	v_cmp_gt_u32_e64 s[76:77], s44, v141
	v_cndmask_b32_e64 v152, 0, v152, s[62:63]
	v_cndmask_b32_e64 v153, 0, v153, s[64:65]
	v_cndmask_b32_e64 v154, 0, v154, s[66:67]
	v_cndmask_b32_e64 v155, 0, v155, s[68:69]
	v_cndmask_b32_e64 v152, 0, v152, s[70:71]
	v_cndmask_b32_e64 v153, 0, v153, s[72:73]
	v_cndmask_b32_e64 v154, 0, v154, s[74:75]
	v_cndmask_b32_e64 v155, 0, v155, s[76:77]
	v_add_f32_e32 v132, v132, v152
	v_add_f32_e32 v132, v132, v153
	v_add_f32_e32 v132, v132, v154
	v_add_f32_e32 v132, v132, v155
	v_cvt_pk_bf16_f32 v128, v152, v153
	v_cvt_pk_bf16_f32 v129, v154, v155
	v_mul_f32_e32 v156, 0x3fb8aa3b, v156
	v_mul_f32_e32 v157, 0x3fb8aa3b, v157
	v_mul_f32_e32 v158, 0x3fb8aa3b, v158
	v_mul_f32_e32 v159, 0x3fb8aa3b, v159
	v_exp_f32_e32 v156, v156
	v_exp_f32_e32 v157, v157
	v_exp_f32_e32 v158, v158
	v_exp_f32_e32 v159, v159
	v_add_u32_e32 v138, 0x80, v175
	v_add_u32_e32 v139, 0x81, v175
	v_add_u32_e32 v140, 0x82, v175
	v_add_u32_e32 v141, 0x83, v175
	v_cmp_gt_u32_e64 s[70:71], s44, v138
	v_cmp_gt_u32_e64 s[72:73], s44, v139
	v_cmp_gt_u32_e64 s[74:75], s44, v140
	v_cmp_gt_u32_e64 s[76:77], s44, v141
	v_cndmask_b32_e64 v156, 0, v156, s[70:71]
	v_cndmask_b32_e64 v157, 0, v157, s[72:73]
	v_cndmask_b32_e64 v158, 0, v158, s[74:75]
	v_cndmask_b32_e64 v159, 0, v159, s[76:77]
	v_add_f32_e32 v133, v133, v156
	v_add_f32_e32 v133, v133, v157
	v_add_f32_e32 v133, v133, v158
	v_add_f32_e32 v133, v133, v159
	v_cvt_pk_bf16_f32 v200, v156, v157
	v_cvt_pk_bf16_f32 v201, v158, v159
	v_min_f32_e32 v156, 0x42a00000, v248
	v_min_f32_e32 v157, 0x42a00000, v249
	v_min_f32_e32 v158, 0x42a00000, v250
	v_min_f32_e32 v159, 0x42a00000, v251
	v_mul_f32_e32 v156, 0x3fb8aa3b, v156
	v_mul_f32_e32 v157, 0x3fb8aa3b, v157
	v_mul_f32_e32 v158, 0x3fb8aa3b, v158
	v_mul_f32_e32 v159, 0x3fb8aa3b, v159
	v_exp_f32_e32 v156, v156
	v_exp_f32_e32 v157, v157
	v_exp_f32_e32 v158, v158
	v_exp_f32_e32 v159, v159
	v_add_u32_e32 v138, 0x90, v175
	v_add_u32_e32 v139, 0x91, v175
	v_add_u32_e32 v140, 0x92, v175
	v_add_u32_e32 v141, 0x93, v175
	v_cmp_gt_u32_e64 s[70:71], s44, v138
	v_cmp_gt_u32_e64 s[72:73], s44, v139
	v_cmp_gt_u32_e64 s[74:75], s44, v140
	v_cmp_gt_u32_e64 s[76:77], s44, v141
	v_cndmask_b32_e64 v156, 0, v156, s[62:63]
	v_cndmask_b32_e64 v157, 0, v157, s[64:65]
	v_cndmask_b32_e64 v158, 0, v158, s[66:67]
	v_cndmask_b32_e64 v159, 0, v159, s[68:69]
	v_cndmask_b32_e64 v156, 0, v156, s[70:71]
	v_cndmask_b32_e64 v157, 0, v157, s[72:73]
	v_cndmask_b32_e64 v158, 0, v158, s[74:75]
	v_cndmask_b32_e64 v159, 0, v159, s[76:77]
	v_add_f32_e32 v133, v133, v156
	v_add_f32_e32 v133, v133, v157
	v_add_f32_e32 v133, v133, v158
	v_add_f32_e32 v133, v133, v159
	v_cvt_pk_bf16_f32 v202, v156, v157
	v_cvt_pk_bf16_f32 v203, v158, v159
	ds_bpermute_b32 v142, v167, v132
	s_waitcnt lgkmcnt(0)
	v_add_f32_e32 v132, v132, v142
	ds_bpermute_b32 v142, v168, v132
	s_waitcnt lgkmcnt(0)
	v_add_f32_e32 v132, v132, v142
	ds_bpermute_b32 v142, v167, v133
	s_waitcnt lgkmcnt(0)
	v_add_f32_e32 v133, v133, v142
	ds_bpermute_b32 v142, v168, v133
	s_waitcnt lgkmcnt(0)
	v_add_f32_e32 v133, v133, v142
	ds_read_b64_tr_b16 v[236:237], v151 offset:0
	ds_read_b64_tr_b16 v[238:239], v151 offset:2304
	ds_read_b64_tr_b16 v[240:241], v151 offset:32
	ds_read_b64_tr_b16 v[242:243], v151 offset:2336
	ds_read_b64_tr_b16 v[244:245], v151 offset:64
	ds_read_b64_tr_b16 v[246:247], v151 offset:2368
	ds_read_b64_tr_b16 v[248:249], v151 offset:96
	ds_read_b64_tr_b16 v[250:251], v151 offset:2400
	s_waitcnt lgkmcnt(0)
	v_mfma_f32_16x16x32_bf16 v[204:207], v[236:239], v[112:115], 0
	v_mfma_f32_16x16x32_bf16 v[208:211], v[240:243], v[112:115], 0
	v_mfma_f32_16x16x32_bf16 v[212:215], v[244:247], v[112:115], 0
	v_mfma_f32_16x16x32_bf16 v[216:219], v[248:251], v[112:115], 0
	v_mfma_f32_16x16x32_bf16 v[220:223], v[236:239], v[184:187], 0
	v_mfma_f32_16x16x32_bf16 v[224:227], v[240:243], v[184:187], 0
	v_mfma_f32_16x16x32_bf16 v[228:231], v[244:247], v[184:187], 0
	v_mfma_f32_16x16x32_bf16 v[232:235], v[248:251], v[184:187], 0
	s_nop 7
	ds_read_b64_tr_b16 v[236:237], v151 offset:4608
	ds_read_b64_tr_b16 v[238:239], v151 offset:6912
	ds_read_b64_tr_b16 v[240:241], v151 offset:4640
	ds_read_b64_tr_b16 v[242:243], v151 offset:6944
	ds_read_b64_tr_b16 v[244:245], v151 offset:4672
	ds_read_b64_tr_b16 v[246:247], v151 offset:6976
	ds_read_b64_tr_b16 v[248:249], v151 offset:4704
	ds_read_b64_tr_b16 v[250:251], v151 offset:7008
	s_waitcnt lgkmcnt(0)
	v_mfma_f32_16x16x32_bf16 v[204:207], v[236:239], v[116:119], v[204:207]
	v_mfma_f32_16x16x32_bf16 v[208:211], v[240:243], v[116:119], v[208:211]
	v_mfma_f32_16x16x32_bf16 v[212:215], v[244:247], v[116:119], v[212:215]
	v_mfma_f32_16x16x32_bf16 v[216:219], v[248:251], v[116:119], v[216:219]
	v_mfma_f32_16x16x32_bf16 v[220:223], v[236:239], v[188:191], v[220:223]
	v_mfma_f32_16x16x32_bf16 v[224:227], v[240:243], v[188:191], v[224:227]
	v_mfma_f32_16x16x32_bf16 v[228:231], v[244:247], v[188:191], v[228:231]
	v_mfma_f32_16x16x32_bf16 v[232:235], v[248:251], v[188:191], v[232:235]
	s_nop 7
	ds_read_b64_tr_b16 v[236:237], v151 offset:9216
	ds_read_b64_tr_b16 v[238:239], v151 offset:11520
	ds_read_b64_tr_b16 v[240:241], v151 offset:9248
	ds_read_b64_tr_b16 v[242:243], v151 offset:11552
	ds_read_b64_tr_b16 v[244:245], v151 offset:9280
	ds_read_b64_tr_b16 v[246:247], v151 offset:11584
	ds_read_b64_tr_b16 v[248:249], v151 offset:9312
	ds_read_b64_tr_b16 v[250:251], v151 offset:11616
	s_waitcnt lgkmcnt(0)
	v_mfma_f32_16x16x32_bf16 v[204:207], v[236:239], v[120:123], v[204:207]
	v_mfma_f32_16x16x32_bf16 v[208:211], v[240:243], v[120:123], v[208:211]
	v_mfma_f32_16x16x32_bf16 v[212:215], v[244:247], v[120:123], v[212:215]
	v_mfma_f32_16x16x32_bf16 v[216:219], v[248:251], v[120:123], v[216:219]
	v_mfma_f32_16x16x32_bf16 v[220:223], v[236:239], v[192:195], v[220:223]
	v_mfma_f32_16x16x32_bf16 v[224:227], v[240:243], v[192:195], v[224:227]
	v_mfma_f32_16x16x32_bf16 v[228:231], v[244:247], v[192:195], v[228:231]
	v_mfma_f32_16x16x32_bf16 v[232:235], v[248:251], v[192:195], v[232:235]
	s_nop 7
	ds_read_b64_tr_b16 v[236:237], v151 offset:13824
	ds_read_b64_tr_b16 v[238:239], v151 offset:16128
	ds_read_b64_tr_b16 v[240:241], v151 offset:13856
	ds_read_b64_tr_b16 v[242:243], v151 offset:16160
	ds_read_b64_tr_b16 v[244:245], v151 offset:13888
	ds_read_b64_tr_b16 v[246:247], v151 offset:16192
	ds_read_b64_tr_b16 v[248:249], v151 offset:13920
	ds_read_b64_tr_b16 v[250:251], v151 offset:16224
	s_waitcnt lgkmcnt(0)
	v_mfma_f32_16x16x32_bf16 v[204:207], v[236:239], v[124:127], v[204:207]
	v_mfma_f32_16x16x32_bf16 v[208:211], v[240:243], v[124:127], v[208:211]
	v_mfma_f32_16x16x32_bf16 v[212:215], v[244:247], v[124:127], v[212:215]
	v_mfma_f32_16x16x32_bf16 v[216:219], v[248:251], v[124:127], v[216:219]
	v_mfma_f32_16x16x32_bf16 v[220:223], v[236:239], v[196:199], v[220:223]
	v_mfma_f32_16x16x32_bf16 v[224:227], v[240:243], v[196:199], v[224:227]
	v_mfma_f32_16x16x32_bf16 v[228:231], v[244:247], v[196:199], v[228:231]
	v_mfma_f32_16x16x32_bf16 v[232:235], v[248:251], v[196:199], v[232:235]
	s_nop 7
	ds_read_b64_tr_b16 v[236:237], v151 offset:18432
	ds_read_b64_tr_b16 v[238:239], v151 offset:20736
	ds_read_b64_tr_b16 v[240:241], v151 offset:18464
	ds_read_b64_tr_b16 v[242:243], v151 offset:20768
	ds_read_b64_tr_b16 v[244:245], v151 offset:18496
	ds_read_b64_tr_b16 v[246:247], v151 offset:20800
	ds_read_b64_tr_b16 v[248:249], v151 offset:18528
	ds_read_b64_tr_b16 v[250:251], v151 offset:20832
	s_waitcnt lgkmcnt(0)
	v_mfma_f32_16x16x32_bf16 v[204:207], v[236:239], v[128:131], v[204:207]
	v_mfma_f32_16x16x32_bf16 v[208:211], v[240:243], v[128:131], v[208:211]
	v_mfma_f32_16x16x32_bf16 v[212:215], v[244:247], v[128:131], v[212:215]
	v_mfma_f32_16x16x32_bf16 v[216:219], v[248:251], v[128:131], v[216:219]
	v_mfma_f32_16x16x32_bf16 v[220:223], v[236:239], v[200:203], v[220:223]
	v_mfma_f32_16x16x32_bf16 v[224:227], v[240:243], v[200:203], v[224:227]
	v_mfma_f32_16x16x32_bf16 v[228:231], v[244:247], v[200:203], v[228:231]
	v_mfma_f32_16x16x32_bf16 v[232:235], v[248:251], v[200:203], v[232:235]
	s_barrier
	ds_write_b128 v173, v[204:207] offset:0
	ds_write_b128 v173, v[208:211] offset:64
	ds_write_b128 v173, v[212:215] offset:128
	ds_write_b128 v173, v[216:219] offset:192
	ds_write_b32 v174, v132 offset:0
	ds_write_b128 v173, v[220:223] offset:4624
	ds_write_b128 v173, v[224:227] offset:4688
	ds_write_b128 v173, v[228:231] offset:4752
	ds_write_b128 v173, v[232:235] offset:4816
	ds_write_b32 v174, v133 offset:64
	s_waitcnt lgkmcnt(0)
	s_barrier
	s_mov_b32 s40, s42
	s_mov_b32 s41, s43
	v_mov_b32_e32 v173, v176
	v_mov_b32_e32 v174, v177
	v_mov_b32_e32 v175, v178
	v_mov_b32_e32 v179, v183
	v_mov_b32_e32 v182, v252
	s_lshr_b32 s44, s33, 2
	s_lshr_b32 s42, s15, 4
	s_add_i32 s43, s0, 0
	v_subrev_u32_e32 v143, s80, v174
	v_lshl_add_u32 v143, v143, 5, v161
	v_add_u32_e32 v143, 0x1b500, v143
	ds_read_b128 v[48:51], v143
	ds_read_b128 v[52:55], v143 offset:64
	ds_read_b128 v[56:59], v143 offset:8192
	ds_read_b128 v[60:63], v143 offset:8256
	s_waitcnt vmcnt(12)
	s_waitcnt lgkmcnt(0)
	v_mov_b32_e32 v132, 0
	v_mov_b32_e32 v133, 0
	v_mfma_f32_16x16x32_bf16 v[236:239], v[0:3], v[48:51], 0
	v_mfma_f32_16x16x32_bf16 v[236:239], v[4:7], v[52:55], v[236:239]
	v_mfma_f32_16x16x32_bf16 v[240:243], v[8:11], v[48:51], 0
	v_mfma_f32_16x16x32_bf16 v[240:243], v[12:15], v[52:55], v[240:243]
	v_mfma_f32_16x16x32_bf16 v[248:251], v[8:11], v[56:59], 0
	v_mfma_f32_16x16x32_bf16 v[248:251], v[12:15], v[60:63], v[248:251]
	s_nop 7
	v_min_f32_e32 v152, 0x42a00000, v236
	v_min_f32_e32 v153, 0x42a00000, v237
	v_min_f32_e32 v154, 0x42a00000, v238
	v_min_f32_e32 v155, 0x42a00000, v239
	v_mfma_f32_16x16x32_bf16 v[236:239], v[16:19], v[48:51], 0
	v_mfma_f32_16x16x32_bf16 v[236:239], v[20:23], v[52:55], v[236:239]
	v_mfma_f32_16x16x32_bf16 v[244:247], v[16:19], v[56:59], 0
	v_mfma_f32_16x16x32_bf16 v[244:247], v[20:23], v[60:63], v[244:247]
	v_add_u32_e32 v136, 24, v182
	v_med3_i32 v136, v136, 0, s38
	v_lshl_add_u32 v136, v136, 9, v179
	global_load_dwordx4 v[0:3], v136, s[24:25]
	global_load_dwordx4 v[4:7], v136, s[24:25] offset:64
	v_mul_f32_e32 v152, 0x3fb8aa3b, v152
	v_mul_f32_e32 v153, 0x3fb8aa3b, v153
	v_mul_f32_e32 v154, 0x3fb8aa3b, v154
	v_mul_f32_e32 v155, 0x3fb8aa3b, v155
	v_exp_f32_e32 v152, v152
	v_exp_f32_e32 v153, v153
	v_exp_f32_e32 v154, v154
	v_exp_f32_e32 v155, v155
	v_add_u32_e32 v138, 0, v175
	v_add_u32_e32 v139, 1, v175
	v_add_u32_e32 v140, 2, v175
	v_add_u32_e32 v141, 3, v175
	v_cmp_gt_u32_e64 s[70:71], s44, v138
	v_cmp_gt_u32_e64 s[72:73], s44, v139
	v_cmp_gt_u32_e64 s[74:75], s44, v140
	v_cmp_gt_u32_e64 s[76:77], s44, v141
	v_cndmask_b32_e64 v152, 0, v152, s[54:55]
	v_cndmask_b32_e64 v153, 0, v153, s[56:57]
	v_cndmask_b32_e64 v154, 0, v154, s[58:59]
	v_cndmask_b32_e64 v155, 0, v155, s[60:61]
	v_cndmask_b32_e64 v152, 0, v152, s[70:71]
	v_cndmask_b32_e64 v153, 0, v153, s[72:73]
	v_cndmask_b32_e64 v154, 0, v154, s[74:75]
	v_cndmask_b32_e64 v155, 0, v155, s[76:77]
	v_add_f32_e32 v132, v132, v152
	v_add_f32_e32 v132, v132, v153
	v_add_f32_e32 v132, v132, v154
	v_add_f32_e32 v132, v132, v155
	v_cvt_pk_bf16_f32 v112, v152, v153
	v_cvt_pk_bf16_f32 v113, v154, v155
	v_min_f32_e32 v152, 0x42a00000, v240
	v_min_f32_e32 v153, 0x42a00000, v241
	v_min_f32_e32 v154, 0x42a00000, v242
	v_min_f32_e32 v155, 0x42a00000, v243
	v_min_f32_e32 v156, 0x42a00000, v248
	v_min_f32_e32 v157, 0x42a00000, v249
	v_min_f32_e32 v158, 0x42a00000, v250
	v_min_f32_e32 v159, 0x42a00000, v251
	v_mfma_f32_16x16x32_bf16 v[240:243], v[24:27], v[48:51], 0
	v_mfma_f32_16x16x32_bf16 v[240:243], v[28:31], v[52:55], v[240:243]
	v_mfma_f32_16x16x32_bf16 v[248:251], v[24:27], v[56:59], 0
	v_mfma_f32_16x16x32_bf16 v[248:251], v[28:31], v[60:63], v[248:251]
	v_add_u32_e32 v135, 28, v182
	v_med3_i32 v135, v135, 0, s38
	v_lshl_add_u32 v135, v135, 9, v179
	global_load_dwordx4 v[8:11], v135, s[24:25]
	global_load_dwordx4 v[12:15], v135, s[24:25] offset:64
	v_mul_f32_e32 v152, 0x3fb8aa3b, v152
	v_mul_f32_e32 v153, 0x3fb8aa3b, v153
	v_mul_f32_e32 v154, 0x3fb8aa3b, v154
	v_mul_f32_e32 v155, 0x3fb8aa3b, v155
	v_exp_f32_e32 v152, v152
	v_exp_f32_e32 v153, v153
	v_exp_f32_e32 v154, v154
	v_exp_f32_e32 v155, v155
	v_add_u32_e32 v138, 16, v175
	v_add_u32_e32 v139, 17, v175
	v_add_u32_e32 v140, 18, v175
	v_add_u32_e32 v141, 19, v175
	v_cmp_gt_u32_e64 s[70:71], s44, v138
	v_cmp_gt_u32_e64 s[72:73], s44, v139
	v_cmp_gt_u32_e64 s[74:75], s44, v140
	v_cmp_gt_u32_e64 s[76:77], s44, v141
	v_cndmask_b32_e64 v152, 0, v152, s[70:71]
	v_cndmask_b32_e64 v153, 0, v153, s[72:73]
	v_cndmask_b32_e64 v154, 0, v154, s[74:75]
	v_cndmask_b32_e64 v155, 0, v155, s[76:77]
	v_add_f32_e32 v132, v132, v152
	v_add_f32_e32 v132, v132, v153
	v_add_f32_e32 v132, v132, v154
	v_add_f32_e32 v132, v132, v155
	v_cvt_pk_bf16_f32 v114, v152, v153
	v_cvt_pk_bf16_f32 v115, v154, v155
	v_mul_f32_e32 v156, 0x3fb8aa3b, v156
	v_mul_f32_e32 v157, 0x3fb8aa3b, v157
	v_mul_f32_e32 v158, 0x3fb8aa3b, v158
	v_mul_f32_e32 v159, 0x3fb8aa3b, v159
	v_exp_f32_e32 v156, v156
	v_exp_f32_e32 v157, v157
	v_exp_f32_e32 v158, v158
	v_exp_f32_e32 v159, v159
	v_add_u32_e32 v138, 16, v175
	v_add_u32_e32 v139, 17, v175
	v_add_u32_e32 v140, 18, v175
	v_add_u32_e32 v141, 19, v175
	v_cmp_gt_u32_e64 s[70:71], s44, v138
	v_cmp_gt_u32_e64 s[72:73], s44, v139
	v_cmp_gt_u32_e64 s[74:75], s44, v140
	v_cmp_gt_u32_e64 s[76:77], s44, v141
	v_cndmask_b32_e64 v156, 0, v156, s[54:55]
	v_cndmask_b32_e64 v157, 0, v157, s[56:57]
	v_cndmask_b32_e64 v158, 0, v158, s[58:59]
	v_cndmask_b32_e64 v159, 0, v159, s[60:61]
	v_cndmask_b32_e64 v156, 0, v156, s[70:71]
	v_cndmask_b32_e64 v157, 0, v157, s[72:73]
	v_cndmask_b32_e64 v158, 0, v158, s[74:75]
	v_cndmask_b32_e64 v159, 0, v159, s[76:77]
	v_add_f32_e32 v133, v133, v156
	v_add_f32_e32 v133, v133, v157
	v_add_f32_e32 v133, v133, v158
	v_add_f32_e32 v133, v133, v159
	v_cvt_pk_bf16_f32 v186, v156, v157
	v_cvt_pk_bf16_f32 v187, v158, v159
	v_min_f32_e32 v152, 0x42a00000, v236
	v_min_f32_e32 v153, 0x42a00000, v237
	v_min_f32_e32 v154, 0x42a00000, v238
	v_min_f32_e32 v155, 0x42a00000, v239
	v_min_f32_e32 v156, 0x42a00000, v244
	v_min_f32_e32 v157, 0x42a00000, v245
	v_min_f32_e32 v158, 0x42a00000, v246
	v_min_f32_e32 v159, 0x42a00000, v247
	v_mfma_f32_16x16x32_bf16 v[236:239], v[32:35], v[48:51], 0
	v_mfma_f32_16x16x32_bf16 v[236:239], v[36:39], v[52:55], v[236:239]
	v_mfma_f32_16x16x32_bf16 v[244:247], v[32:35], v[56:59], 0
	v_mfma_f32_16x16x32_bf16 v[244:247], v[36:39], v[60:63], v[244:247]
	v_add_u32_e32 v136, 32, v182
	v_med3_i32 v136, v136, 0, s38
	v_lshl_add_u32 v136, v136, 9, v179
	global_load_dwordx4 v[16:19], v136, s[24:25]
	global_load_dwordx4 v[20:23], v136, s[24:25] offset:64
	v_mul_f32_e32 v152, 0x3fb8aa3b, v152
	v_mul_f32_e32 v153, 0x3fb8aa3b, v153
	v_mul_f32_e32 v154, 0x3fb8aa3b, v154
	v_mul_f32_e32 v155, 0x3fb8aa3b, v155
	v_exp_f32_e32 v152, v152
	v_exp_f32_e32 v153, v153
	v_exp_f32_e32 v154, v154
	v_exp_f32_e32 v155, v155
	v_add_u32_e32 v138, 32, v175
	v_add_u32_e32 v139, 33, v175
	v_add_u32_e32 v140, 34, v175
	v_add_u32_e32 v141, 35, v175
	v_cmp_gt_u32_e64 s[70:71], s44, v138
	v_cmp_gt_u32_e64 s[72:73], s44, v139
	v_cmp_gt_u32_e64 s[74:75], s44, v140
	v_cmp_gt_u32_e64 s[76:77], s44, v141
	v_cndmask_b32_e64 v152, 0, v152, s[70:71]
	v_cndmask_b32_e64 v153, 0, v153, s[72:73]
	v_cndmask_b32_e64 v154, 0, v154, s[74:75]
	v_cndmask_b32_e64 v155, 0, v155, s[76:77]
	v_add_f32_e32 v132, v132, v152
	v_add_f32_e32 v132, v132, v153
	v_add_f32_e32 v132, v132, v154
	v_add_f32_e32 v132, v132, v155
	v_cvt_pk_bf16_f32 v116, v152, v153
	v_cvt_pk_bf16_f32 v117, v154, v155
	v_mul_f32_e32 v156, 0x3fb8aa3b, v156
	v_mul_f32_e32 v157, 0x3fb8aa3b, v157
	v_mul_f32_e32 v158, 0x3fb8aa3b, v158
	v_mul_f32_e32 v159, 0x3fb8aa3b, v159
	v_exp_f32_e32 v156, v156
	v_exp_f32_e32 v157, v157
	v_exp_f32_e32 v158, v158
	v_exp_f32_e32 v159, v159
	v_add_u32_e32 v138, 32, v175
	v_add_u32_e32 v139, 33, v175
	v_add_u32_e32 v140, 34, v175
	v_add_u32_e32 v141, 35, v175
	v_cmp_gt_u32_e64 s[70:71], s44, v138
	v_cmp_gt_u32_e64 s[72:73], s44, v139
	v_cmp_gt_u32_e64 s[74:75], s44, v140
	v_cmp_gt_u32_e64 s[76:77], s44, v141
	v_cndmask_b32_e64 v156, 0, v156, s[70:71]
	v_cndmask_b32_e64 v157, 0, v157, s[72:73]
	v_cndmask_b32_e64 v158, 0, v158, s[74:75]
	v_cndmask_b32_e64 v159, 0, v159, s[76:77]
	v_add_f32_e32 v133, v133, v156
	v_add_f32_e32 v133, v133, v157
	v_add_f32_e32 v133, v133, v158
	v_add_f32_e32 v133, v133, v159
	v_cvt_pk_bf16_f32 v188, v156, v157
	v_cvt_pk_bf16_f32 v189, v158, v159
	v_min_f32_e32 v152, 0x42a00000, v240
	v_min_f32_e32 v153, 0x42a00000, v241
	v_min_f32_e32 v154, 0x42a00000, v242
	v_min_f32_e32 v155, 0x42a00000, v243
	v_min_f32_e32 v156, 0x42a00000, v248
	v_min_f32_e32 v157, 0x42a00000, v249
	v_min_f32_e32 v158, 0x42a00000, v250
	v_min_f32_e32 v159, 0x42a00000, v251
	v_mfma_f32_16x16x32_bf16 v[240:243], v[40:43], v[48:51], 0
	v_mfma_f32_16x16x32_bf16 v[240:243], v[44:47], v[52:55], v[240:243]
	v_mfma_f32_16x16x32_bf16 v[248:251], v[40:43], v[56:59], 0
	v_mfma_f32_16x16x32_bf16 v[248:251], v[44:47], v[60:63], v[248:251]
	v_add_u32_e32 v135, 36, v182
	v_med3_i32 v135, v135, 0, s38
	v_lshl_add_u32 v135, v135, 9, v179
	global_load_dwordx4 v[24:27], v135, s[24:25]
	global_load_dwordx4 v[28:31], v135, s[24:25] offset:64
	v_mul_f32_e32 v152, 0x3fb8aa3b, v152
	v_mul_f32_e32 v153, 0x3fb8aa3b, v153
	v_mul_f32_e32 v154, 0x3fb8aa3b, v154
	v_mul_f32_e32 v155, 0x3fb8aa3b, v155
	v_exp_f32_e32 v152, v152
	v_exp_f32_e32 v153, v153
	v_exp_f32_e32 v154, v154
	v_exp_f32_e32 v155, v155
	v_add_u32_e32 v138, 48, v175
	v_add_u32_e32 v139, 49, v175
	v_add_u32_e32 v140, 50, v175
	v_add_u32_e32 v141, 51, v175
	v_cmp_gt_u32_e64 s[70:71], s44, v138
	v_cmp_gt_u32_e64 s[72:73], s44, v139
	v_cmp_gt_u32_e64 s[74:75], s44, v140
	v_cmp_gt_u32_e64 s[76:77], s44, v141
	v_cndmask_b32_e64 v152, 0, v152, s[70:71]
	v_cndmask_b32_e64 v153, 0, v153, s[72:73]
	v_cndmask_b32_e64 v154, 0, v154, s[74:75]
	v_cndmask_b32_e64 v155, 0, v155, s[76:77]
	v_add_f32_e32 v132, v132, v152
	v_add_f32_e32 v132, v132, v153
	v_add_f32_e32 v132, v132, v154
	v_add_f32_e32 v132, v132, v155
	v_cvt_pk_bf16_f32 v118, v152, v153
	v_cvt_pk_bf16_f32 v119, v154, v155
	v_mul_f32_e32 v156, 0x3fb8aa3b, v156
	v_mul_f32_e32 v157, 0x3fb8aa3b, v157
	v_mul_f32_e32 v158, 0x3fb8aa3b, v158
	v_mul_f32_e32 v159, 0x3fb8aa3b, v159
	v_exp_f32_e32 v156, v156
	v_exp_f32_e32 v157, v157
	v_exp_f32_e32 v158, v158
	v_exp_f32_e32 v159, v159
	v_add_u32_e32 v138, 48, v175
	v_add_u32_e32 v139, 49, v175
	v_add_u32_e32 v140, 50, v175
	v_add_u32_e32 v141, 51, v175
	v_cmp_gt_u32_e64 s[70:71], s44, v138
	v_cmp_gt_u32_e64 s[72:73], s44, v139
	v_cmp_gt_u32_e64 s[74:75], s44, v140
	v_cmp_gt_u32_e64 s[76:77], s44, v141
	v_cndmask_b32_e64 v156, 0, v156, s[70:71]
	v_cndmask_b32_e64 v157, 0, v157, s[72:73]
	v_cndmask_b32_e64 v158, 0, v158, s[74:75]
	v_cndmask_b32_e64 v159, 0, v159, s[76:77]
	v_add_f32_e32 v133, v133, v156
	v_add_f32_e32 v133, v133, v157
	v_add_f32_e32 v133, v133, v158
	v_add_f32_e32 v133, v133, v159
	v_cvt_pk_bf16_f32 v190, v156, v157
	v_cvt_pk_bf16_f32 v191, v158, v159
	v_min_f32_e32 v152, 0x42a00000, v236
	v_min_f32_e32 v153, 0x42a00000, v237
	v_min_f32_e32 v154, 0x42a00000, v238
	v_min_f32_e32 v155, 0x42a00000, v239
	v_min_f32_e32 v156, 0x42a00000, v244
	v_min_f32_e32 v157, 0x42a00000, v245
	v_min_f32_e32 v158, 0x42a00000, v246
	v_min_f32_e32 v159, 0x42a00000, v247
	s_waitcnt vmcnt(6)
	v_mfma_f32_16x16x32_bf16 v[236:239], v[0:3], v[48:51], 0
	v_mfma_f32_16x16x32_bf16 v[236:239], v[4:7], v[52:55], v[236:239]
	v_mfma_f32_16x16x32_bf16 v[244:247], v[0:3], v[56:59], 0
	v_mfma_f32_16x16x32_bf16 v[244:247], v[4:7], v[60:63], v[244:247]
	v_mul_f32_e32 v152, 0x3fb8aa3b, v152
	v_mul_f32_e32 v153, 0x3fb8aa3b, v153
	v_mul_f32_e32 v154, 0x3fb8aa3b, v154
	v_mul_f32_e32 v155, 0x3fb8aa3b, v155
	v_exp_f32_e32 v152, v152
	v_exp_f32_e32 v153, v153
	v_exp_f32_e32 v154, v154
	v_exp_f32_e32 v155, v155
	v_add_u32_e32 v138, 64, v175
	v_add_u32_e32 v139, 0x41, v175
	v_add_u32_e32 v140, 0x42, v175
	v_add_u32_e32 v141, 0x43, v175
	v_cmp_gt_u32_e64 s[70:71], s44, v138
	v_cmp_gt_u32_e64 s[72:73], s44, v139
	v_cmp_gt_u32_e64 s[74:75], s44, v140
	v_cmp_gt_u32_e64 s[76:77], s44, v141
	v_cndmask_b32_e64 v152, 0, v152, s[70:71]
	v_cndmask_b32_e64 v153, 0, v153, s[72:73]
	v_cndmask_b32_e64 v154, 0, v154, s[74:75]
	v_cndmask_b32_e64 v155, 0, v155, s[76:77]
	v_add_f32_e32 v132, v132, v152
	v_add_f32_e32 v132, v132, v153
	v_add_f32_e32 v132, v132, v154
	v_add_f32_e32 v132, v132, v155
	v_cvt_pk_bf16_f32 v120, v152, v153
	v_cvt_pk_bf16_f32 v121, v154, v155
	v_mul_f32_e32 v156, 0x3fb8aa3b, v156
	v_mul_f32_e32 v157, 0x3fb8aa3b, v157
	v_mul_f32_e32 v158, 0x3fb8aa3b, v158
	v_mul_f32_e32 v159, 0x3fb8aa3b, v159
	v_exp_f32_e32 v156, v156
	v_exp_f32_e32 v157, v157
	v_exp_f32_e32 v158, v158
	v_exp_f32_e32 v159, v159
	v_add_u32_e32 v138, 64, v175
	v_add_u32_e32 v139, 0x41, v175
	v_add_u32_e32 v140, 0x42, v175
	v_add_u32_e32 v141, 0x43, v175
	v_cmp_gt_u32_e64 s[70:71], s44, v138
	v_cmp_gt_u32_e64 s[72:73], s44, v139
	v_cmp_gt_u32_e64 s[74:75], s44, v140
	v_cmp_gt_u32_e64 s[76:77], s44, v141
	v_cndmask_b32_e64 v156, 0, v156, s[70:71]
	v_cndmask_b32_e64 v157, 0, v157, s[72:73]
	v_cndmask_b32_e64 v158, 0, v158, s[74:75]
	v_cndmask_b32_e64 v159, 0, v159, s[76:77]
	v_add_f32_e32 v133, v133, v156
	v_add_f32_e32 v133, v133, v157
	v_add_f32_e32 v133, v133, v158
	v_add_f32_e32 v133, v133, v159
	v_cvt_pk_bf16_f32 v192, v156, v157
	v_cvt_pk_bf16_f32 v193, v158, v159
	v_min_f32_e32 v152, 0x42a00000, v240
	v_min_f32_e32 v153, 0x42a00000, v241
	v_min_f32_e32 v154, 0x42a00000, v242
	v_min_f32_e32 v155, 0x42a00000, v243
	v_min_f32_e32 v156, 0x42a00000, v248
	v_min_f32_e32 v157, 0x42a00000, v249
	v_min_f32_e32 v158, 0x42a00000, v250
	v_min_f32_e32 v159, 0x42a00000, v251
	s_waitcnt vmcnt(4)
	v_mfma_f32_16x16x32_bf16 v[240:243], v[8:11], v[48:51], 0
	v_mfma_f32_16x16x32_bf16 v[240:243], v[12:15], v[52:55], v[240:243]
	v_mfma_f32_16x16x32_bf16 v[248:251], v[8:11], v[56:59], 0
	v_mfma_f32_16x16x32_bf16 v[248:251], v[12:15], v[60:63], v[248:251]
	v_mul_f32_e32 v152, 0x3fb8aa3b, v152
	v_mul_f32_e32 v153, 0x3fb8aa3b, v153
	v_mul_f32_e32 v154, 0x3fb8aa3b, v154
	v_mul_f32_e32 v155, 0x3fb8aa3b, v155
	v_exp_f32_e32 v152, v152
	v_exp_f32_e32 v153, v153
	v_exp_f32_e32 v154, v154
	v_exp_f32_e32 v155, v155
	v_add_u32_e32 v138, 0x50, v175
	v_add_u32_e32 v139, 0x51, v175
	v_add_u32_e32 v140, 0x52, v175
	v_add_u32_e32 v141, 0x53, v175
	v_cmp_gt_u32_e64 s[70:71], s44, v138
	v_cmp_gt_u32_e64 s[72:73], s44, v139
	v_cmp_gt_u32_e64 s[74:75], s44, v140
	v_cmp_gt_u32_e64 s[76:77], s44, v141
	v_cndmask_b32_e64 v152, 0, v152, s[70:71]
	v_cndmask_b32_e64 v153, 0, v153, s[72:73]
	v_cndmask_b32_e64 v154, 0, v154, s[74:75]
	v_cndmask_b32_e64 v155, 0, v155, s[76:77]
	v_add_f32_e32 v132, v132, v152
	v_add_f32_e32 v132, v132, v153
	v_add_f32_e32 v132, v132, v154
	v_add_f32_e32 v132, v132, v155
	v_cvt_pk_bf16_f32 v122, v152, v153
	v_cvt_pk_bf16_f32 v123, v154, v155
	v_mul_f32_e32 v156, 0x3fb8aa3b, v156
	v_mul_f32_e32 v157, 0x3fb8aa3b, v157
	v_mul_f32_e32 v158, 0x3fb8aa3b, v158
	v_mul_f32_e32 v159, 0x3fb8aa3b, v159
	v_exp_f32_e32 v156, v156
	v_exp_f32_e32 v157, v157
	v_exp_f32_e32 v158, v158
	v_exp_f32_e32 v159, v159
	v_add_u32_e32 v138, 0x50, v175
	v_add_u32_e32 v139, 0x51, v175
	v_add_u32_e32 v140, 0x52, v175
	v_add_u32_e32 v141, 0x53, v175
	v_cmp_gt_u32_e64 s[70:71], s44, v138
	v_cmp_gt_u32_e64 s[72:73], s44, v139
	v_cmp_gt_u32_e64 s[74:75], s44, v140
	v_cmp_gt_u32_e64 s[76:77], s44, v141
	v_cndmask_b32_e64 v156, 0, v156, s[70:71]
	v_cndmask_b32_e64 v157, 0, v157, s[72:73]
	v_cndmask_b32_e64 v158, 0, v158, s[74:75]
	v_cndmask_b32_e64 v159, 0, v159, s[76:77]
	v_add_f32_e32 v133, v133, v156
	v_add_f32_e32 v133, v133, v157
	v_add_f32_e32 v133, v133, v158
	v_add_f32_e32 v133, v133, v159
	v_cvt_pk_bf16_f32 v194, v156, v157
	v_cvt_pk_bf16_f32 v195, v158, v159
	v_min_f32_e32 v152, 0x42a00000, v236
	v_min_f32_e32 v153, 0x42a00000, v237
	v_min_f32_e32 v154, 0x42a00000, v238
	v_min_f32_e32 v155, 0x42a00000, v239
	v_min_f32_e32 v156, 0x42a00000, v244
	v_min_f32_e32 v157, 0x42a00000, v245
	v_min_f32_e32 v158, 0x42a00000, v246
	v_min_f32_e32 v159, 0x42a00000, v247
	s_waitcnt vmcnt(2)
	v_mfma_f32_16x16x32_bf16 v[236:239], v[16:19], v[48:51], 0
	v_mfma_f32_16x16x32_bf16 v[236:239], v[20:23], v[52:55], v[236:239]
	v_mfma_f32_16x16x32_bf16 v[244:247], v[16:19], v[56:59], 0
	v_mfma_f32_16x16x32_bf16 v[244:247], v[20:23], v[60:63], v[244:247]
	v_mul_f32_e32 v152, 0x3fb8aa3b, v152
	v_mul_f32_e32 v153, 0x3fb8aa3b, v153
	v_mul_f32_e32 v154, 0x3fb8aa3b, v154
	v_mul_f32_e32 v155, 0x3fb8aa3b, v155
	v_exp_f32_e32 v152, v152
	v_exp_f32_e32 v153, v153
	v_exp_f32_e32 v154, v154
	v_exp_f32_e32 v155, v155
	v_add_u32_e32 v138, 0x60, v175
	v_add_u32_e32 v139, 0x61, v175
	v_add_u32_e32 v140, 0x62, v175
	v_add_u32_e32 v141, 0x63, v175
	v_cmp_gt_u32_e64 s[70:71], s44, v138
	v_cmp_gt_u32_e64 s[72:73], s44, v139
	v_cmp_gt_u32_e64 s[74:75], s44, v140
	v_cmp_gt_u32_e64 s[76:77], s44, v141
	v_cndmask_b32_e64 v152, 0, v152, s[70:71]
	v_cndmask_b32_e64 v153, 0, v153, s[72:73]
	v_cndmask_b32_e64 v154, 0, v154, s[74:75]
	v_cndmask_b32_e64 v155, 0, v155, s[76:77]
	v_add_f32_e32 v132, v132, v152
	v_add_f32_e32 v132, v132, v153
	v_add_f32_e32 v132, v132, v154
	v_add_f32_e32 v132, v132, v155
	v_cvt_pk_bf16_f32 v124, v152, v153
	v_cvt_pk_bf16_f32 v125, v154, v155
	v_mul_f32_e32 v156, 0x3fb8aa3b, v156
	v_mul_f32_e32 v157, 0x3fb8aa3b, v157
	v_mul_f32_e32 v158, 0x3fb8aa3b, v158
	v_mul_f32_e32 v159, 0x3fb8aa3b, v159
	v_exp_f32_e32 v156, v156
	v_exp_f32_e32 v157, v157
	v_exp_f32_e32 v158, v158
	v_exp_f32_e32 v159, v159
	v_add_u32_e32 v138, 0x60, v175
	v_add_u32_e32 v139, 0x61, v175
	v_add_u32_e32 v140, 0x62, v175
	v_add_u32_e32 v141, 0x63, v175
	v_cmp_gt_u32_e64 s[70:71], s44, v138
	v_cmp_gt_u32_e64 s[72:73], s44, v139
	v_cmp_gt_u32_e64 s[74:75], s44, v140
	v_cmp_gt_u32_e64 s[76:77], s44, v141
	v_cndmask_b32_e64 v156, 0, v156, s[70:71]
	v_cndmask_b32_e64 v157, 0, v157, s[72:73]
	v_cndmask_b32_e64 v158, 0, v158, s[74:75]
	v_cndmask_b32_e64 v159, 0, v159, s[76:77]
	v_add_f32_e32 v133, v133, v156
	v_add_f32_e32 v133, v133, v157
	v_add_f32_e32 v133, v133, v158
	v_add_f32_e32 v133, v133, v159
	v_cvt_pk_bf16_f32 v196, v156, v157
	v_cvt_pk_bf16_f32 v197, v158, v159
	v_min_f32_e32 v152, 0x42a00000, v240
	v_min_f32_e32 v153, 0x42a00000, v241
	v_min_f32_e32 v154, 0x42a00000, v242
	v_min_f32_e32 v155, 0x42a00000, v243
	v_min_f32_e32 v156, 0x42a00000, v248
	v_min_f32_e32 v157, 0x42a00000, v249
	v_min_f32_e32 v158, 0x42a00000, v250
	v_min_f32_e32 v159, 0x42a00000, v251
	s_waitcnt vmcnt(0)
	v_mfma_f32_16x16x32_bf16 v[248:251], v[24:27], v[56:59], 0
	v_mfma_f32_16x16x32_bf16 v[248:251], v[28:31], v[60:63], v[248:251]
	v_mul_f32_e32 v152, 0x3fb8aa3b, v152
	v_mul_f32_e32 v153, 0x3fb8aa3b, v153
	v_mul_f32_e32 v154, 0x3fb8aa3b, v154
	v_mul_f32_e32 v155, 0x3fb8aa3b, v155
	v_exp_f32_e32 v152, v152
	v_exp_f32_e32 v153, v153
	v_exp_f32_e32 v154, v154
	v_exp_f32_e32 v155, v155
	v_add_u32_e32 v138, 0x70, v175
	v_add_u32_e32 v139, 0x71, v175
	v_add_u32_e32 v140, 0x72, v175
	v_add_u32_e32 v141, 0x73, v175
	v_cmp_gt_u32_e64 s[70:71], s44, v138
	v_cmp_gt_u32_e64 s[72:73], s44, v139
	v_cmp_gt_u32_e64 s[74:75], s44, v140
	v_cmp_gt_u32_e64 s[76:77], s44, v141
	v_cndmask_b32_e64 v152, 0, v152, s[70:71]
	v_cndmask_b32_e64 v153, 0, v153, s[72:73]
	v_cndmask_b32_e64 v154, 0, v154, s[74:75]
	v_cndmask_b32_e64 v155, 0, v155, s[76:77]
	v_add_f32_e32 v132, v132, v152
	v_add_f32_e32 v132, v132, v153
	v_add_f32_e32 v132, v132, v154
	v_add_f32_e32 v132, v132, v155
	v_cvt_pk_bf16_f32 v126, v152, v153
	v_cvt_pk_bf16_f32 v127, v154, v155
	v_mul_f32_e32 v156, 0x3fb8aa3b, v156
	v_mul_f32_e32 v157, 0x3fb8aa3b, v157
	v_mul_f32_e32 v158, 0x3fb8aa3b, v158
	v_mul_f32_e32 v159, 0x3fb8aa3b, v159
	v_exp_f32_e32 v156, v156
	v_exp_f32_e32 v157, v157
	v_exp_f32_e32 v158, v158
	v_exp_f32_e32 v159, v159
	v_add_u32_e32 v138, 0x70, v175
	v_add_u32_e32 v139, 0x71, v175
	v_add_u32_e32 v140, 0x72, v175
	v_add_u32_e32 v141, 0x73, v175
	v_cmp_gt_u32_e64 s[70:71], s44, v138
	v_cmp_gt_u32_e64 s[72:73], s44, v139
	v_cmp_gt_u32_e64 s[74:75], s44, v140
	v_cmp_gt_u32_e64 s[76:77], s44, v141
	v_cndmask_b32_e64 v156, 0, v156, s[70:71]
	v_cndmask_b32_e64 v157, 0, v157, s[72:73]
	v_cndmask_b32_e64 v158, 0, v158, s[74:75]
	v_cndmask_b32_e64 v159, 0, v159, s[76:77]
	v_add_f32_e32 v133, v133, v156
	v_add_f32_e32 v133, v133, v157
	v_add_f32_e32 v133, v133, v158
	v_add_f32_e32 v133, v133, v159
	v_cvt_pk_bf16_f32 v198, v156, v157
	v_cvt_pk_bf16_f32 v199, v158, v159
	v_min_f32_e32 v152, 0x42a00000, v236
	v_min_f32_e32 v153, 0x42a00000, v237
	v_min_f32_e32 v154, 0x42a00000, v238
	v_min_f32_e32 v155, 0x42a00000, v239
	v_min_f32_e32 v156, 0x42a00000, v244
	v_min_f32_e32 v157, 0x42a00000, v245
	v_min_f32_e32 v158, 0x42a00000, v246
	v_min_f32_e32 v159, 0x42a00000, v247
	v_mul_f32_e32 v152, 0x3fb8aa3b, v152
	v_mul_f32_e32 v153, 0x3fb8aa3b, v153
	v_mul_f32_e32 v154, 0x3fb8aa3b, v154
	v_mul_f32_e32 v155, 0x3fb8aa3b, v155
	v_exp_f32_e32 v152, v152
	v_exp_f32_e32 v153, v153
	v_exp_f32_e32 v154, v154
	v_exp_f32_e32 v155, v155
	v_add_u32_e32 v138, 0x80, v175
	v_add_u32_e32 v139, 0x81, v175
	v_add_u32_e32 v140, 0x82, v175
	v_add_u32_e32 v141, 0x83, v175
	v_cmp_gt_u32_e64 s[70:71], s44, v138
	v_cmp_gt_u32_e64 s[72:73], s44, v139
	v_cmp_gt_u32_e64 s[74:75], s44, v140
	v_cmp_gt_u32_e64 s[76:77], s44, v141
	v_cndmask_b32_e64 v152, 0, v152, s[62:63]
	v_cndmask_b32_e64 v153, 0, v153, s[64:65]
	v_cndmask_b32_e64 v154, 0, v154, s[66:67]
	v_cndmask_b32_e64 v155, 0, v155, s[68:69]
	v_cndmask_b32_e64 v152, 0, v152, s[70:71]
	v_cndmask_b32_e64 v153, 0, v153, s[72:73]
	v_cndmask_b32_e64 v154, 0, v154, s[74:75]
	v_cndmask_b32_e64 v155, 0, v155, s[76:77]
	v_add_f32_e32 v132, v132, v152
	v_add_f32_e32 v132, v132, v153
	v_add_f32_e32 v132, v132, v154
	v_add_f32_e32 v132, v132, v155
	v_cvt_pk_bf16_f32 v128, v152, v153
	v_cvt_pk_bf16_f32 v129, v154, v155
	v_mul_f32_e32 v156, 0x3fb8aa3b, v156
	v_mul_f32_e32 v157, 0x3fb8aa3b, v157
	v_mul_f32_e32 v158, 0x3fb8aa3b, v158
	v_mul_f32_e32 v159, 0x3fb8aa3b, v159
	v_exp_f32_e32 v156, v156
	v_exp_f32_e32 v157, v157
	v_exp_f32_e32 v158, v158
	v_exp_f32_e32 v159, v159
	v_add_u32_e32 v138, 0x80, v175
	v_add_u32_e32 v139, 0x81, v175
	v_add_u32_e32 v140, 0x82, v175
	v_add_u32_e32 v141, 0x83, v175
	v_cmp_gt_u32_e64 s[70:71], s44, v138
	v_cmp_gt_u32_e64 s[72:73], s44, v139
	v_cmp_gt_u32_e64 s[74:75], s44, v140
	v_cmp_gt_u32_e64 s[76:77], s44, v141
	v_cndmask_b32_e64 v156, 0, v156, s[70:71]
	v_cndmask_b32_e64 v157, 0, v157, s[72:73]
	v_cndmask_b32_e64 v158, 0, v158, s[74:75]
	v_cndmask_b32_e64 v159, 0, v159, s[76:77]
	v_add_f32_e32 v133, v133, v156
	v_add_f32_e32 v133, v133, v157
	v_add_f32_e32 v133, v133, v158
	v_add_f32_e32 v133, v133, v159
	v_cvt_pk_bf16_f32 v200, v156, v157
	v_cvt_pk_bf16_f32 v201, v158, v159
	v_min_f32_e32 v156, 0x42a00000, v248
	v_min_f32_e32 v157, 0x42a00000, v249
	v_min_f32_e32 v158, 0x42a00000, v250
	v_min_f32_e32 v159, 0x42a00000, v251
	v_mul_f32_e32 v156, 0x3fb8aa3b, v156
	v_mul_f32_e32 v157, 0x3fb8aa3b, v157
	v_mul_f32_e32 v158, 0x3fb8aa3b, v158
	v_mul_f32_e32 v159, 0x3fb8aa3b, v159
	v_exp_f32_e32 v156, v156
	v_exp_f32_e32 v157, v157
	v_exp_f32_e32 v158, v158
	v_exp_f32_e32 v159, v159
	v_add_u32_e32 v138, 0x90, v175
	v_add_u32_e32 v139, 0x91, v175
	v_add_u32_e32 v140, 0x92, v175
	v_add_u32_e32 v141, 0x93, v175
	v_cmp_gt_u32_e64 s[70:71], s44, v138
	v_cmp_gt_u32_e64 s[72:73], s44, v139
	v_cmp_gt_u32_e64 s[74:75], s44, v140
	v_cmp_gt_u32_e64 s[76:77], s44, v141
	v_cndmask_b32_e64 v156, 0, v156, s[62:63]
	v_cndmask_b32_e64 v157, 0, v157, s[64:65]
	v_cndmask_b32_e64 v158, 0, v158, s[66:67]
	v_cndmask_b32_e64 v159, 0, v159, s[68:69]
	v_cndmask_b32_e64 v156, 0, v156, s[70:71]
	v_cndmask_b32_e64 v157, 0, v157, s[72:73]
	v_cndmask_b32_e64 v158, 0, v158, s[74:75]
	v_cndmask_b32_e64 v159, 0, v159, s[76:77]
	v_add_f32_e32 v133, v133, v156
	v_add_f32_e32 v133, v133, v157
	v_add_f32_e32 v133, v133, v158
	v_add_f32_e32 v133, v133, v159
	v_cvt_pk_bf16_f32 v202, v156, v157
	v_cvt_pk_bf16_f32 v203, v158, v159
	v_add_u32_e32 v134, s42, v160
	v_lshlrev_b32_e32 v134, 4, v134
	v_add_u32_e32 v134, s43, v134
	v_subrev_u32_e32 v135, s15, v134
	v_lshrrev_b32_e32 v136, 4, v135
	v_add_u32_e32 v136, v136, v135
	v_mad_u32_u24 v176, v136, s79, v161
	v_lshl_add_u32 v177, v135, 2, s80
	s_sub_i32 s2, s42, 64
	v_add_u32_e32 v178, s2, v169
	v_and_b32_e32 v135, 3, v134
	v_lshlrev_b32_e32 v135, s13, v135
	v_lshrrev_b32_e32 v136, 2, v134
	v_add_u32_e32 v135, v135, v136
	v_lshl_add_u32 v135, v135, 7, v161
	v_subrev_u32_e32 v134, 0x400, v134
	v_and_b32_e32 v137, 3, v134
	v_lshlrev_b32_e32 v137, s13, v137
	v_bfe_u32 v135, v134, 2, 2
	v_add_u32_e32 v137, v137, v135
	v_lshl_add_u32 v183, v137, 7, v161
	v_ashrrev_i32_e32 v252, 4, v134
	v_med3_i32 v136, v252, 0, s14
	v_lshl_add_u32 v136, v136, 9, v183
	global_load_dwordx4 v[0:3], v136, s[20:21]
	global_load_dwordx4 v[4:7], v136, s[20:21] offset:64
	v_add_u32_e32 v135, 16, v252
	v_med3_i32 v135, v135, 0, s14
	v_lshl_add_u32 v135, v135, 9, v183
	global_load_dwordx4 v[8:11], v135, s[20:21]
	global_load_dwordx4 v[12:15], v135, s[20:21] offset:64
	v_add_u32_e32 v136, 32, v252
	v_med3_i32 v136, v136, 0, s14
	v_lshl_add_u32 v136, v136, 9, v183
	global_load_dwordx4 v[16:19], v136, s[20:21]
	global_load_dwordx4 v[20:23], v136, s[20:21] offset:64
	v_add_u32_e32 v135, 48, v252
	v_med3_i32 v135, v135, 0, s14
	v_lshl_add_u32 v135, v135, 9, v183
	global_load_dwordx4 v[24:27], v135, s[20:21]
	global_load_dwordx4 v[28:31], v135, s[20:21] offset:64
	v_add_u32_e32 v136, 64, v252
	v_med3_i32 v136, v136, 0, s14
	v_lshl_add_u32 v136, v136, 9, v183
	global_load_dwordx4 v[32:35], v136, s[20:21]
	global_load_dwordx4 v[36:39], v136, s[20:21] offset:64
	v_add_u32_e32 v135, 0x50, v252
	v_med3_i32 v135, v135, 0, s14
	v_lshl_add_u32 v135, v135, 9, v183
	global_load_dwordx4 v[40:43], v135, s[20:21]
	global_load_dwordx4 v[44:47], v135, s[20:21] offset:64
	ds_bpermute_b32 v142, v167, v132
	s_waitcnt lgkmcnt(0)
	v_add_f32_e32 v132, v132, v142
	ds_bpermute_b32 v142, v168, v132
	s_waitcnt lgkmcnt(0)
	v_add_f32_e32 v132, v132, v142
	ds_bpermute_b32 v142, v167, v133
	s_waitcnt lgkmcnt(0)
	v_add_f32_e32 v133, v133, v142
	ds_bpermute_b32 v142, v168, v133
	s_waitcnt lgkmcnt(0)
	v_add_f32_e32 v133, v133, v142
	s_waitcnt vmcnt(12)
	ds_write_b128 v165, v[64:67]
	ds_write_b128 v165, v[68:71] offset:1152
	ds_write_b128 v165, v[72:75] offset:2304
	ds_write_b128 v165, v[76:79] offset:3456
	s_waitcnt lgkmcnt(0)
	ds_read_b64_tr_b16 v[236:237], v166
	ds_read_b64_tr_b16 v[238:239], v166 offset:2304
	ds_read_b64_tr_b16 v[240:241], v166 offset:32
	ds_read_b64_tr_b16 v[242:243], v166 offset:2336
	ds_read_b64_tr_b16 v[244:245], v166 offset:64
	ds_read_b64_tr_b16 v[246:247], v166 offset:2368
	ds_read_b64_tr_b16 v[248:249], v166 offset:96
	ds_read_b64_tr_b16 v[250:251], v166 offset:2400
	s_waitcnt lgkmcnt(0)
	s_add_i32 s2, s40, 32
	v_add_u32_e32 v138, s2, v164
	v_lshlrev_b32_e32 v138, 2, v138
	v_add_u32_e32 v138, s41, v138
	v_and_b32_e32 v139, 3, v138
	v_lshlrev_b32_e32 v139, s39, v139
	v_bfe_u32 v140, v138, 2, 2
	v_add_u32_e32 v139, v139, v140
	v_lshl_add_u32 v139, v139, 7, v162
	v_ashrrev_i32_e32 v138, 4, v138
	v_med3_i32 v138, v138, 0, s38
	v_lshl_add_u32 v138, v138, 9, v139
	global_load_dwordx4 v[64:67], v138, s[26:27]
	s_add_i32 s2, s40, 40
	v_add_u32_e32 v138, s2, v164
	v_lshlrev_b32_e32 v138, 2, v138
	v_add_u32_e32 v138, s41, v138
	v_and_b32_e32 v139, 3, v138
	v_lshlrev_b32_e32 v139, s39, v139
	v_bfe_u32 v140, v138, 2, 2
	v_add_u32_e32 v139, v139, v140
	v_lshl_add_u32 v139, v139, 7, v162
	v_ashrrev_i32_e32 v138, 4, v138
	v_med3_i32 v138, v138, 0, s38
	v_lshl_add_u32 v138, v138, 9, v139
	global_load_dwordx4 v[68:71], v138, s[26:27]
	s_add_i32 s2, s40, 48
	v_add_u32_e32 v138, s2, v164
	v_lshlrev_b32_e32 v138, 2, v138
	v_add_u32_e32 v138, s41, v138
	v_and_b32_e32 v139, 3, v138
	v_lshlrev_b32_e32 v139, s39, v139
	v_bfe_u32 v140, v138, 2, 2
	v_add_u32_e32 v139, v139, v140
	v_lshl_add_u32 v139, v139, 7, v162
	v_ashrrev_i32_e32 v138, 4, v138
	v_med3_i32 v138, v138, 0, s38
	v_lshl_add_u32 v138, v138, 9, v139
	global_load_dwordx4 v[72:75], v138, s[26:27]
	s_add_i32 s2, s40, 56
	v_add_u32_e32 v138, s2, v164
	v_lshlrev_b32_e32 v138, 2, v138
	v_add_u32_e32 v138, s41, v138
	v_and_b32_e32 v139, 3, v138
	v_lshlrev_b32_e32 v139, s39, v139
	v_bfe_u32 v140, v138, 2, 2
	v_add_u32_e32 v139, v139, v140
	v_lshl_add_u32 v139, v139, 7, v162
	v_ashrrev_i32_e32 v138, 4, v138
	v_med3_i32 v138, v138, 0, s38
	v_lshl_add_u32 v138, v138, 9, v139
	global_load_dwordx4 v[76:79], v138, s[26:27]
	ds_write_b128 v165, v[80:83]
	ds_write_b128 v165, v[84:87] offset:1152
	ds_write_b128 v165, v[88:91] offset:2304
	ds_write_b128 v165, v[92:95] offset:3456
	v_mfma_f32_16x16x32_bf16 v[204:207], v[236:239], v[112:115], 0
	v_mfma_f32_16x16x32_bf16 v[208:211], v[240:243], v[112:115], 0
	v_mfma_f32_16x16x32_bf16 v[212:215], v[244:247], v[112:115], 0
	v_mfma_f32_16x16x32_bf16 v[216:219], v[248:251], v[112:115], 0
	v_mfma_f32_16x16x32_bf16 v[220:223], v[236:239], v[184:187], 0
	v_mfma_f32_16x16x32_bf16 v[224:227], v[240:243], v[184:187], 0
	v_mfma_f32_16x16x32_bf16 v[228:231], v[244:247], v[184:187], 0
	v_mfma_f32_16x16x32_bf16 v[232:235], v[248:251], v[184:187], 0
	s_waitcnt lgkmcnt(0)
	ds_read_b64_tr_b16 v[236:237], v166
	ds_read_b64_tr_b16 v[238:239], v166 offset:2304
	ds_read_b64_tr_b16 v[240:241], v166 offset:32
	ds_read_b64_tr_b16 v[242:243], v166 offset:2336
	ds_read_b64_tr_b16 v[244:245], v166 offset:64
	ds_read_b64_tr_b16 v[246:247], v166 offset:2368
	ds_read_b64_tr_b16 v[248:249], v166 offset:96
	ds_read_b64_tr_b16 v[250:251], v166 offset:2400
	s_waitcnt lgkmcnt(0)
	s_add_i32 s2, s40, 64
	v_add_u32_e32 v138, s2, v164
	v_lshlrev_b32_e32 v138, 2, v138
	v_add_u32_e32 v138, s41, v138
	v_and_b32_e32 v139, 3, v138
	v_lshlrev_b32_e32 v139, s39, v139
	v_bfe_u32 v140, v138, 2, 2
	v_add_u32_e32 v139, v139, v140
	v_lshl_add_u32 v139, v139, 7, v162
	v_ashrrev_i32_e32 v138, 4, v138
	v_med3_i32 v138, v138, 0, s38
	v_lshl_add_u32 v138, v138, 9, v139
	global_load_dwordx4 v[80:83], v138, s[26:27]
	s_add_i32 s2, s40, 72
	v_add_u32_e32 v138, s2, v164
	v_lshlrev_b32_e32 v138, 2, v138
	v_add_u32_e32 v138, s41, v138
	v_and_b32_e32 v139, 3, v138
	v_lshlrev_b32_e32 v139, s39, v139
	v_bfe_u32 v140, v138, 2, 2
	v_add_u32_e32 v139, v139, v140
	v_lshl_add_u32 v139, v139, 7, v162
	v_ashrrev_i32_e32 v138, 4, v138
	v_med3_i32 v138, v138, 0, s38
	v_lshl_add_u32 v138, v138, 9, v139
	global_load_dwordx4 v[84:87], v138, s[26:27]
	s_add_i32 s2, s40, 80
	v_add_u32_e32 v138, s2, v164
	v_lshlrev_b32_e32 v138, 2, v138
	v_add_u32_e32 v138, s41, v138
	v_and_b32_e32 v139, 3, v138
	v_lshlrev_b32_e32 v139, s39, v139
	v_bfe_u32 v140, v138, 2, 2
	v_add_u32_e32 v139, v139, v140
	v_lshl_add_u32 v139, v139, 7, v162
	v_ashrrev_i32_e32 v138, 4, v138
	v_med3_i32 v138, v138, 0, s38
	v_lshl_add_u32 v138, v138, 9, v139
	global_load_dwordx4 v[88:91], v138, s[26:27]
	s_add_i32 s2, s40, 88
	v_add_u32_e32 v138, s2, v164
	v_lshlrev_b32_e32 v138, 2, v138
	v_add_u32_e32 v138, s41, v138
	v_and_b32_e32 v139, 3, v138
	v_lshlrev_b32_e32 v139, s39, v139
	v_bfe_u32 v140, v138, 2, 2
	v_add_u32_e32 v139, v139, v140
	v_lshl_add_u32 v139, v139, 7, v162
	v_ashrrev_i32_e32 v138, 4, v138
	v_med3_i32 v138, v138, 0, s38
	v_lshl_add_u32 v138, v138, 9, v139
	global_load_dwordx4 v[92:95], v138, s[26:27]
	ds_write_b128 v165, v[96:99]
	ds_write_b128 v165, v[100:103] offset:1152
	ds_write_b128 v165, v[104:107] offset:2304
	ds_write_b128 v165, v[108:111] offset:3456
	v_mfma_f32_16x16x32_bf16 v[204:207], v[236:239], v[116:119], v[204:207]
	v_mfma_f32_16x16x32_bf16 v[208:211], v[240:243], v[116:119], v[208:211]
	v_mfma_f32_16x16x32_bf16 v[212:215], v[244:247], v[116:119], v[212:215]
	v_mfma_f32_16x16x32_bf16 v[216:219], v[248:251], v[116:119], v[216:219]
	v_mfma_f32_16x16x32_bf16 v[220:223], v[236:239], v[188:191], v[220:223]
	v_mfma_f32_16x16x32_bf16 v[224:227], v[240:243], v[188:191], v[224:227]
	v_mfma_f32_16x16x32_bf16 v[228:231], v[244:247], v[188:191], v[228:231]
	v_mfma_f32_16x16x32_bf16 v[232:235], v[248:251], v[188:191], v[232:235]
	s_waitcnt lgkmcnt(0)
	ds_read_b64_tr_b16 v[236:237], v166
	ds_read_b64_tr_b16 v[238:239], v166 offset:2304
	ds_read_b64_tr_b16 v[240:241], v166 offset:32
	ds_read_b64_tr_b16 v[242:243], v166 offset:2336
	ds_read_b64_tr_b16 v[244:245], v166 offset:64
	ds_read_b64_tr_b16 v[246:247], v166 offset:2368
	ds_read_b64_tr_b16 v[248:249], v166 offset:96
	ds_read_b64_tr_b16 v[250:251], v166 offset:2400
	s_waitcnt lgkmcnt(0)
	s_waitcnt vmcnt(4)
	ds_write_b128 v165, v[64:67]
	ds_write_b128 v165, v[68:71] offset:1152
	ds_write_b128 v165, v[72:75] offset:2304
	ds_write_b128 v165, v[76:79] offset:3456
	v_mfma_f32_16x16x32_bf16 v[204:207], v[236:239], v[120:123], v[204:207]
	v_mfma_f32_16x16x32_bf16 v[208:211], v[240:243], v[120:123], v[208:211]
	v_mfma_f32_16x16x32_bf16 v[212:215], v[244:247], v[120:123], v[212:215]
	v_mfma_f32_16x16x32_bf16 v[216:219], v[248:251], v[120:123], v[216:219]
	v_mfma_f32_16x16x32_bf16 v[220:223], v[236:239], v[192:195], v[220:223]
	v_mfma_f32_16x16x32_bf16 v[224:227], v[240:243], v[192:195], v[224:227]
	v_mfma_f32_16x16x32_bf16 v[228:231], v[244:247], v[192:195], v[228:231]
	v_mfma_f32_16x16x32_bf16 v[232:235], v[248:251], v[192:195], v[232:235]
	s_waitcnt lgkmcnt(0)
	ds_read_b64_tr_b16 v[236:237], v166
	ds_read_b64_tr_b16 v[238:239], v166 offset:2304
	ds_read_b64_tr_b16 v[240:241], v166 offset:32
	ds_read_b64_tr_b16 v[242:243], v166 offset:2336
	ds_read_b64_tr_b16 v[244:245], v166 offset:64
	ds_read_b64_tr_b16 v[246:247], v166 offset:2368
	ds_read_b64_tr_b16 v[248:249], v166 offset:96
	ds_read_b64_tr_b16 v[250:251], v166 offset:2400
	s_waitcnt lgkmcnt(0)
	s_waitcnt vmcnt(0)
	ds_write_b128 v165, v[80:83]
	ds_write_b128 v165, v[84:87] offset:1152
	ds_write_b128 v165, v[88:91] offset:2304
	ds_write_b128 v165, v[92:95] offset:3456
	v_mfma_f32_16x16x32_bf16 v[204:207], v[236:239], v[124:127], v[204:207]
	v_mfma_f32_16x16x32_bf16 v[208:211], v[240:243], v[124:127], v[208:211]
	v_mfma_f32_16x16x32_bf16 v[212:215], v[244:247], v[124:127], v[212:215]
	v_mfma_f32_16x16x32_bf16 v[216:219], v[248:251], v[124:127], v[216:219]
	v_mfma_f32_16x16x32_bf16 v[220:223], v[236:239], v[196:199], v[220:223]
	v_mfma_f32_16x16x32_bf16 v[224:227], v[240:243], v[196:199], v[224:227]
	v_mfma_f32_16x16x32_bf16 v[228:231], v[244:247], v[196:199], v[228:231]
	v_mfma_f32_16x16x32_bf16 v[232:235], v[248:251], v[196:199], v[232:235]
	s_waitcnt lgkmcnt(0)
	ds_read_b64_tr_b16 v[236:237], v166
	ds_read_b64_tr_b16 v[238:239], v166 offset:2304
	ds_read_b64_tr_b16 v[240:241], v166 offset:32
	ds_read_b64_tr_b16 v[242:243], v166 offset:2336
	ds_read_b64_tr_b16 v[244:245], v166 offset:64
	ds_read_b64_tr_b16 v[246:247], v166 offset:2368
	ds_read_b64_tr_b16 v[248:249], v166 offset:96
	ds_read_b64_tr_b16 v[250:251], v166 offset:2400
	s_waitcnt lgkmcnt(0)
	v_mfma_f32_16x16x32_bf16 v[204:207], v[236:239], v[128:131], v[204:207]
	v_mfma_f32_16x16x32_bf16 v[208:211], v[240:243], v[128:131], v[208:211]
	v_mfma_f32_16x16x32_bf16 v[212:215], v[244:247], v[128:131], v[212:215]
	v_mfma_f32_16x16x32_bf16 v[216:219], v[248:251], v[128:131], v[216:219]
	v_mfma_f32_16x16x32_bf16 v[220:223], v[236:239], v[200:203], v[220:223]
	v_mfma_f32_16x16x32_bf16 v[224:227], v[240:243], v[200:203], v[224:227]
	v_mfma_f32_16x16x32_bf16 v[228:231], v[244:247], v[200:203], v[228:231]
	v_mfma_f32_16x16x32_bf16 v[232:235], v[248:251], v[200:203], v[232:235]
	s_add_i32 s2, s42, -64
	v_add_u32_e32 v138, s2, v164
	v_lshlrev_b32_e32 v138, 4, v138
	v_add_u32_e32 v138, s43, v138
	v_and_b32_e32 v139, 3, v138
	v_lshlrev_b32_e32 v139, s13, v139
	v_bfe_u32 v140, v138, 2, 2
	v_add_u32_e32 v139, v139, v140
	v_lshl_add_u32 v139, v139, 7, v162
	v_ashrrev_i32_e32 v138, 4, v138
	v_med3_i32 v138, v138, 0, s14
	v_lshl_add_u32 v138, v138, 9, v139
	global_load_dwordx4 v[64:67], v138, s[22:23]
	s_add_i32 s2, s42, -56
	v_add_u32_e32 v138, s2, v164
	v_lshlrev_b32_e32 v138, 4, v138
	v_add_u32_e32 v138, s43, v138
	v_and_b32_e32 v139, 3, v138
	v_lshlrev_b32_e32 v139, s13, v139
	v_bfe_u32 v140, v138, 2, 2
	v_add_u32_e32 v139, v139, v140
	v_lshl_add_u32 v139, v139, 7, v162
	v_ashrrev_i32_e32 v138, 4, v138
	v_med3_i32 v138, v138, 0, s14
	v_lshl_add_u32 v138, v138, 9, v139
	global_load_dwordx4 v[68:71], v138, s[22:23]
	s_add_i32 s2, s42, -48
	v_add_u32_e32 v138, s2, v164
	v_lshlrev_b32_e32 v138, 4, v138
	v_add_u32_e32 v138, s43, v138
	v_and_b32_e32 v139, 3, v138
	v_lshlrev_b32_e32 v139, s13, v139
	v_bfe_u32 v140, v138, 2, 2
	v_add_u32_e32 v139, v139, v140
	v_lshl_add_u32 v139, v139, 7, v162
	v_ashrrev_i32_e32 v138, 4, v138
	v_med3_i32 v138, v138, 0, s14
	v_lshl_add_u32 v138, v138, 9, v139
	global_load_dwordx4 v[72:75], v138, s[22:23]
	s_add_i32 s2, s42, -40
	v_add_u32_e32 v138, s2, v164
	v_lshlrev_b32_e32 v138, 4, v138
	v_add_u32_e32 v138, s43, v138
	v_and_b32_e32 v139, 3, v138
	v_lshlrev_b32_e32 v139, s13, v139
	v_bfe_u32 v140, v138, 2, 2
	v_add_u32_e32 v139, v139, v140
	v_lshl_add_u32 v139, v139, 7, v162
	v_ashrrev_i32_e32 v138, 4, v138
	v_med3_i32 v138, v138, 0, s14
	v_lshl_add_u32 v138, v138, 9, v139
	global_load_dwordx4 v[76:79], v138, s[22:23]
	s_add_i32 s2, s42, -32
	v_add_u32_e32 v138, s2, v164
	v_lshlrev_b32_e32 v138, 4, v138
	v_add_u32_e32 v138, s43, v138
	v_and_b32_e32 v139, 3, v138
	v_lshlrev_b32_e32 v139, s13, v139
	v_bfe_u32 v140, v138, 2, 2
	v_add_u32_e32 v139, v139, v140
	v_lshl_add_u32 v139, v139, 7, v162
	v_ashrrev_i32_e32 v138, 4, v138
	v_med3_i32 v138, v138, 0, s14
	v_lshl_add_u32 v138, v138, 9, v139
	global_load_dwordx4 v[80:83], v138, s[22:23]
	s_add_i32 s2, s42, -24
	v_add_u32_e32 v138, s2, v164
	v_lshlrev_b32_e32 v138, 4, v138
	v_add_u32_e32 v138, s43, v138
	v_and_b32_e32 v139, 3, v138
	v_lshlrev_b32_e32 v139, s13, v139
	v_bfe_u32 v140, v138, 2, 2
	v_add_u32_e32 v139, v139, v140
	v_lshl_add_u32 v139, v139, 7, v162
	v_ashrrev_i32_e32 v138, 4, v138
	v_med3_i32 v138, v138, 0, s14
	v_lshl_add_u32 v138, v138, 9, v139
	global_load_dwordx4 v[84:87], v138, s[22:23]
	s_add_i32 s2, s42, -16
	v_add_u32_e32 v138, s2, v164
	v_lshlrev_b32_e32 v138, 4, v138
	v_add_u32_e32 v138, s43, v138
	v_and_b32_e32 v139, 3, v138
	v_lshlrev_b32_e32 v139, s13, v139
	v_bfe_u32 v140, v138, 2, 2
	v_add_u32_e32 v139, v139, v140
	v_lshl_add_u32 v139, v139, 7, v162
	v_ashrrev_i32_e32 v138, 4, v138
	v_med3_i32 v138, v138, 0, s14
	v_lshl_add_u32 v138, v138, 9, v139
	global_load_dwordx4 v[88:91], v138, s[22:23]
	s_add_i32 s2, s42, -8
	v_add_u32_e32 v138, s2, v164
	v_lshlrev_b32_e32 v138, 4, v138
	v_add_u32_e32 v138, s43, v138
	v_and_b32_e32 v139, 3, v138
	v_lshlrev_b32_e32 v139, s13, v139
	v_bfe_u32 v140, v138, 2, 2
	v_add_u32_e32 v139, v139, v140
	v_lshl_add_u32 v139, v139, 7, v162
	v_ashrrev_i32_e32 v138, 4, v138
	v_med3_i32 v138, v138, 0, s14
	v_lshl_add_u32 v138, v138, 9, v139
	global_load_dwordx4 v[92:95], v138, s[22:23]
	s_add_i32 s2, s42, 0
	v_add_u32_e32 v138, s2, v164
	v_lshlrev_b32_e32 v138, 4, v138
	v_add_u32_e32 v138, s43, v138
	v_and_b32_e32 v139, 3, v138
	v_lshlrev_b32_e32 v139, s13, v139
	v_bfe_u32 v140, v138, 2, 2
	v_add_u32_e32 v139, v139, v140
	v_lshl_add_u32 v139, v139, 7, v162
	v_ashrrev_i32_e32 v138, 4, v138
	v_med3_i32 v138, v138, 0, s14
	v_lshl_add_u32 v138, v138, 9, v139
	global_load_dwordx4 v[96:99], v138, s[22:23]
	s_add_i32 s2, s42, 8
	v_add_u32_e32 v138, s2, v164
	v_lshlrev_b32_e32 v138, 4, v138
	v_add_u32_e32 v138, s43, v138
	v_and_b32_e32 v139, 3, v138
	v_lshlrev_b32_e32 v139, s13, v139
	v_bfe_u32 v140, v138, 2, 2
	v_add_u32_e32 v139, v139, v140
	v_lshl_add_u32 v139, v139, 7, v162
	v_ashrrev_i32_e32 v138, 4, v138
	v_med3_i32 v138, v138, 0, s14
	v_lshl_add_u32 v138, v138, 9, v139
	global_load_dwordx4 v[100:103], v138, s[22:23]
	s_add_i32 s2, s42, 16
	v_add_u32_e32 v138, s2, v164
	v_lshlrev_b32_e32 v138, 4, v138
	v_add_u32_e32 v138, s43, v138
	v_and_b32_e32 v139, 3, v138
	v_lshlrev_b32_e32 v139, s13, v139
	v_bfe_u32 v140, v138, 2, 2
	v_add_u32_e32 v139, v139, v140
	v_lshl_add_u32 v139, v139, 7, v162
	v_ashrrev_i32_e32 v138, 4, v138
	v_med3_i32 v138, v138, 0, s14
	v_lshl_add_u32 v138, v138, 9, v139
	global_load_dwordx4 v[104:107], v138, s[22:23]
	s_add_i32 s2, s42, 24
	v_add_u32_e32 v138, s2, v164
	v_lshlrev_b32_e32 v138, 4, v138
	v_add_u32_e32 v138, s43, v138
	v_and_b32_e32 v139, 3, v138
	v_lshlrev_b32_e32 v139, s13, v139
	v_bfe_u32 v140, v138, 2, 2
	v_add_u32_e32 v139, v139, v140
	v_lshl_add_u32 v139, v139, 7, v162
	v_ashrrev_i32_e32 v138, 4, v138
	v_med3_i32 v138, v138, 0, s14
	v_lshl_add_u32 v138, v138, 9, v139
	global_load_dwordx4 v[108:111], v138, s[22:23]
	ds_read_b128 v[236:239], v173 offset:0
	ds_read_b128 v[240:243], v173 offset:64
	ds_read_b128 v[244:247], v173 offset:128
	ds_read_b128 v[248:251], v173 offset:192
	ds_read_b32 v142, v174 offset:0
	s_waitcnt lgkmcnt(0)
	v_add_f32_e32 v204, v236, v204
	v_add_f32_e32 v205, v237, v205
	v_add_f32_e32 v206, v238, v206
	v_add_f32_e32 v207, v239, v207
	v_add_f32_e32 v208, v240, v208
	v_add_f32_e32 v209, v241, v209
	v_add_f32_e32 v210, v242, v210
	v_add_f32_e32 v211, v243, v211
	v_add_f32_e32 v212, v244, v212
	v_add_f32_e32 v213, v245, v213
	v_add_f32_e32 v214, v246, v214
	v_add_f32_e32 v215, v247, v215
	v_add_f32_e32 v216, v248, v216
	v_add_f32_e32 v217, v249, v217
	v_add_f32_e32 v218, v250, v218
	v_add_f32_e32 v219, v251, v219
	v_add_f32_e32 v132, v142, v132
	ds_write_b128 v173, v[204:207] offset:0
	ds_write_b128 v173, v[208:211] offset:64
	ds_write_b128 v173, v[212:215] offset:128
	ds_write_b128 v173, v[216:219] offset:192
	ds_write_b32 v174, v132 offset:0
	ds_read_b128 v[236:239], v173 offset:18496
	ds_read_b128 v[240:243], v173 offset:18560
	ds_read_b128 v[244:247], v173 offset:18624
	ds_read_b128 v[248:251], v173 offset:18688
	ds_read_b32 v142, v174 offset:256
	s_waitcnt lgkmcnt(0)
	v_add_f32_e32 v220, v236, v220
	v_add_f32_e32 v221, v237, v221
	v_add_f32_e32 v222, v238, v222
	v_add_f32_e32 v223, v239, v223
	v_add_f32_e32 v224, v240, v224
	v_add_f32_e32 v225, v241, v225
	v_add_f32_e32 v226, v242, v226
	v_add_f32_e32 v227, v243, v227
	v_add_f32_e32 v228, v244, v228
	v_add_f32_e32 v229, v245, v229
	v_add_f32_e32 v230, v246, v230
	v_add_f32_e32 v231, v247, v231
	v_add_f32_e32 v232, v248, v232
	v_add_f32_e32 v233, v249, v233
	v_add_f32_e32 v234, v250, v234
	v_add_f32_e32 v235, v251, v235
	v_add_f32_e32 v133, v142, v133
	ds_write_b128 v173, v[220:223] offset:18496
	ds_write_b128 v173, v[224:227] offset:18560
	ds_write_b128 v173, v[228:231] offset:18624
	ds_write_b128 v173, v[232:235] offset:18688
	ds_write_b32 v174, v133 offset:256
	s_waitcnt lgkmcnt(0)
	s_barrier
	s_mov_b32 s40, s42
	s_mov_b32 s41, s43
	v_mov_b32_e32 v173, v176
	v_mov_b32_e32 v174, v177
	v_mov_b32_e32 v175, v178
	v_mov_b32_e32 v179, v183
	v_mov_b32_e32 v182, v252
	s_lshr_b32 s44, s33, 4
	s_lshr_b32 s42, s15, 4
	s_add_i32 s43, s0, 8
	v_subrev_u32_e32 v143, s80, v174
	v_lshl_add_u32 v143, v143, 5, v161
	v_add_u32_e32 v143, 0x1b500, v143
	ds_read_b128 v[48:51], v143
	ds_read_b128 v[52:55], v143 offset:64
	s_waitcnt vmcnt(12)
	s_waitcnt lgkmcnt(0)
	v_mov_b32_e32 v132, 0
	v_mfma_f32_16x16x32_bf16 v[236:239], v[0:3], v[48:51], 0
	v_mfma_f32_16x16x32_bf16 v[236:239], v[4:7], v[52:55], v[236:239]
	v_mfma_f32_16x16x32_bf16 v[240:243], v[8:11], v[48:51], 0
	v_mfma_f32_16x16x32_bf16 v[240:243], v[12:15], v[52:55], v[240:243]
	s_nop 7
	v_min_f32_e32 v152, 0x42a00000, v236
	v_min_f32_e32 v153, 0x42a00000, v237
	v_min_f32_e32 v154, 0x42a00000, v238
	v_min_f32_e32 v155, 0x42a00000, v239
	v_mfma_f32_16x16x32_bf16 v[236:239], v[16:19], v[48:51], 0
	v_mfma_f32_16x16x32_bf16 v[236:239], v[20:23], v[52:55], v[236:239]
	v_add_u32_e32 v136, 0x60, v182
	v_med3_i32 v136, v136, 0, s38
	v_lshl_add_u32 v136, v136, 9, v179
	global_load_dwordx4 v[0:3], v136, s[24:25]
	global_load_dwordx4 v[4:7], v136, s[24:25] offset:64
	v_mul_f32_e32 v152, 0x3fb8aa3b, v152
	v_mul_f32_e32 v153, 0x3fb8aa3b, v153
	v_mul_f32_e32 v154, 0x3fb8aa3b, v154
	v_mul_f32_e32 v155, 0x3fb8aa3b, v155
	v_exp_f32_e32 v152, v152
	v_exp_f32_e32 v153, v153
	v_exp_f32_e32 v154, v154
	v_exp_f32_e32 v155, v155
	v_add_u32_e32 v138, 0, v175
	v_add_u32_e32 v139, 1, v175
	v_add_u32_e32 v140, 2, v175
	v_add_u32_e32 v141, 3, v175
	v_cmp_gt_u32_e64 s[70:71], s44, v138
	v_cmp_gt_u32_e64 s[72:73], s44, v139
	v_cmp_gt_u32_e64 s[74:75], s44, v140
	v_cmp_gt_u32_e64 s[76:77], s44, v141
	v_cndmask_b32_e64 v152, 0, v152, s[54:55]
	v_cndmask_b32_e64 v153, 0, v153, s[56:57]
	v_cndmask_b32_e64 v154, 0, v154, s[58:59]
	v_cndmask_b32_e64 v155, 0, v155, s[60:61]
	v_cndmask_b32_e64 v152, 0, v152, s[70:71]
	v_cndmask_b32_e64 v153, 0, v153, s[72:73]
	v_cndmask_b32_e64 v154, 0, v154, s[74:75]
	v_cndmask_b32_e64 v155, 0, v155, s[76:77]
	v_add_f32_e32 v132, v132, v152
	v_add_f32_e32 v132, v132, v153
	v_add_f32_e32 v132, v132, v154
	v_add_f32_e32 v132, v132, v155
	v_cvt_pk_bf16_f32 v112, v152, v153
	v_cvt_pk_bf16_f32 v113, v154, v155
	v_min_f32_e32 v152, 0x42a00000, v240
	v_min_f32_e32 v153, 0x42a00000, v241
	v_min_f32_e32 v154, 0x42a00000, v242
	v_min_f32_e32 v155, 0x42a00000, v243
	v_mfma_f32_16x16x32_bf16 v[240:243], v[24:27], v[48:51], 0
	v_mfma_f32_16x16x32_bf16 v[240:243], v[28:31], v[52:55], v[240:243]
	v_add_u32_e32 v135, 0x70, v182
	v_med3_i32 v135, v135, 0, s38
	v_lshl_add_u32 v135, v135, 9, v179
	global_load_dwordx4 v[8:11], v135, s[24:25]
	global_load_dwordx4 v[12:15], v135, s[24:25] offset:64
	v_mul_f32_e32 v152, 0x3fb8aa3b, v152
	v_mul_f32_e32 v153, 0x3fb8aa3b, v153
	v_mul_f32_e32 v154, 0x3fb8aa3b, v154
	v_mul_f32_e32 v155, 0x3fb8aa3b, v155
	v_exp_f32_e32 v152, v152
	v_exp_f32_e32 v153, v153
	v_exp_f32_e32 v154, v154
	v_exp_f32_e32 v155, v155
	v_add_u32_e32 v138, 16, v175
	v_add_u32_e32 v139, 17, v175
	v_add_u32_e32 v140, 18, v175
	v_add_u32_e32 v141, 19, v175
	v_cmp_gt_u32_e64 s[70:71], s44, v138
	v_cmp_gt_u32_e64 s[72:73], s44, v139
	v_cmp_gt_u32_e64 s[74:75], s44, v140
	v_cmp_gt_u32_e64 s[76:77], s44, v141
	v_cndmask_b32_e64 v152, 0, v152, s[70:71]
	v_cndmask_b32_e64 v153, 0, v153, s[72:73]
	v_cndmask_b32_e64 v154, 0, v154, s[74:75]
	v_cndmask_b32_e64 v155, 0, v155, s[76:77]
	v_add_f32_e32 v132, v132, v152
	v_add_f32_e32 v132, v132, v153
	v_add_f32_e32 v132, v132, v154
	v_add_f32_e32 v132, v132, v155
	v_cvt_pk_bf16_f32 v114, v152, v153
	v_cvt_pk_bf16_f32 v115, v154, v155
	v_min_f32_e32 v152, 0x42a00000, v236
	v_min_f32_e32 v153, 0x42a00000, v237
	v_min_f32_e32 v154, 0x42a00000, v238
	v_min_f32_e32 v155, 0x42a00000, v239
	v_mfma_f32_16x16x32_bf16 v[236:239], v[32:35], v[48:51], 0
	v_mfma_f32_16x16x32_bf16 v[236:239], v[36:39], v[52:55], v[236:239]
	v_add_u32_e32 v136, 0x80, v182
	v_med3_i32 v136, v136, 0, s38
	v_lshl_add_u32 v136, v136, 9, v179
	global_load_dwordx4 v[16:19], v136, s[24:25]
	global_load_dwordx4 v[20:23], v136, s[24:25] offset:64
	v_mul_f32_e32 v152, 0x3fb8aa3b, v152
	v_mul_f32_e32 v153, 0x3fb8aa3b, v153
	v_mul_f32_e32 v154, 0x3fb8aa3b, v154
	v_mul_f32_e32 v155, 0x3fb8aa3b, v155
	v_exp_f32_e32 v152, v152
	v_exp_f32_e32 v153, v153
	v_exp_f32_e32 v154, v154
	v_exp_f32_e32 v155, v155
	v_add_u32_e32 v138, 32, v175
	v_add_u32_e32 v139, 33, v175
	v_add_u32_e32 v140, 34, v175
	v_add_u32_e32 v141, 35, v175
	v_cmp_gt_u32_e64 s[70:71], s44, v138
	v_cmp_gt_u32_e64 s[72:73], s44, v139
	v_cmp_gt_u32_e64 s[74:75], s44, v140
	v_cmp_gt_u32_e64 s[76:77], s44, v141
	v_cndmask_b32_e64 v152, 0, v152, s[70:71]
	v_cndmask_b32_e64 v153, 0, v153, s[72:73]
	v_cndmask_b32_e64 v154, 0, v154, s[74:75]
	v_cndmask_b32_e64 v155, 0, v155, s[76:77]
	v_add_f32_e32 v132, v132, v152
	v_add_f32_e32 v132, v132, v153
	v_add_f32_e32 v132, v132, v154
	v_add_f32_e32 v132, v132, v155
	v_cvt_pk_bf16_f32 v116, v152, v153
	v_cvt_pk_bf16_f32 v117, v154, v155
	v_min_f32_e32 v152, 0x42a00000, v240
	v_min_f32_e32 v153, 0x42a00000, v241
	v_min_f32_e32 v154, 0x42a00000, v242
	v_min_f32_e32 v155, 0x42a00000, v243
	v_mfma_f32_16x16x32_bf16 v[240:243], v[40:43], v[48:51], 0
	v_mfma_f32_16x16x32_bf16 v[240:243], v[44:47], v[52:55], v[240:243]
	v_mul_f32_e32 v152, 0x3fb8aa3b, v152
	v_mul_f32_e32 v153, 0x3fb8aa3b, v153
	v_mul_f32_e32 v154, 0x3fb8aa3b, v154
	v_mul_f32_e32 v155, 0x3fb8aa3b, v155
	v_exp_f32_e32 v152, v152
	v_exp_f32_e32 v153, v153
	v_exp_f32_e32 v154, v154
	v_exp_f32_e32 v155, v155
	v_add_u32_e32 v138, 48, v175
	v_add_u32_e32 v139, 49, v175
	v_add_u32_e32 v140, 50, v175
	v_add_u32_e32 v141, 51, v175
	v_cmp_gt_u32_e64 s[70:71], s44, v138
	v_cmp_gt_u32_e64 s[72:73], s44, v139
	v_cmp_gt_u32_e64 s[74:75], s44, v140
	v_cmp_gt_u32_e64 s[76:77], s44, v141
	v_cndmask_b32_e64 v152, 0, v152, s[70:71]
	v_cndmask_b32_e64 v153, 0, v153, s[72:73]
	v_cndmask_b32_e64 v154, 0, v154, s[74:75]
	v_cndmask_b32_e64 v155, 0, v155, s[76:77]
	v_add_f32_e32 v132, v132, v152
	v_add_f32_e32 v132, v132, v153
	v_add_f32_e32 v132, v132, v154
	v_add_f32_e32 v132, v132, v155
	v_cvt_pk_bf16_f32 v118, v152, v153
	v_cvt_pk_bf16_f32 v119, v154, v155
	v_min_f32_e32 v152, 0x42a00000, v236
	v_min_f32_e32 v153, 0x42a00000, v237
	v_min_f32_e32 v154, 0x42a00000, v238
	v_min_f32_e32 v155, 0x42a00000, v239
	s_waitcnt vmcnt(4)
	v_mfma_f32_16x16x32_bf16 v[236:239], v[0:3], v[48:51], 0
	v_mfma_f32_16x16x32_bf16 v[236:239], v[4:7], v[52:55], v[236:239]
	v_mul_f32_e32 v152, 0x3fb8aa3b, v152
	v_mul_f32_e32 v153, 0x3fb8aa3b, v153
	v_mul_f32_e32 v154, 0x3fb8aa3b, v154
	v_mul_f32_e32 v155, 0x3fb8aa3b, v155
	v_exp_f32_e32 v152, v152
	v_exp_f32_e32 v153, v153
	v_exp_f32_e32 v154, v154
	v_exp_f32_e32 v155, v155
	v_add_u32_e32 v138, 64, v175
	v_add_u32_e32 v139, 0x41, v175
	v_add_u32_e32 v140, 0x42, v175
	v_add_u32_e32 v141, 0x43, v175
	v_cmp_gt_u32_e64 s[70:71], s44, v138
	v_cmp_gt_u32_e64 s[72:73], s44, v139
	v_cmp_gt_u32_e64 s[74:75], s44, v140
	v_cmp_gt_u32_e64 s[76:77], s44, v141
	v_cndmask_b32_e64 v152, 0, v152, s[70:71]
	v_cndmask_b32_e64 v153, 0, v153, s[72:73]
	v_cndmask_b32_e64 v154, 0, v154, s[74:75]
	v_cndmask_b32_e64 v155, 0, v155, s[76:77]
	v_add_f32_e32 v132, v132, v152
	v_add_f32_e32 v132, v132, v153
	v_add_f32_e32 v132, v132, v154
	v_add_f32_e32 v132, v132, v155
	v_cvt_pk_bf16_f32 v120, v152, v153
	v_cvt_pk_bf16_f32 v121, v154, v155
	v_min_f32_e32 v152, 0x42a00000, v240
	v_min_f32_e32 v153, 0x42a00000, v241
	v_min_f32_e32 v154, 0x42a00000, v242
	v_min_f32_e32 v155, 0x42a00000, v243
	s_waitcnt vmcnt(2)
	v_mfma_f32_16x16x32_bf16 v[240:243], v[8:11], v[48:51], 0
	v_mfma_f32_16x16x32_bf16 v[240:243], v[12:15], v[52:55], v[240:243]
	v_mul_f32_e32 v152, 0x3fb8aa3b, v152
	v_mul_f32_e32 v153, 0x3fb8aa3b, v153
	v_mul_f32_e32 v154, 0x3fb8aa3b, v154
	v_mul_f32_e32 v155, 0x3fb8aa3b, v155
	v_exp_f32_e32 v152, v152
	v_exp_f32_e32 v153, v153
	v_exp_f32_e32 v154, v154
	v_exp_f32_e32 v155, v155
	v_add_u32_e32 v138, 0x50, v175
	v_add_u32_e32 v139, 0x51, v175
	v_add_u32_e32 v140, 0x52, v175
	v_add_u32_e32 v141, 0x53, v175
	v_cmp_gt_u32_e64 s[70:71], s44, v138
	v_cmp_gt_u32_e64 s[72:73], s44, v139
	v_cmp_gt_u32_e64 s[74:75], s44, v140
	v_cmp_gt_u32_e64 s[76:77], s44, v141
	v_cndmask_b32_e64 v152, 0, v152, s[70:71]
	v_cndmask_b32_e64 v153, 0, v153, s[72:73]
	v_cndmask_b32_e64 v154, 0, v154, s[74:75]
	v_cndmask_b32_e64 v155, 0, v155, s[76:77]
	v_add_f32_e32 v132, v132, v152
	v_add_f32_e32 v132, v132, v153
	v_add_f32_e32 v132, v132, v154
	v_add_f32_e32 v132, v132, v155
	v_cvt_pk_bf16_f32 v122, v152, v153
	v_cvt_pk_bf16_f32 v123, v154, v155
	v_min_f32_e32 v152, 0x42a00000, v236
	v_min_f32_e32 v153, 0x42a00000, v237
	v_min_f32_e32 v154, 0x42a00000, v238
	v_min_f32_e32 v155, 0x42a00000, v239
	s_waitcnt vmcnt(0)
	v_mfma_f32_16x16x32_bf16 v[236:239], v[16:19], v[48:51], 0
	v_mfma_f32_16x16x32_bf16 v[236:239], v[20:23], v[52:55], v[236:239]
	v_mul_f32_e32 v152, 0x3fb8aa3b, v152
	v_mul_f32_e32 v153, 0x3fb8aa3b, v153
	v_mul_f32_e32 v154, 0x3fb8aa3b, v154
	v_mul_f32_e32 v155, 0x3fb8aa3b, v155
	v_exp_f32_e32 v152, v152
	v_exp_f32_e32 v153, v153
	v_exp_f32_e32 v154, v154
	v_exp_f32_e32 v155, v155
	v_add_u32_e32 v138, 0x60, v175
	v_add_u32_e32 v139, 0x61, v175
	v_add_u32_e32 v140, 0x62, v175
	v_add_u32_e32 v141, 0x63, v175
	v_cmp_gt_u32_e64 s[70:71], s44, v138
	v_cmp_gt_u32_e64 s[72:73], s44, v139
	v_cmp_gt_u32_e64 s[74:75], s44, v140
	v_cmp_gt_u32_e64 s[76:77], s44, v141
	v_cndmask_b32_e64 v152, 0, v152, s[70:71]
	v_cndmask_b32_e64 v153, 0, v153, s[72:73]
	v_cndmask_b32_e64 v154, 0, v154, s[74:75]
	v_cndmask_b32_e64 v155, 0, v155, s[76:77]
	v_add_f32_e32 v132, v132, v152
	v_add_f32_e32 v132, v132, v153
	v_add_f32_e32 v132, v132, v154
	v_add_f32_e32 v132, v132, v155
	v_cvt_pk_bf16_f32 v124, v152, v153
	v_cvt_pk_bf16_f32 v125, v154, v155
	v_min_f32_e32 v152, 0x42a00000, v240
	v_min_f32_e32 v153, 0x42a00000, v241
	v_min_f32_e32 v154, 0x42a00000, v242
	v_min_f32_e32 v155, 0x42a00000, v243
	v_mul_f32_e32 v152, 0x3fb8aa3b, v152
	v_mul_f32_e32 v153, 0x3fb8aa3b, v153
	v_mul_f32_e32 v154, 0x3fb8aa3b, v154
	v_mul_f32_e32 v155, 0x3fb8aa3b, v155
	v_exp_f32_e32 v152, v152
	v_exp_f32_e32 v153, v153
	v_exp_f32_e32 v154, v154
	v_exp_f32_e32 v155, v155
	v_add_u32_e32 v138, 0x70, v175
	v_add_u32_e32 v139, 0x71, v175
	v_add_u32_e32 v140, 0x72, v175
	v_add_u32_e32 v141, 0x73, v175
	v_cmp_gt_u32_e64 s[70:71], s44, v138
	v_cmp_gt_u32_e64 s[72:73], s44, v139
	v_cmp_gt_u32_e64 s[74:75], s44, v140
	v_cmp_gt_u32_e64 s[76:77], s44, v141
	v_cndmask_b32_e64 v152, 0, v152, s[70:71]
	v_cndmask_b32_e64 v153, 0, v153, s[72:73]
	v_cndmask_b32_e64 v154, 0, v154, s[74:75]
	v_cndmask_b32_e64 v155, 0, v155, s[76:77]
	v_add_f32_e32 v132, v132, v152
	v_add_f32_e32 v132, v132, v153
	v_add_f32_e32 v132, v132, v154
	v_add_f32_e32 v132, v132, v155
	v_cvt_pk_bf16_f32 v126, v152, v153
	v_cvt_pk_bf16_f32 v127, v154, v155
	v_min_f32_e32 v152, 0x42a00000, v236
	v_min_f32_e32 v153, 0x42a00000, v237
	v_min_f32_e32 v154, 0x42a00000, v238
	v_min_f32_e32 v155, 0x42a00000, v239
	v_mul_f32_e32 v152, 0x3fb8aa3b, v152
	v_mul_f32_e32 v153, 0x3fb8aa3b, v153
	v_mul_f32_e32 v154, 0x3fb8aa3b, v154
	v_mul_f32_e32 v155, 0x3fb8aa3b, v155
	v_exp_f32_e32 v152, v152
	v_exp_f32_e32 v153, v153
	v_exp_f32_e32 v154, v154
	v_exp_f32_e32 v155, v155
	v_add_u32_e32 v138, 0x80, v175
	v_add_u32_e32 v139, 0x81, v175
	v_add_u32_e32 v140, 0x82, v175
	v_add_u32_e32 v141, 0x83, v175
	v_cmp_gt_u32_e64 s[70:71], s44, v138
	v_cmp_gt_u32_e64 s[72:73], s44, v139
	v_cmp_gt_u32_e64 s[74:75], s44, v140
	v_cmp_gt_u32_e64 s[76:77], s44, v141
	v_cndmask_b32_e64 v152, 0, v152, s[62:63]
	v_cndmask_b32_e64 v153, 0, v153, s[64:65]
	v_cndmask_b32_e64 v154, 0, v154, s[66:67]
	v_cndmask_b32_e64 v155, 0, v155, s[68:69]
	v_cndmask_b32_e64 v152, 0, v152, s[70:71]
	v_cndmask_b32_e64 v153, 0, v153, s[72:73]
	v_cndmask_b32_e64 v154, 0, v154, s[74:75]
	v_cndmask_b32_e64 v155, 0, v155, s[76:77]
	v_add_f32_e32 v132, v132, v152
	v_add_f32_e32 v132, v132, v153
	v_add_f32_e32 v132, v132, v154
	v_add_f32_e32 v132, v132, v155
	v_cvt_pk_bf16_f32 v128, v152, v153
	v_cvt_pk_bf16_f32 v129, v154, v155
	v_add_u32_e32 v134, s42, v160
	v_lshlrev_b32_e32 v134, 4, v134
	v_add_u32_e32 v134, s43, v134
	v_subrev_u32_e32 v135, s15, v134
	v_lshrrev_b32_e32 v136, 4, v135
	v_add_u32_e32 v136, v136, v135
	v_mad_u32_u24 v176, v136, s79, v161
	v_lshl_add_u32 v177, v135, 2, s80
	s_sub_i32 s2, s42, 64
	v_add_u32_e32 v178, s2, v169
	v_and_b32_e32 v135, 3, v134
	v_lshlrev_b32_e32 v135, s13, v135
	v_lshrrev_b32_e32 v136, 2, v134
	v_add_u32_e32 v135, v135, v136
	v_lshl_add_u32 v135, v135, 7, v161
	v_subrev_u32_e32 v134, 0x400, v134
	v_and_b32_e32 v137, 3, v134
	v_lshlrev_b32_e32 v137, s13, v137
	v_bfe_u32 v135, v134, 2, 2
	v_add_u32_e32 v137, v137, v135
	v_lshl_add_u32 v183, v137, 7, v161
	v_ashrrev_i32_e32 v252, 4, v134
	v_med3_i32 v136, v252, 0, s14
	v_lshl_add_u32 v136, v136, 9, v183
	global_load_dwordx4 v[0:3], v136, s[20:21]
	global_load_dwordx4 v[4:7], v136, s[20:21] offset:64
	v_add_u32_e32 v135, 16, v252
	v_med3_i32 v135, v135, 0, s14
	v_lshl_add_u32 v135, v135, 9, v183
	global_load_dwordx4 v[8:11], v135, s[20:21]
	global_load_dwordx4 v[12:15], v135, s[20:21] offset:64
	v_add_u32_e32 v136, 32, v252
	v_med3_i32 v136, v136, 0, s14
	v_lshl_add_u32 v136, v136, 9, v183
	global_load_dwordx4 v[16:19], v136, s[20:21]
	global_load_dwordx4 v[20:23], v136, s[20:21] offset:64
	v_add_u32_e32 v135, 48, v252
	v_med3_i32 v135, v135, 0, s14
	v_lshl_add_u32 v135, v135, 9, v183
	global_load_dwordx4 v[24:27], v135, s[20:21]
	global_load_dwordx4 v[28:31], v135, s[20:21] offset:64
	v_add_u32_e32 v136, 64, v252
	v_med3_i32 v136, v136, 0, s14
	v_lshl_add_u32 v136, v136, 9, v183
	global_load_dwordx4 v[32:35], v136, s[20:21]
	global_load_dwordx4 v[36:39], v136, s[20:21] offset:64
	v_add_u32_e32 v135, 0x50, v252
	v_med3_i32 v135, v135, 0, s14
	v_lshl_add_u32 v135, v135, 9, v183
	global_load_dwordx4 v[40:43], v135, s[20:21]
	global_load_dwordx4 v[44:47], v135, s[20:21] offset:64
	ds_bpermute_b32 v142, v167, v132
	s_waitcnt lgkmcnt(0)
	v_add_f32_e32 v132, v132, v142
	ds_bpermute_b32 v142, v168, v132
	s_waitcnt lgkmcnt(0)
	v_add_f32_e32 v132, v132, v142
	s_waitcnt vmcnt(12)
	ds_write_b128 v165, v[64:67]
	ds_write_b128 v165, v[68:71] offset:1152
	ds_write_b128 v165, v[72:75] offset:2304
	ds_write_b128 v165, v[76:79] offset:3456
	s_waitcnt lgkmcnt(0)
	ds_read_b64_tr_b16 v[236:237], v166
	ds_read_b64_tr_b16 v[238:239], v166 offset:2304
	ds_read_b64_tr_b16 v[240:241], v166 offset:32
	ds_read_b64_tr_b16 v[242:243], v166 offset:2336
	ds_read_b64_tr_b16 v[244:245], v166 offset:64
	ds_read_b64_tr_b16 v[246:247], v166 offset:2368
	ds_read_b64_tr_b16 v[248:249], v166 offset:96
	ds_read_b64_tr_b16 v[250:251], v166 offset:2400
	s_waitcnt lgkmcnt(0)
	s_add_i32 s2, s40, 32
	v_add_u32_e32 v138, s2, v164
	v_lshlrev_b32_e32 v138, 4, v138
	v_add_u32_e32 v138, s41, v138
	v_and_b32_e32 v139, 3, v138
	v_lshlrev_b32_e32 v139, s39, v139
	v_bfe_u32 v140, v138, 2, 2
	v_add_u32_e32 v139, v139, v140
	v_lshl_add_u32 v139, v139, 7, v162
	v_ashrrev_i32_e32 v138, 4, v138
	v_med3_i32 v138, v138, 0, s38
	v_lshl_add_u32 v138, v138, 9, v139
	global_load_dwordx4 v[64:67], v138, s[26:27]
	s_add_i32 s2, s40, 40
	v_add_u32_e32 v138, s2, v164
	v_lshlrev_b32_e32 v138, 4, v138
	v_add_u32_e32 v138, s41, v138
	v_and_b32_e32 v139, 3, v138
	v_lshlrev_b32_e32 v139, s39, v139
	v_bfe_u32 v140, v138, 2, 2
	v_add_u32_e32 v139, v139, v140
	v_lshl_add_u32 v139, v139, 7, v162
	v_ashrrev_i32_e32 v138, 4, v138
	v_med3_i32 v138, v138, 0, s38
	v_lshl_add_u32 v138, v138, 9, v139
	global_load_dwordx4 v[68:71], v138, s[26:27]
	s_add_i32 s2, s40, 48
	v_add_u32_e32 v138, s2, v164
	v_lshlrev_b32_e32 v138, 4, v138
	v_add_u32_e32 v138, s41, v138
	v_and_b32_e32 v139, 3, v138
	v_lshlrev_b32_e32 v139, s39, v139
	v_bfe_u32 v140, v138, 2, 2
	v_add_u32_e32 v139, v139, v140
	v_lshl_add_u32 v139, v139, 7, v162
	v_ashrrev_i32_e32 v138, 4, v138
	v_med3_i32 v138, v138, 0, s38
	v_lshl_add_u32 v138, v138, 9, v139
	global_load_dwordx4 v[72:75], v138, s[26:27]
	s_add_i32 s2, s40, 56
	v_add_u32_e32 v138, s2, v164
	v_lshlrev_b32_e32 v138, 4, v138
	v_add_u32_e32 v138, s41, v138
	v_and_b32_e32 v139, 3, v138
	v_lshlrev_b32_e32 v139, s39, v139
	v_bfe_u32 v140, v138, 2, 2
	v_add_u32_e32 v139, v139, v140
	v_lshl_add_u32 v139, v139, 7, v162
	v_ashrrev_i32_e32 v138, 4, v138
	v_med3_i32 v138, v138, 0, s38
	v_lshl_add_u32 v138, v138, 9, v139
	global_load_dwordx4 v[76:79], v138, s[26:27]
	ds_write_b128 v165, v[80:83]
	ds_write_b128 v165, v[84:87] offset:1152
	ds_write_b128 v165, v[88:91] offset:2304
	ds_write_b128 v165, v[92:95] offset:3456
	v_mfma_f32_16x16x32_bf16 v[204:207], v[236:239], v[112:115], 0
	v_mfma_f32_16x16x32_bf16 v[208:211], v[240:243], v[112:115], 0
	v_mfma_f32_16x16x32_bf16 v[212:215], v[244:247], v[112:115], 0
	v_mfma_f32_16x16x32_bf16 v[216:219], v[248:251], v[112:115], 0
	s_waitcnt lgkmcnt(0)
	ds_read_b64_tr_b16 v[236:237], v166
	ds_read_b64_tr_b16 v[238:239], v166 offset:2304
	ds_read_b64_tr_b16 v[240:241], v166 offset:32
	ds_read_b64_tr_b16 v[242:243], v166 offset:2336
	ds_read_b64_tr_b16 v[244:245], v166 offset:64
	ds_read_b64_tr_b16 v[246:247], v166 offset:2368
	ds_read_b64_tr_b16 v[248:249], v166 offset:96
	ds_read_b64_tr_b16 v[250:251], v166 offset:2400
	s_waitcnt lgkmcnt(0)
	s_add_i32 s2, s40, 64
	v_add_u32_e32 v138, s2, v164
	v_lshlrev_b32_e32 v138, 4, v138
	v_add_u32_e32 v138, s41, v138
	v_and_b32_e32 v139, 3, v138
	v_lshlrev_b32_e32 v139, s39, v139
	v_bfe_u32 v140, v138, 2, 2
	v_add_u32_e32 v139, v139, v140
	v_lshl_add_u32 v139, v139, 7, v162
	v_ashrrev_i32_e32 v138, 4, v138
	v_med3_i32 v138, v138, 0, s38
	v_lshl_add_u32 v138, v138, 9, v139
	global_load_dwordx4 v[80:83], v138, s[26:27]
	s_add_i32 s2, s40, 72
	v_add_u32_e32 v138, s2, v164
	v_lshlrev_b32_e32 v138, 4, v138
	v_add_u32_e32 v138, s41, v138
	v_and_b32_e32 v139, 3, v138
	v_lshlrev_b32_e32 v139, s39, v139
	v_bfe_u32 v140, v138, 2, 2
	v_add_u32_e32 v139, v139, v140
	v_lshl_add_u32 v139, v139, 7, v162
	v_ashrrev_i32_e32 v138, 4, v138
	v_med3_i32 v138, v138, 0, s38
	v_lshl_add_u32 v138, v138, 9, v139
	global_load_dwordx4 v[84:87], v138, s[26:27]
	ds_write_b128 v165, v[96:99]
	ds_write_b128 v165, v[100:103] offset:1152
	ds_write_b128 v165, v[104:107] offset:2304
	ds_write_b128 v165, v[108:111] offset:3456
	v_mfma_f32_16x16x32_bf16 v[204:207], v[236:239], v[116:119], v[204:207]
	v_mfma_f32_16x16x32_bf16 v[208:211], v[240:243], v[116:119], v[208:211]
	v_mfma_f32_16x16x32_bf16 v[212:215], v[244:247], v[116:119], v[212:215]
	v_mfma_f32_16x16x32_bf16 v[216:219], v[248:251], v[116:119], v[216:219]
	s_waitcnt lgkmcnt(0)
	ds_read_b64_tr_b16 v[236:237], v166
	ds_read_b64_tr_b16 v[238:239], v166 offset:2304
	ds_read_b64_tr_b16 v[240:241], v166 offset:32
	ds_read_b64_tr_b16 v[242:243], v166 offset:2336
	ds_read_b64_tr_b16 v[244:245], v166 offset:64
	ds_read_b64_tr_b16 v[246:247], v166 offset:2368
	ds_read_b64_tr_b16 v[248:249], v166 offset:96
	ds_read_b64_tr_b16 v[250:251], v166 offset:2400
	s_waitcnt lgkmcnt(0)
	s_waitcnt vmcnt(2)
	ds_write_b128 v165, v[64:67]
	ds_write_b128 v165, v[68:71] offset:1152
	ds_write_b128 v165, v[72:75] offset:2304
	ds_write_b128 v165, v[76:79] offset:3456
	v_mfma_f32_16x16x32_bf16 v[204:207], v[236:239], v[120:123], v[204:207]
	v_mfma_f32_16x16x32_bf16 v[208:211], v[240:243], v[120:123], v[208:211]
	v_mfma_f32_16x16x32_bf16 v[212:215], v[244:247], v[120:123], v[212:215]
	v_mfma_f32_16x16x32_bf16 v[216:219], v[248:251], v[120:123], v[216:219]
	s_waitcnt lgkmcnt(0)
	ds_read_b64_tr_b16 v[236:237], v166
	ds_read_b64_tr_b16 v[238:239], v166 offset:2304
	ds_read_b64_tr_b16 v[240:241], v166 offset:32
	ds_read_b64_tr_b16 v[242:243], v166 offset:2336
	ds_read_b64_tr_b16 v[244:245], v166 offset:64
	ds_read_b64_tr_b16 v[246:247], v166 offset:2368
	ds_read_b64_tr_b16 v[248:249], v166 offset:96
	ds_read_b64_tr_b16 v[250:251], v166 offset:2400
	s_waitcnt lgkmcnt(0)
	s_waitcnt vmcnt(0)
	ds_write_b128 v165, v[80:83]
	ds_write_b128 v165, v[84:87] offset:1152
	v_mfma_f32_16x16x32_bf16 v[204:207], v[236:239], v[124:127], v[204:207]
	v_mfma_f32_16x16x32_bf16 v[208:211], v[240:243], v[124:127], v[208:211]
	v_mfma_f32_16x16x32_bf16 v[212:215], v[244:247], v[124:127], v[212:215]
	v_mfma_f32_16x16x32_bf16 v[216:219], v[248:251], v[124:127], v[216:219]
	s_waitcnt lgkmcnt(0)
	ds_read_b64_tr_b16 v[236:237], v166
	ds_read_b64_tr_b16 v[238:239], v166 offset:2304
	ds_read_b64_tr_b16 v[240:241], v166 offset:32
	ds_read_b64_tr_b16 v[242:243], v166 offset:2336
	ds_read_b64_tr_b16 v[244:245], v166 offset:64
	ds_read_b64_tr_b16 v[246:247], v166 offset:2368
	ds_read_b64_tr_b16 v[248:249], v166 offset:96
	ds_read_b64_tr_b16 v[250:251], v166 offset:2400
	s_waitcnt lgkmcnt(0)
	v_mfma_f32_16x16x32_bf16 v[204:207], v[236:239], v[128:131], v[204:207]
	v_mfma_f32_16x16x32_bf16 v[208:211], v[240:243], v[128:131], v[208:211]
	v_mfma_f32_16x16x32_bf16 v[212:215], v[244:247], v[128:131], v[212:215]
	v_mfma_f32_16x16x32_bf16 v[216:219], v[248:251], v[128:131], v[216:219]
	s_add_i32 s2, s42, -64
	v_add_u32_e32 v138, s2, v164
	v_lshlrev_b32_e32 v138, 4, v138
	v_add_u32_e32 v138, s43, v138
	v_and_b32_e32 v139, 3, v138
	v_lshlrev_b32_e32 v139, s13, v139
	v_bfe_u32 v140, v138, 2, 2
	v_add_u32_e32 v139, v139, v140
	v_lshl_add_u32 v139, v139, 7, v162
	v_ashrrev_i32_e32 v138, 4, v138
	v_med3_i32 v138, v138, 0, s14
	v_lshl_add_u32 v138, v138, 9, v139
	global_load_dwordx4 v[64:67], v138, s[22:23]
	s_add_i32 s2, s42, -56
	v_add_u32_e32 v138, s2, v164
	v_lshlrev_b32_e32 v138, 4, v138
	v_add_u32_e32 v138, s43, v138
	v_and_b32_e32 v139, 3, v138
	v_lshlrev_b32_e32 v139, s13, v139
	v_bfe_u32 v140, v138, 2, 2
	v_add_u32_e32 v139, v139, v140
	v_lshl_add_u32 v139, v139, 7, v162
	v_ashrrev_i32_e32 v138, 4, v138
	v_med3_i32 v138, v138, 0, s14
	v_lshl_add_u32 v138, v138, 9, v139
	global_load_dwordx4 v[68:71], v138, s[22:23]
	s_add_i32 s2, s42, -48
	v_add_u32_e32 v138, s2, v164
	v_lshlrev_b32_e32 v138, 4, v138
	v_add_u32_e32 v138, s43, v138
	v_and_b32_e32 v139, 3, v138
	v_lshlrev_b32_e32 v139, s13, v139
	v_bfe_u32 v140, v138, 2, 2
	v_add_u32_e32 v139, v139, v140
	v_lshl_add_u32 v139, v139, 7, v162
	v_ashrrev_i32_e32 v138, 4, v138
	v_med3_i32 v138, v138, 0, s14
	v_lshl_add_u32 v138, v138, 9, v139
	global_load_dwordx4 v[72:75], v138, s[22:23]
	s_add_i32 s2, s42, -40
	v_add_u32_e32 v138, s2, v164
	v_lshlrev_b32_e32 v138, 4, v138
	v_add_u32_e32 v138, s43, v138
	v_and_b32_e32 v139, 3, v138
	v_lshlrev_b32_e32 v139, s13, v139
	v_bfe_u32 v140, v138, 2, 2
	v_add_u32_e32 v139, v139, v140
	v_lshl_add_u32 v139, v139, 7, v162
	v_ashrrev_i32_e32 v138, 4, v138
	v_med3_i32 v138, v138, 0, s14
	v_lshl_add_u32 v138, v138, 9, v139
	global_load_dwordx4 v[76:79], v138, s[22:23]
	s_add_i32 s2, s42, -32
	v_add_u32_e32 v138, s2, v164
	v_lshlrev_b32_e32 v138, 4, v138
	v_add_u32_e32 v138, s43, v138
	v_and_b32_e32 v139, 3, v138
	v_lshlrev_b32_e32 v139, s13, v139
	v_bfe_u32 v140, v138, 2, 2
	v_add_u32_e32 v139, v139, v140
	v_lshl_add_u32 v139, v139, 7, v162
	v_ashrrev_i32_e32 v138, 4, v138
	v_med3_i32 v138, v138, 0, s14
	v_lshl_add_u32 v138, v138, 9, v139
	global_load_dwordx4 v[80:83], v138, s[22:23]
	s_add_i32 s2, s42, -24
	v_add_u32_e32 v138, s2, v164
	v_lshlrev_b32_e32 v138, 4, v138
	v_add_u32_e32 v138, s43, v138
	v_and_b32_e32 v139, 3, v138
	v_lshlrev_b32_e32 v139, s13, v139
	v_bfe_u32 v140, v138, 2, 2
	v_add_u32_e32 v139, v139, v140
	v_lshl_add_u32 v139, v139, 7, v162
	v_ashrrev_i32_e32 v138, 4, v138
	v_med3_i32 v138, v138, 0, s14
	v_lshl_add_u32 v138, v138, 9, v139
	global_load_dwordx4 v[84:87], v138, s[22:23]
	s_add_i32 s2, s42, -16
	v_add_u32_e32 v138, s2, v164
	v_lshlrev_b32_e32 v138, 4, v138
	v_add_u32_e32 v138, s43, v138
	v_and_b32_e32 v139, 3, v138
	v_lshlrev_b32_e32 v139, s13, v139
	v_bfe_u32 v140, v138, 2, 2
	v_add_u32_e32 v139, v139, v140
	v_lshl_add_u32 v139, v139, 7, v162
	v_ashrrev_i32_e32 v138, 4, v138
	v_med3_i32 v138, v138, 0, s14
	v_lshl_add_u32 v138, v138, 9, v139
	global_load_dwordx4 v[88:91], v138, s[22:23]
	s_add_i32 s2, s42, -8
	v_add_u32_e32 v138, s2, v164
	v_lshlrev_b32_e32 v138, 4, v138
	v_add_u32_e32 v138, s43, v138
	v_and_b32_e32 v139, 3, v138
	v_lshlrev_b32_e32 v139, s13, v139
	v_bfe_u32 v140, v138, 2, 2
	v_add_u32_e32 v139, v139, v140
	v_lshl_add_u32 v139, v139, 7, v162
	v_ashrrev_i32_e32 v138, 4, v138
	v_med3_i32 v138, v138, 0, s14
	v_lshl_add_u32 v138, v138, 9, v139
	global_load_dwordx4 v[92:95], v138, s[22:23]
	s_add_i32 s2, s42, 0
	v_add_u32_e32 v138, s2, v164
	v_lshlrev_b32_e32 v138, 4, v138
	v_add_u32_e32 v138, s43, v138
	v_and_b32_e32 v139, 3, v138
	v_lshlrev_b32_e32 v139, s13, v139
	v_bfe_u32 v140, v138, 2, 2
	v_add_u32_e32 v139, v139, v140
	v_lshl_add_u32 v139, v139, 7, v162
	v_ashrrev_i32_e32 v138, 4, v138
	v_med3_i32 v138, v138, 0, s14
	v_lshl_add_u32 v138, v138, 9, v139
	global_load_dwordx4 v[96:99], v138, s[22:23]
	s_add_i32 s2, s42, 8
	v_add_u32_e32 v138, s2, v164
	v_lshlrev_b32_e32 v138, 4, v138
	v_add_u32_e32 v138, s43, v138
	v_and_b32_e32 v139, 3, v138
	v_lshlrev_b32_e32 v139, s13, v139
	v_bfe_u32 v140, v138, 2, 2
	v_add_u32_e32 v139, v139, v140
	v_lshl_add_u32 v139, v139, 7, v162
	v_ashrrev_i32_e32 v138, 4, v138
	v_med3_i32 v138, v138, 0, s14
	v_lshl_add_u32 v138, v138, 9, v139
	global_load_dwordx4 v[100:103], v138, s[22:23]
	s_add_i32 s2, s42, 16
	v_add_u32_e32 v138, s2, v164
	v_lshlrev_b32_e32 v138, 4, v138
	v_add_u32_e32 v138, s43, v138
	v_and_b32_e32 v139, 3, v138
	v_lshlrev_b32_e32 v139, s13, v139
	v_bfe_u32 v140, v138, 2, 2
	v_add_u32_e32 v139, v139, v140
	v_lshl_add_u32 v139, v139, 7, v162
	v_ashrrev_i32_e32 v138, 4, v138
	v_med3_i32 v138, v138, 0, s14
	v_lshl_add_u32 v138, v138, 9, v139
	global_load_dwordx4 v[104:107], v138, s[22:23]
	s_add_i32 s2, s42, 24
	v_add_u32_e32 v138, s2, v164
	v_lshlrev_b32_e32 v138, 4, v138
	v_add_u32_e32 v138, s43, v138
	v_and_b32_e32 v139, 3, v138
	v_lshlrev_b32_e32 v139, s13, v139
	v_bfe_u32 v140, v138, 2, 2
	v_add_u32_e32 v139, v139, v140
	v_lshl_add_u32 v139, v139, 7, v162
	v_ashrrev_i32_e32 v138, 4, v138
	v_med3_i32 v138, v138, 0, s14
	v_lshl_add_u32 v138, v138, 9, v139
	global_load_dwordx4 v[108:111], v138, s[22:23]
	ds_read_b128 v[236:239], v173 offset:0
	ds_read_b128 v[240:243], v173 offset:64
	ds_read_b128 v[244:247], v173 offset:128
	ds_read_b128 v[248:251], v173 offset:192
	ds_read_b32 v142, v174 offset:0
	s_waitcnt lgkmcnt(0)
	v_add_f32_e32 v204, v236, v204
	v_add_f32_e32 v205, v237, v205
	v_add_f32_e32 v206, v238, v206
	v_add_f32_e32 v207, v239, v207
	v_add_f32_e32 v208, v240, v208
	v_add_f32_e32 v209, v241, v209
	v_add_f32_e32 v210, v242, v210
	v_add_f32_e32 v211, v243, v211
	v_add_f32_e32 v212, v244, v212
	v_add_f32_e32 v213, v245, v213
	v_add_f32_e32 v214, v246, v214
	v_add_f32_e32 v215, v247, v215
	v_add_f32_e32 v216, v248, v216
	v_add_f32_e32 v217, v249, v217
	v_add_f32_e32 v218, v250, v218
	v_add_f32_e32 v219, v251, v219
	v_add_f32_e32 v132, v142, v132
	ds_write_b128 v173, v[204:207] offset:0
	ds_write_b128 v173, v[208:211] offset:64
	ds_write_b128 v173, v[212:215] offset:128
	ds_write_b128 v173, v[216:219] offset:192
	ds_write_b32 v174, v132 offset:0
	s_mov_b32 s40, s42
	s_mov_b32 s41, s43
	v_mov_b32_e32 v173, v176
	v_mov_b32_e32 v174, v177
	v_mov_b32_e32 v175, v178
	v_mov_b32_e32 v179, v183
	v_mov_b32_e32 v182, v252
	s_lshr_b32 s44, s33, 4
	s_add_i32 s45, s10, s8
	s_cmp_lt_u32 s45, 0x800
	s_cbranch_scc1 .Latt_newunit
	s_mov_b32 s37, 1
	s_branch .Latt_ud_done

.Latt_ud_done:
	s_lshl_b32 s2, s0, 5
	s_add_i32 s42, s15, s2
	s_mov_b32 s43, 0
	v_subrev_u32_e32 v143, s80, v174
	v_lshl_add_u32 v143, v143, 5, v161
	v_add_u32_e32 v143, 0x1b500, v143
	ds_read_b128 v[48:51], v143
	ds_read_b128 v[52:55], v143 offset:64
	s_waitcnt vmcnt(12)
	s_waitcnt lgkmcnt(0)
	v_mov_b32_e32 v132, 0
	v_mfma_f32_16x16x32_bf16 v[236:239], v[0:3], v[48:51], 0
	v_mfma_f32_16x16x32_bf16 v[236:239], v[4:7], v[52:55], v[236:239]
	v_mfma_f32_16x16x32_bf16 v[240:243], v[8:11], v[48:51], 0
	v_mfma_f32_16x16x32_bf16 v[240:243], v[12:15], v[52:55], v[240:243]
	s_nop 7
	v_min_f32_e32 v152, 0x42a00000, v236
	v_min_f32_e32 v153, 0x42a00000, v237
	v_min_f32_e32 v154, 0x42a00000, v238
	v_min_f32_e32 v155, 0x42a00000, v239
	v_mfma_f32_16x16x32_bf16 v[236:239], v[16:19], v[48:51], 0
	v_mfma_f32_16x16x32_bf16 v[236:239], v[20:23], v[52:55], v[236:239]
	v_add_u32_e32 v136, 0x60, v182
	v_med3_i32 v136, v136, 0, s38
	v_lshl_add_u32 v136, v136, 9, v179
	global_load_dwordx4 v[0:3], v136, s[24:25]
	global_load_dwordx4 v[4:7], v136, s[24:25] offset:64
	v_mul_f32_e32 v152, 0x3fb8aa3b, v152
	v_mul_f32_e32 v153, 0x3fb8aa3b, v153
	v_mul_f32_e32 v154, 0x3fb8aa3b, v154
	v_mul_f32_e32 v155, 0x3fb8aa3b, v155
	v_exp_f32_e32 v152, v152
	v_exp_f32_e32 v153, v153
	v_exp_f32_e32 v154, v154
	v_exp_f32_e32 v155, v155
	v_add_u32_e32 v138, 0, v175
	v_add_u32_e32 v139, 1, v175
	v_add_u32_e32 v140, 2, v175
	v_add_u32_e32 v141, 3, v175
	v_cmp_gt_u32_e64 s[70:71], s44, v138
	v_cmp_gt_u32_e64 s[72:73], s44, v139
	v_cmp_gt_u32_e64 s[74:75], s44, v140
	v_cmp_gt_u32_e64 s[76:77], s44, v141
	v_cndmask_b32_e64 v152, 0, v152, s[54:55]
	v_cndmask_b32_e64 v153, 0, v153, s[56:57]
	v_cndmask_b32_e64 v154, 0, v154, s[58:59]
	v_cndmask_b32_e64 v155, 0, v155, s[60:61]
	v_cndmask_b32_e64 v152, 0, v152, s[70:71]
	v_cndmask_b32_e64 v153, 0, v153, s[72:73]
	v_cndmask_b32_e64 v154, 0, v154, s[74:75]
	v_cndmask_b32_e64 v155, 0, v155, s[76:77]
	v_add_f32_e32 v132, v132, v152
	v_add_f32_e32 v132, v132, v153
	v_add_f32_e32 v132, v132, v154
	v_add_f32_e32 v132, v132, v155
	v_cvt_pk_bf16_f32 v112, v152, v153
	v_cvt_pk_bf16_f32 v113, v154, v155
	v_min_f32_e32 v152, 0x42a00000, v240
	v_min_f32_e32 v153, 0x42a00000, v241
	v_min_f32_e32 v154, 0x42a00000, v242
	v_min_f32_e32 v155, 0x42a00000, v243
	v_mfma_f32_16x16x32_bf16 v[240:243], v[24:27], v[48:51], 0
	v_mfma_f32_16x16x32_bf16 v[240:243], v[28:31], v[52:55], v[240:243]
	v_add_u32_e32 v135, 0x70, v182
	v_med3_i32 v135, v135, 0, s38
	v_lshl_add_u32 v135, v135, 9, v179
	global_load_dwordx4 v[8:11], v135, s[24:25]
	global_load_dwordx4 v[12:15], v135, s[24:25] offset:64
	v_mul_f32_e32 v152, 0x3fb8aa3b, v152
	v_mul_f32_e32 v153, 0x3fb8aa3b, v153
	v_mul_f32_e32 v154, 0x3fb8aa3b, v154
	v_mul_f32_e32 v155, 0x3fb8aa3b, v155
	v_exp_f32_e32 v152, v152
	v_exp_f32_e32 v153, v153
	v_exp_f32_e32 v154, v154
	v_exp_f32_e32 v155, v155
	v_add_u32_e32 v138, 16, v175
	v_add_u32_e32 v139, 17, v175
	v_add_u32_e32 v140, 18, v175
	v_add_u32_e32 v141, 19, v175
	v_cmp_gt_u32_e64 s[70:71], s44, v138
	v_cmp_gt_u32_e64 s[72:73], s44, v139
	v_cmp_gt_u32_e64 s[74:75], s44, v140
	v_cmp_gt_u32_e64 s[76:77], s44, v141
	v_cndmask_b32_e64 v152, 0, v152, s[70:71]
	v_cndmask_b32_e64 v153, 0, v153, s[72:73]
	v_cndmask_b32_e64 v154, 0, v154, s[74:75]
	v_cndmask_b32_e64 v155, 0, v155, s[76:77]
	v_add_f32_e32 v132, v132, v152
	v_add_f32_e32 v132, v132, v153
	v_add_f32_e32 v132, v132, v154
	v_add_f32_e32 v132, v132, v155
	v_cvt_pk_bf16_f32 v114, v152, v153
	v_cvt_pk_bf16_f32 v115, v154, v155
	v_min_f32_e32 v152, 0x42a00000, v236
	v_min_f32_e32 v153, 0x42a00000, v237
	v_min_f32_e32 v154, 0x42a00000, v238
	v_min_f32_e32 v155, 0x42a00000, v239
	v_mfma_f32_16x16x32_bf16 v[236:239], v[32:35], v[48:51], 0
	v_mfma_f32_16x16x32_bf16 v[236:239], v[36:39], v[52:55], v[236:239]
	v_add_u32_e32 v136, 0x80, v182
	v_med3_i32 v136, v136, 0, s38
	v_lshl_add_u32 v136, v136, 9, v179
	global_load_dwordx4 v[16:19], v136, s[24:25]
	global_load_dwordx4 v[20:23], v136, s[24:25] offset:64
	v_mul_f32_e32 v152, 0x3fb8aa3b, v152
	v_mul_f32_e32 v153, 0x3fb8aa3b, v153
	v_mul_f32_e32 v154, 0x3fb8aa3b, v154
	v_mul_f32_e32 v155, 0x3fb8aa3b, v155
	v_exp_f32_e32 v152, v152
	v_exp_f32_e32 v153, v153
	v_exp_f32_e32 v154, v154
	v_exp_f32_e32 v155, v155
	v_add_u32_e32 v138, 32, v175
	v_add_u32_e32 v139, 33, v175
	v_add_u32_e32 v140, 34, v175
	v_add_u32_e32 v141, 35, v175
	v_cmp_gt_u32_e64 s[70:71], s44, v138
	v_cmp_gt_u32_e64 s[72:73], s44, v139
	v_cmp_gt_u32_e64 s[74:75], s44, v140
	v_cmp_gt_u32_e64 s[76:77], s44, v141
	v_cndmask_b32_e64 v152, 0, v152, s[70:71]
	v_cndmask_b32_e64 v153, 0, v153, s[72:73]
	v_cndmask_b32_e64 v154, 0, v154, s[74:75]
	v_cndmask_b32_e64 v155, 0, v155, s[76:77]
	v_add_f32_e32 v132, v132, v152
	v_add_f32_e32 v132, v132, v153
	v_add_f32_e32 v132, v132, v154
	v_add_f32_e32 v132, v132, v155
	v_cvt_pk_bf16_f32 v116, v152, v153
	v_cvt_pk_bf16_f32 v117, v154, v155
	v_min_f32_e32 v152, 0x42a00000, v240
	v_min_f32_e32 v153, 0x42a00000, v241
	v_min_f32_e32 v154, 0x42a00000, v242
	v_min_f32_e32 v155, 0x42a00000, v243
	v_mfma_f32_16x16x32_bf16 v[240:243], v[40:43], v[48:51], 0
	v_mfma_f32_16x16x32_bf16 v[240:243], v[44:47], v[52:55], v[240:243]
	v_mul_f32_e32 v152, 0x3fb8aa3b, v152
	v_mul_f32_e32 v153, 0x3fb8aa3b, v153
	v_mul_f32_e32 v154, 0x3fb8aa3b, v154
	v_mul_f32_e32 v155, 0x3fb8aa3b, v155
	v_exp_f32_e32 v152, v152
	v_exp_f32_e32 v153, v153
	v_exp_f32_e32 v154, v154
	v_exp_f32_e32 v155, v155
	v_add_u32_e32 v138, 48, v175
	v_add_u32_e32 v139, 49, v175
	v_add_u32_e32 v140, 50, v175
	v_add_u32_e32 v141, 51, v175
	v_cmp_gt_u32_e64 s[70:71], s44, v138
	v_cmp_gt_u32_e64 s[72:73], s44, v139
	v_cmp_gt_u32_e64 s[74:75], s44, v140
	v_cmp_gt_u32_e64 s[76:77], s44, v141
	v_cndmask_b32_e64 v152, 0, v152, s[70:71]
	v_cndmask_b32_e64 v153, 0, v153, s[72:73]
	v_cndmask_b32_e64 v154, 0, v154, s[74:75]
	v_cndmask_b32_e64 v155, 0, v155, s[76:77]
	v_add_f32_e32 v132, v132, v152
	v_add_f32_e32 v132, v132, v153
	v_add_f32_e32 v132, v132, v154
	v_add_f32_e32 v132, v132, v155
	v_cvt_pk_bf16_f32 v118, v152, v153
	v_cvt_pk_bf16_f32 v119, v154, v155
	v_min_f32_e32 v152, 0x42a00000, v236
	v_min_f32_e32 v153, 0x42a00000, v237
	v_min_f32_e32 v154, 0x42a00000, v238
	v_min_f32_e32 v155, 0x42a00000, v239
	s_waitcnt vmcnt(4)
	v_mfma_f32_16x16x32_bf16 v[236:239], v[0:3], v[48:51], 0
	v_mfma_f32_16x16x32_bf16 v[236:239], v[4:7], v[52:55], v[236:239]
	v_mul_f32_e32 v152, 0x3fb8aa3b, v152
	v_mul_f32_e32 v153, 0x3fb8aa3b, v153
	v_mul_f32_e32 v154, 0x3fb8aa3b, v154
	v_mul_f32_e32 v155, 0x3fb8aa3b, v155
	v_exp_f32_e32 v152, v152
	v_exp_f32_e32 v153, v153
	v_exp_f32_e32 v154, v154
	v_exp_f32_e32 v155, v155
	v_add_u32_e32 v138, 64, v175
	v_add_u32_e32 v139, 0x41, v175
	v_add_u32_e32 v140, 0x42, v175
	v_add_u32_e32 v141, 0x43, v175
	v_cmp_gt_u32_e64 s[70:71], s44, v138
	v_cmp_gt_u32_e64 s[72:73], s44, v139
	v_cmp_gt_u32_e64 s[74:75], s44, v140
	v_cmp_gt_u32_e64 s[76:77], s44, v141
	v_cndmask_b32_e64 v152, 0, v152, s[70:71]
	v_cndmask_b32_e64 v153, 0, v153, s[72:73]
	v_cndmask_b32_e64 v154, 0, v154, s[74:75]
	v_cndmask_b32_e64 v155, 0, v155, s[76:77]
	v_add_f32_e32 v132, v132, v152
	v_add_f32_e32 v132, v132, v153
	v_add_f32_e32 v132, v132, v154
	v_add_f32_e32 v132, v132, v155
	v_cvt_pk_bf16_f32 v120, v152, v153
	v_cvt_pk_bf16_f32 v121, v154, v155
	v_min_f32_e32 v152, 0x42a00000, v240
	v_min_f32_e32 v153, 0x42a00000, v241
	v_min_f32_e32 v154, 0x42a00000, v242
	v_min_f32_e32 v155, 0x42a00000, v243
	s_waitcnt vmcnt(2)
	v_mfma_f32_16x16x32_bf16 v[240:243], v[8:11], v[48:51], 0
	v_mfma_f32_16x16x32_bf16 v[240:243], v[12:15], v[52:55], v[240:243]
	v_mul_f32_e32 v152, 0x3fb8aa3b, v152
	v_mul_f32_e32 v153, 0x3fb8aa3b, v153
	v_mul_f32_e32 v154, 0x3fb8aa3b, v154
	v_mul_f32_e32 v155, 0x3fb8aa3b, v155
	v_exp_f32_e32 v152, v152
	v_exp_f32_e32 v153, v153
	v_exp_f32_e32 v154, v154
	v_exp_f32_e32 v155, v155
	v_add_u32_e32 v138, 0x50, v175
	v_add_u32_e32 v139, 0x51, v175
	v_add_u32_e32 v140, 0x52, v175
	v_add_u32_e32 v141, 0x53, v175
	v_cmp_gt_u32_e64 s[70:71], s44, v138
	v_cmp_gt_u32_e64 s[72:73], s44, v139
	v_cmp_gt_u32_e64 s[74:75], s44, v140
	v_cmp_gt_u32_e64 s[76:77], s44, v141
	v_cndmask_b32_e64 v152, 0, v152, s[70:71]
	v_cndmask_b32_e64 v153, 0, v153, s[72:73]
	v_cndmask_b32_e64 v154, 0, v154, s[74:75]
	v_cndmask_b32_e64 v155, 0, v155, s[76:77]
	v_add_f32_e32 v132, v132, v152
	v_add_f32_e32 v132, v132, v153
	v_add_f32_e32 v132, v132, v154
	v_add_f32_e32 v132, v132, v155
	v_cvt_pk_bf16_f32 v122, v152, v153
	v_cvt_pk_bf16_f32 v123, v154, v155
	v_min_f32_e32 v152, 0x42a00000, v236
	v_min_f32_e32 v153, 0x42a00000, v237
	v_min_f32_e32 v154, 0x42a00000, v238
	v_min_f32_e32 v155, 0x42a00000, v239
	s_waitcnt vmcnt(0)
	v_mfma_f32_16x16x32_bf16 v[236:239], v[16:19], v[48:51], 0
	v_mfma_f32_16x16x32_bf16 v[236:239], v[20:23], v[52:55], v[236:239]
	v_mul_f32_e32 v152, 0x3fb8aa3b, v152
	v_mul_f32_e32 v153, 0x3fb8aa3b, v153
	v_mul_f32_e32 v154, 0x3fb8aa3b, v154
	v_mul_f32_e32 v155, 0x3fb8aa3b, v155
	v_exp_f32_e32 v152, v152
	v_exp_f32_e32 v153, v153
	v_exp_f32_e32 v154, v154
	v_exp_f32_e32 v155, v155
	v_add_u32_e32 v138, 0x60, v175
	v_add_u32_e32 v139, 0x61, v175
	v_add_u32_e32 v140, 0x62, v175
	v_add_u32_e32 v141, 0x63, v175
	v_cmp_gt_u32_e64 s[70:71], s44, v138
	v_cmp_gt_u32_e64 s[72:73], s44, v139
	v_cmp_gt_u32_e64 s[74:75], s44, v140
	v_cmp_gt_u32_e64 s[76:77], s44, v141
	v_cndmask_b32_e64 v152, 0, v152, s[70:71]
	v_cndmask_b32_e64 v153, 0, v153, s[72:73]
	v_cndmask_b32_e64 v154, 0, v154, s[74:75]
	v_cndmask_b32_e64 v155, 0, v155, s[76:77]
	v_add_f32_e32 v132, v132, v152
	v_add_f32_e32 v132, v132, v153
	v_add_f32_e32 v132, v132, v154
	v_add_f32_e32 v132, v132, v155
	v_cvt_pk_bf16_f32 v124, v152, v153
	v_cvt_pk_bf16_f32 v125, v154, v155
	v_min_f32_e32 v152, 0x42a00000, v240
	v_min_f32_e32 v153, 0x42a00000, v241
	v_min_f32_e32 v154, 0x42a00000, v242
	v_min_f32_e32 v155, 0x42a00000, v243
	v_mul_f32_e32 v152, 0x3fb8aa3b, v152
	v_mul_f32_e32 v153, 0x3fb8aa3b, v153
	v_mul_f32_e32 v154, 0x3fb8aa3b, v154
	v_mul_f32_e32 v155, 0x3fb8aa3b, v155
	v_exp_f32_e32 v152, v152
	v_exp_f32_e32 v153, v153
	v_exp_f32_e32 v154, v154
	v_exp_f32_e32 v155, v155
	v_add_u32_e32 v138, 0x70, v175
	v_add_u32_e32 v139, 0x71, v175
	v_add_u32_e32 v140, 0x72, v175
	v_add_u32_e32 v141, 0x73, v175
	v_cmp_gt_u32_e64 s[70:71], s44, v138
	v_cmp_gt_u32_e64 s[72:73], s44, v139
	v_cmp_gt_u32_e64 s[74:75], s44, v140
	v_cmp_gt_u32_e64 s[76:77], s44, v141
	v_cndmask_b32_e64 v152, 0, v152, s[70:71]
	v_cndmask_b32_e64 v153, 0, v153, s[72:73]
	v_cndmask_b32_e64 v154, 0, v154, s[74:75]
	v_cndmask_b32_e64 v155, 0, v155, s[76:77]
	v_add_f32_e32 v132, v132, v152
	v_add_f32_e32 v132, v132, v153
	v_add_f32_e32 v132, v132, v154
	v_add_f32_e32 v132, v132, v155
	v_cvt_pk_bf16_f32 v126, v152, v153
	v_cvt_pk_bf16_f32 v127, v154, v155
	v_min_f32_e32 v152, 0x42a00000, v236
	v_min_f32_e32 v153, 0x42a00000, v237
	v_min_f32_e32 v154, 0x42a00000, v238
	v_min_f32_e32 v155, 0x42a00000, v239
	v_mul_f32_e32 v152, 0x3fb8aa3b, v152
	v_mul_f32_e32 v153, 0x3fb8aa3b, v153
	v_mul_f32_e32 v154, 0x3fb8aa3b, v154
	v_mul_f32_e32 v155, 0x3fb8aa3b, v155
	v_exp_f32_e32 v152, v152
	v_exp_f32_e32 v153, v153
	v_exp_f32_e32 v154, v154
	v_exp_f32_e32 v155, v155
	v_add_u32_e32 v138, 0x80, v175
	v_add_u32_e32 v139, 0x81, v175
	v_add_u32_e32 v140, 0x82, v175
	v_add_u32_e32 v141, 0x83, v175
	v_cmp_gt_u32_e64 s[70:71], s44, v138
	v_cmp_gt_u32_e64 s[72:73], s44, v139
	v_cmp_gt_u32_e64 s[74:75], s44, v140
	v_cmp_gt_u32_e64 s[76:77], s44, v141
	v_cndmask_b32_e64 v152, 0, v152, s[62:63]
	v_cndmask_b32_e64 v153, 0, v153, s[64:65]
	v_cndmask_b32_e64 v154, 0, v154, s[66:67]
	v_cndmask_b32_e64 v155, 0, v155, s[68:69]
	v_cndmask_b32_e64 v152, 0, v152, s[70:71]
	v_cndmask_b32_e64 v153, 0, v153, s[72:73]
	v_cndmask_b32_e64 v154, 0, v154, s[74:75]
	v_cndmask_b32_e64 v155, 0, v155, s[76:77]
	v_add_f32_e32 v132, v132, v152
	v_add_f32_e32 v132, v132, v153
	v_add_f32_e32 v132, v132, v154
	v_add_f32_e32 v132, v132, v155
	v_cvt_pk_bf16_f32 v128, v152, v153
	v_cvt_pk_bf16_f32 v129, v154, v155
	v_add_u32_e32 v134, s42, v160
	v_add_u32_e32 v134, s43, v134
	v_subrev_u32_e32 v135, s15, v134
	v_lshrrev_b32_e32 v136, 4, v135
	v_add_u32_e32 v136, v136, v135
	v_mad_u32_u24 v176, v136, s79, v161
	v_lshl_add_u32 v177, v135, 2, s80
	s_sub_i32 s2, s42, 64
	v_add_u32_e32 v178, s2, v169
	v_and_b32_e32 v135, 3, v134
	v_lshlrev_b32_e32 v135, s13, v135
	v_lshrrev_b32_e32 v136, 2, v134
	v_add_u32_e32 v135, v135, v136
	v_lshl_add_u32 v135, v135, 7, v161
	v_add_u32_e32 v137, 16, v134
	v_and_b32_e32 v135, 3, v137
	v_lshlrev_b32_e32 v135, s13, v135
	v_lshrrev_b32_e32 v136, 2, v137
	v_add_u32_e32 v135, v135, v136
	v_lshl_add_u32 v135, v135, 7, v161
	s_mul_i32 s2, s0, 48
	s_add_i32 s2, s2, s15
	s_add_i32 s2, s2, -64
	v_add_u32_e32 v138, s2, v164
	v_and_b32_e32 v139, 3, v138
	v_lshlrev_b32_e32 v139, s13, v139
	v_bfe_u32 v140, v138, 2, 2
	v_add_u32_e32 v139, v139, v140
	v_lshl_add_u32 v139, v139, 7, v162
	v_ashrrev_i32_e32 v138, 4, v138
	v_med3_i32 v138, v138, 0, s14
	v_lshl_add_u32 v138, v138, 9, v139
	global_load_dwordx4 v[0:3], v138, s[20:21]
	s_mul_i32 s2, s0, 48
	s_add_i32 s2, s2, s15
	s_add_i32 s2, s2, -56
	v_add_u32_e32 v138, s2, v164
	v_and_b32_e32 v139, 3, v138
	v_lshlrev_b32_e32 v139, s13, v139
	v_bfe_u32 v140, v138, 2, 2
	v_add_u32_e32 v139, v139, v140
	v_lshl_add_u32 v139, v139, 7, v162
	v_ashrrev_i32_e32 v138, 4, v138
	v_med3_i32 v138, v138, 0, s14
	v_lshl_add_u32 v138, v138, 9, v139
	global_load_dwordx4 v[4:7], v138, s[20:21]
	s_mul_i32 s2, s0, 48
	s_add_i32 s2, s2, s15
	s_add_i32 s2, s2, -48
	v_add_u32_e32 v138, s2, v164
	v_and_b32_e32 v139, 3, v138
	v_lshlrev_b32_e32 v139, s13, v139
	v_bfe_u32 v140, v138, 2, 2
	v_add_u32_e32 v139, v139, v140
	v_lshl_add_u32 v139, v139, 7, v162
	v_ashrrev_i32_e32 v138, 4, v138
	v_med3_i32 v138, v138, 0, s14
	v_lshl_add_u32 v138, v138, 9, v139
	global_load_dwordx4 v[8:11], v138, s[20:21]
	s_mul_i32 s2, s0, 48
	s_add_i32 s2, s2, s15
	s_add_i32 s2, s2, -40
	v_add_u32_e32 v138, s2, v164
	v_and_b32_e32 v139, 3, v138
	v_lshlrev_b32_e32 v139, s13, v139
	v_bfe_u32 v140, v138, 2, 2
	v_add_u32_e32 v139, v139, v140
	v_lshl_add_u32 v139, v139, 7, v162
	v_ashrrev_i32_e32 v138, 4, v138
	v_med3_i32 v138, v138, 0, s14
	v_lshl_add_u32 v138, v138, 9, v139
	global_load_dwordx4 v[12:15], v138, s[20:21]
	s_mul_i32 s2, s0, 48
	s_add_i32 s2, s2, s15
	s_add_i32 s2, s2, -32
	v_add_u32_e32 v138, s2, v164
	v_and_b32_e32 v139, 3, v138
	v_lshlrev_b32_e32 v139, s13, v139
	v_bfe_u32 v140, v138, 2, 2
	v_add_u32_e32 v139, v139, v140
	v_lshl_add_u32 v139, v139, 7, v162
	v_ashrrev_i32_e32 v138, 4, v138
	v_med3_i32 v138, v138, 0, s14
	v_lshl_add_u32 v138, v138, 9, v139
	global_load_dwordx4 v[16:19], v138, s[20:21]
	s_mul_i32 s2, s0, 48
	s_add_i32 s2, s2, s15
	s_add_i32 s2, s2, -24
	v_add_u32_e32 v138, s2, v164
	v_and_b32_e32 v139, 3, v138
	v_lshlrev_b32_e32 v139, s13, v139
	v_bfe_u32 v140, v138, 2, 2
	v_add_u32_e32 v139, v139, v140
	v_lshl_add_u32 v139, v139, 7, v162
	v_ashrrev_i32_e32 v138, 4, v138
	v_med3_i32 v138, v138, 0, s14
	v_lshl_add_u32 v138, v138, 9, v139
	global_load_dwordx4 v[20:23], v138, s[20:21]
	s_mul_i32 s2, s0, 48
	s_add_i32 s2, s2, s15
	s_add_i32 s2, s2, -64
	v_add_u32_e32 v138, s2, v164
	v_and_b32_e32 v139, 3, v138
	v_lshlrev_b32_e32 v139, s13, v139
	v_bfe_u32 v140, v138, 2, 2
	v_add_u32_e32 v139, v139, v140
	v_lshl_add_u32 v139, v139, 7, v162
	v_ashrrev_i32_e32 v138, 4, v138
	v_med3_i32 v138, v138, 0, s14
	v_lshl_add_u32 v138, v138, 9, v139
	global_load_dwordx4 v[24:27], v138, s[22:23]
	s_mul_i32 s2, s0, 48
	s_add_i32 s2, s2, s15
	s_add_i32 s2, s2, -56
	v_add_u32_e32 v138, s2, v164
	v_and_b32_e32 v139, 3, v138
	v_lshlrev_b32_e32 v139, s13, v139
	v_bfe_u32 v140, v138, 2, 2
	v_add_u32_e32 v139, v139, v140
	v_lshl_add_u32 v139, v139, 7, v162
	v_ashrrev_i32_e32 v138, 4, v138
	v_med3_i32 v138, v138, 0, s14
	v_lshl_add_u32 v138, v138, 9, v139
	global_load_dwordx4 v[28:31], v138, s[22:23]
	s_mul_i32 s2, s0, 48
	s_add_i32 s2, s2, s15
	s_add_i32 s2, s2, -48
	v_add_u32_e32 v138, s2, v164
	v_and_b32_e32 v139, 3, v138
	v_lshlrev_b32_e32 v139, s13, v139
	v_bfe_u32 v140, v138, 2, 2
	v_add_u32_e32 v139, v139, v140
	v_lshl_add_u32 v139, v139, 7, v162
	v_ashrrev_i32_e32 v138, 4, v138
	v_med3_i32 v138, v138, 0, s14
	v_lshl_add_u32 v138, v138, 9, v139
	global_load_dwordx4 v[32:35], v138, s[22:23]
	s_mul_i32 s2, s0, 48
	s_add_i32 s2, s2, s15
	s_add_i32 s2, s2, -40
	v_add_u32_e32 v138, s2, v164
	v_and_b32_e32 v139, 3, v138
	v_lshlrev_b32_e32 v139, s13, v139
	v_bfe_u32 v140, v138, 2, 2
	v_add_u32_e32 v139, v139, v140
	v_lshl_add_u32 v139, v139, 7, v162
	v_ashrrev_i32_e32 v138, 4, v138
	v_med3_i32 v138, v138, 0, s14
	v_lshl_add_u32 v138, v138, 9, v139
	global_load_dwordx4 v[36:39], v138, s[22:23]
	s_mul_i32 s2, s0, 48
	s_add_i32 s2, s2, s15
	s_add_i32 s2, s2, -32
	v_add_u32_e32 v138, s2, v164
	v_and_b32_e32 v139, 3, v138
	v_lshlrev_b32_e32 v139, s13, v139
	v_bfe_u32 v140, v138, 2, 2
	v_add_u32_e32 v139, v139, v140
	v_lshl_add_u32 v139, v139, 7, v162
	v_ashrrev_i32_e32 v138, 4, v138
	v_med3_i32 v138, v138, 0, s14
	v_lshl_add_u32 v138, v138, 9, v139
	global_load_dwordx4 v[40:43], v138, s[22:23]
	s_mul_i32 s2, s0, 48
	s_add_i32 s2, s2, s15
	s_add_i32 s2, s2, -24
	v_add_u32_e32 v138, s2, v164
	v_and_b32_e32 v139, 3, v138
	v_lshlrev_b32_e32 v139, s13, v139
	v_bfe_u32 v140, v138, 2, 2
	v_add_u32_e32 v139, v139, v140
	v_lshl_add_u32 v139, v139, 7, v162
	v_ashrrev_i32_e32 v138, 4, v138
	v_med3_i32 v138, v138, 0, s14
	v_lshl_add_u32 v138, v138, 9, v139
	global_load_dwordx4 v[44:47], v138, s[22:23]
	s_lshl_b32 s2, s0, 5
	s_add_i32 s2, s2, s15
	s_add_i32 s2, s2, 0
	v_add_u32_e32 v138, s2, v164
	v_and_b32_e32 v139, 3, v138
	v_lshlrev_b32_e32 v139, s13, v139
	v_lshrrev_b32_e32 v140, 2, v138
	v_add_u32_e32 v139, v139, v140
	v_lshl_add_u32 v139, v139, 7, v162
	global_load_dwordx4 v[48:51], v139, s[18:19]
	s_lshl_b32 s2, s0, 5
	s_add_i32 s2, s2, s15
	s_add_i32 s2, s2, 8
	v_add_u32_e32 v138, s2, v164
	v_and_b32_e32 v139, 3, v138
	v_lshlrev_b32_e32 v139, s13, v139
	v_lshrrev_b32_e32 v140, 2, v138
	v_add_u32_e32 v139, v139, v140
	v_lshl_add_u32 v139, v139, 7, v162
	global_load_dwordx4 v[52:55], v139, s[18:19]
	s_lshl_b32 s2, s0, 5
	s_add_i32 s2, s2, s15
	s_add_i32 s2, s2, 16
	v_add_u32_e32 v138, s2, v164
	v_and_b32_e32 v139, 3, v138
	v_lshlrev_b32_e32 v139, s13, v139
	v_lshrrev_b32_e32 v140, 2, v138
	v_add_u32_e32 v139, v139, v140
	v_lshl_add_u32 v139, v139, 7, v162
	global_load_dwordx4 v[56:59], v139, s[18:19]
	s_lshl_b32 s2, s0, 5
	s_add_i32 s2, s2, s15
	s_add_i32 s2, s2, 24
	v_add_u32_e32 v138, s2, v164
	v_and_b32_e32 v139, 3, v138
	v_lshlrev_b32_e32 v139, s13, v139
	v_lshrrev_b32_e32 v140, 2, v138
	v_add_u32_e32 v139, v139, v140
	v_lshl_add_u32 v139, v139, 7, v162
	global_load_dwordx4 v[60:63], v139, s[18:19]
	ds_bpermute_b32 v142, v167, v132
	s_waitcnt lgkmcnt(0)
	v_add_f32_e32 v132, v132, v142
	ds_bpermute_b32 v142, v168, v132
	s_waitcnt lgkmcnt(0)
	v_add_f32_e32 v132, v132, v142
	s_waitcnt vmcnt(16)
	ds_write_b128 v165, v[64:67]
	ds_write_b128 v165, v[68:71] offset:1152
	ds_write_b128 v165, v[72:75] offset:2304
	ds_write_b128 v165, v[76:79] offset:3456
	s_waitcnt lgkmcnt(0)
	ds_read_b64_tr_b16 v[236:237], v166
	ds_read_b64_tr_b16 v[238:239], v166 offset:2304
	ds_read_b64_tr_b16 v[240:241], v166 offset:32
	ds_read_b64_tr_b16 v[242:243], v166 offset:2336
	ds_read_b64_tr_b16 v[244:245], v166 offset:64
	ds_read_b64_tr_b16 v[246:247], v166 offset:2368
	ds_read_b64_tr_b16 v[248:249], v166 offset:96
	ds_read_b64_tr_b16 v[250:251], v166 offset:2400
	s_waitcnt lgkmcnt(0)
	s_add_i32 s2, s40, 32
	v_add_u32_e32 v138, s2, v164
	v_lshlrev_b32_e32 v138, 4, v138
	v_add_u32_e32 v138, s41, v138
	v_and_b32_e32 v139, 3, v138
	v_lshlrev_b32_e32 v139, s39, v139
	v_bfe_u32 v140, v138, 2, 2
	v_add_u32_e32 v139, v139, v140
	v_lshl_add_u32 v139, v139, 7, v162
	v_ashrrev_i32_e32 v138, 4, v138
	v_med3_i32 v138, v138, 0, s38
	v_lshl_add_u32 v138, v138, 9, v139
	global_load_dwordx4 v[64:67], v138, s[26:27]
	s_add_i32 s2, s40, 40
	v_add_u32_e32 v138, s2, v164
	v_lshlrev_b32_e32 v138, 4, v138
	v_add_u32_e32 v138, s41, v138
	v_and_b32_e32 v139, 3, v138
	v_lshlrev_b32_e32 v139, s39, v139
	v_bfe_u32 v140, v138, 2, 2
	v_add_u32_e32 v139, v139, v140
	v_lshl_add_u32 v139, v139, 7, v162
	v_ashrrev_i32_e32 v138, 4, v138
	v_med3_i32 v138, v138, 0, s38
	v_lshl_add_u32 v138, v138, 9, v139
	global_load_dwordx4 v[68:71], v138, s[26:27]
	s_add_i32 s2, s40, 48
	v_add_u32_e32 v138, s2, v164
	v_lshlrev_b32_e32 v138, 4, v138
	v_add_u32_e32 v138, s41, v138
	v_and_b32_e32 v139, 3, v138
	v_lshlrev_b32_e32 v139, s39, v139
	v_bfe_u32 v140, v138, 2, 2
	v_add_u32_e32 v139, v139, v140
	v_lshl_add_u32 v139, v139, 7, v162
	v_ashrrev_i32_e32 v138, 4, v138
	v_med3_i32 v138, v138, 0, s38
	v_lshl_add_u32 v138, v138, 9, v139
	global_load_dwordx4 v[72:75], v138, s[26:27]
	s_add_i32 s2, s40, 56
	v_add_u32_e32 v138, s2, v164
	v_lshlrev_b32_e32 v138, 4, v138
	v_add_u32_e32 v138, s41, v138
	v_and_b32_e32 v139, 3, v138
	v_lshlrev_b32_e32 v139, s39, v139
	v_bfe_u32 v140, v138, 2, 2
	v_add_u32_e32 v139, v139, v140
	v_lshl_add_u32 v139, v139, 7, v162
	v_ashrrev_i32_e32 v138, 4, v138
	v_med3_i32 v138, v138, 0, s38
	v_lshl_add_u32 v138, v138, 9, v139
	global_load_dwordx4 v[76:79], v138, s[26:27]
	ds_write_b128 v165, v[80:83]
	ds_write_b128 v165, v[84:87] offset:1152
	ds_write_b128 v165, v[88:91] offset:2304
	ds_write_b128 v165, v[92:95] offset:3456
	v_mfma_f32_16x16x32_bf16 v[204:207], v[236:239], v[112:115], 0
	v_mfma_f32_16x16x32_bf16 v[208:211], v[240:243], v[112:115], 0
	v_mfma_f32_16x16x32_bf16 v[212:215], v[244:247], v[112:115], 0
	v_mfma_f32_16x16x32_bf16 v[216:219], v[248:251], v[112:115], 0
	s_waitcnt lgkmcnt(0)
	ds_read_b64_tr_b16 v[236:237], v166
	ds_read_b64_tr_b16 v[238:239], v166 offset:2304
	ds_read_b64_tr_b16 v[240:241], v166 offset:32
	ds_read_b64_tr_b16 v[242:243], v166 offset:2336
	ds_read_b64_tr_b16 v[244:245], v166 offset:64
	ds_read_b64_tr_b16 v[246:247], v166 offset:2368
	ds_read_b64_tr_b16 v[248:249], v166 offset:96
	ds_read_b64_tr_b16 v[250:251], v166 offset:2400
	s_waitcnt lgkmcnt(0)
	s_add_i32 s2, s40, 64
	v_add_u32_e32 v138, s2, v164
	v_lshlrev_b32_e32 v138, 4, v138
	v_add_u32_e32 v138, s41, v138
	v_and_b32_e32 v139, 3, v138
	v_lshlrev_b32_e32 v139, s39, v139
	v_bfe_u32 v140, v138, 2, 2
	v_add_u32_e32 v139, v139, v140
	v_lshl_add_u32 v139, v139, 7, v162
	v_ashrrev_i32_e32 v138, 4, v138
	v_med3_i32 v138, v138, 0, s38
	v_lshl_add_u32 v138, v138, 9, v139
	global_load_dwordx4 v[80:83], v138, s[26:27]
	s_add_i32 s2, s40, 72
	v_add_u32_e32 v138, s2, v164
	v_lshlrev_b32_e32 v138, 4, v138
	v_add_u32_e32 v138, s41, v138
	v_and_b32_e32 v139, 3, v138
	v_lshlrev_b32_e32 v139, s39, v139
	v_bfe_u32 v140, v138, 2, 2
	v_add_u32_e32 v139, v139, v140
	v_lshl_add_u32 v139, v139, 7, v162
	v_ashrrev_i32_e32 v138, 4, v138
	v_med3_i32 v138, v138, 0, s38
	v_lshl_add_u32 v138, v138, 9, v139
	global_load_dwordx4 v[84:87], v138, s[26:27]
	ds_write_b128 v165, v[96:99]
	ds_write_b128 v165, v[100:103] offset:1152
	ds_write_b128 v165, v[104:107] offset:2304
	ds_write_b128 v165, v[108:111] offset:3456
	v_mfma_f32_16x16x32_bf16 v[204:207], v[236:239], v[116:119], v[204:207]
	v_mfma_f32_16x16x32_bf16 v[208:211], v[240:243], v[116:119], v[208:211]
	v_mfma_f32_16x16x32_bf16 v[212:215], v[244:247], v[116:119], v[212:215]
	v_mfma_f32_16x16x32_bf16 v[216:219], v[248:251], v[116:119], v[216:219]
	s_waitcnt lgkmcnt(0)
	ds_read_b64_tr_b16 v[236:237], v166
	ds_read_b64_tr_b16 v[238:239], v166 offset:2304
	ds_read_b64_tr_b16 v[240:241], v166 offset:32
	ds_read_b64_tr_b16 v[242:243], v166 offset:2336
	ds_read_b64_tr_b16 v[244:245], v166 offset:64
	ds_read_b64_tr_b16 v[246:247], v166 offset:2368
	ds_read_b64_tr_b16 v[248:249], v166 offset:96
	ds_read_b64_tr_b16 v[250:251], v166 offset:2400
	s_waitcnt lgkmcnt(0)
	s_waitcnt vmcnt(2)
	ds_write_b128 v165, v[64:67]
	ds_write_b128 v165, v[68:71] offset:1152
	ds_write_b128 v165, v[72:75] offset:2304
	ds_write_b128 v165, v[76:79] offset:3456
	v_mfma_f32_16x16x32_bf16 v[204:207], v[236:239], v[120:123], v[204:207]
	v_mfma_f32_16x16x32_bf16 v[208:211], v[240:243], v[120:123], v[208:211]
	v_mfma_f32_16x16x32_bf16 v[212:215], v[244:247], v[120:123], v[212:215]
	v_mfma_f32_16x16x32_bf16 v[216:219], v[248:251], v[120:123], v[216:219]
	s_waitcnt lgkmcnt(0)
	ds_read_b64_tr_b16 v[236:237], v166
	ds_read_b64_tr_b16 v[238:239], v166 offset:2304
	ds_read_b64_tr_b16 v[240:241], v166 offset:32
	ds_read_b64_tr_b16 v[242:243], v166 offset:2336
	ds_read_b64_tr_b16 v[244:245], v166 offset:64
	ds_read_b64_tr_b16 v[246:247], v166 offset:2368
	ds_read_b64_tr_b16 v[248:249], v166 offset:96
	ds_read_b64_tr_b16 v[250:251], v166 offset:2400
	s_waitcnt lgkmcnt(0)
	s_waitcnt vmcnt(0)
	ds_write_b128 v165, v[80:83]
	ds_write_b128 v165, v[84:87] offset:1152
	v_mfma_f32_16x16x32_bf16 v[204:207], v[236:239], v[124:127], v[204:207]
	v_mfma_f32_16x16x32_bf16 v[208:211], v[240:243], v[124:127], v[208:211]
	v_mfma_f32_16x16x32_bf16 v[212:215], v[244:247], v[124:127], v[212:215]
	v_mfma_f32_16x16x32_bf16 v[216:219], v[248:251], v[124:127], v[216:219]
	s_waitcnt lgkmcnt(0)
	ds_read_b64_tr_b16 v[236:237], v166
	ds_read_b64_tr_b16 v[238:239], v166 offset:2304
	ds_read_b64_tr_b16 v[240:241], v166 offset:32
	ds_read_b64_tr_b16 v[242:243], v166 offset:2336
	ds_read_b64_tr_b16 v[244:245], v166 offset:64
	ds_read_b64_tr_b16 v[246:247], v166 offset:2368
	ds_read_b64_tr_b16 v[248:249], v166 offset:96
	ds_read_b64_tr_b16 v[250:251], v166 offset:2400
	s_waitcnt lgkmcnt(0)
	v_mfma_f32_16x16x32_bf16 v[204:207], v[236:239], v[128:131], v[204:207]
	v_mfma_f32_16x16x32_bf16 v[208:211], v[240:243], v[128:131], v[208:211]
	v_mfma_f32_16x16x32_bf16 v[212:215], v[244:247], v[128:131], v[212:215]
	v_mfma_f32_16x16x32_bf16 v[216:219], v[248:251], v[128:131], v[216:219]
	ds_read_b128 v[236:239], v173 offset:0
	ds_read_b128 v[240:243], v173 offset:64
	ds_read_b128 v[244:247], v173 offset:128
	ds_read_b128 v[248:251], v173 offset:192
	ds_read_b32 v142, v174 offset:0
	s_waitcnt lgkmcnt(0)
	v_add_f32_e32 v204, v236, v204
	v_add_f32_e32 v205, v237, v205
	v_add_f32_e32 v206, v238, v206
	v_add_f32_e32 v207, v239, v207
	v_add_f32_e32 v208, v240, v208
	v_add_f32_e32 v209, v241, v209
	v_add_f32_e32 v210, v242, v210
	v_add_f32_e32 v211, v243, v211
	v_add_f32_e32 v212, v244, v212
	v_add_f32_e32 v213, v245, v213
	v_add_f32_e32 v214, v246, v214
	v_add_f32_e32 v215, v247, v215
	v_add_f32_e32 v216, v248, v216
	v_add_f32_e32 v217, v249, v217
	v_add_f32_e32 v218, v250, v218
	v_add_f32_e32 v219, v251, v219
	v_add_f32_e32 v132, v142, v132
	ds_write_b128 v173, v[204:207] offset:0
	ds_write_b128 v173, v[208:211] offset:64
	ds_write_b128 v173, v[212:215] offset:128
	ds_write_b128 v173, v[216:219] offset:192
	ds_write_b32 v174, v132 offset:0
	s_waitcnt lgkmcnt(0)
	s_barrier
	ds_read_b128 v[204:207], v170
	ds_read_b128 v[208:211], v170 offset:16
	ds_read_b128 v[212:215], v170 offset:32
	ds_read_b128 v[216:219], v170 offset:48
	ds_read_b128 v[220:223], v170 offset:64
	ds_read_b128 v[224:227], v170 offset:80
	ds_read_b128 v[228:231], v170 offset:96
	ds_read_b128 v[232:235], v170 offset:112
	ds_read_b32 v142, v171
	s_lshl_b32 s2, s35, 11
	s_lshl_b32 s3, s36, 7
	s_add_u32 s2, s2, s3
	s_add_u32 s90, s6, s2
	s_addc_u32 s91, s7, 0
	s_waitcnt lgkmcnt(0)
	v_div_scale_f32 v143, s[30:31], v142, v142, 1.0
	v_rcp_f32_e32 v147, v143
	v_div_scale_f32 v134, vcc, 1.0, v142, 1.0
	v_fma_f32 v135, -v143, v147, 1.0
	v_fmac_f32_e32 v147, v135, v147
	v_mul_f32_e32 v135, v134, v147
	v_fma_f32 v136, -v143, v135, v134
	v_fmac_f32_e32 v135, v136, v147
	v_fma_f32 v143, -v143, v135, v134
	v_div_fmas_f32 v143, v143, v147, v135
	v_div_fixup_f32 v142, v143, v142, 1.0
	v_mul_f32_e32 v204, v142, v204
	v_mul_f32_e32 v205, v142, v205
	v_mul_f32_e32 v206, v142, v206
	v_mul_f32_e32 v207, v142, v207
	v_mul_f32_e32 v208, v142, v208
	v_mul_f32_e32 v209, v142, v209
	v_mul_f32_e32 v210, v142, v210
	v_mul_f32_e32 v211, v142, v211
	v_mul_f32_e32 v212, v142, v212
	v_mul_f32_e32 v213, v142, v213
	v_mul_f32_e32 v214, v142, v214
	v_mul_f32_e32 v215, v142, v215
	v_mul_f32_e32 v216, v142, v216
	v_mul_f32_e32 v217, v142, v217
	v_mul_f32_e32 v218, v142, v218
	v_mul_f32_e32 v219, v142, v219
	v_mul_f32_e32 v220, v142, v220
	v_mul_f32_e32 v221, v142, v221
	v_mul_f32_e32 v222, v142, v222
	v_mul_f32_e32 v223, v142, v223
	v_mul_f32_e32 v224, v142, v224
	v_mul_f32_e32 v225, v142, v225
	v_mul_f32_e32 v226, v142, v226
	v_mul_f32_e32 v227, v142, v227
	v_mul_f32_e32 v228, v142, v228
	v_mul_f32_e32 v229, v142, v229
	v_mul_f32_e32 v230, v142, v230
	v_mul_f32_e32 v231, v142, v231
	v_mul_f32_e32 v232, v142, v232
	v_mul_f32_e32 v233, v142, v233
	v_mul_f32_e32 v234, v142, v234
	v_mul_f32_e32 v235, v142, v235
	v_cvt_pk_bf16_f32 v112, v204, v205
	v_cvt_pk_bf16_f32 v113, v206, v207
	v_cvt_pk_bf16_f32 v114, v208, v209
	v_cvt_pk_bf16_f32 v115, v210, v211
	v_cvt_pk_bf16_f32 v116, v212, v213
	v_cvt_pk_bf16_f32 v117, v214, v215
	v_cvt_pk_bf16_f32 v118, v216, v217
	v_cvt_pk_bf16_f32 v119, v218, v219
	v_cvt_pk_bf16_f32 v120, v220, v221
	v_cvt_pk_bf16_f32 v121, v222, v223
	v_cvt_pk_bf16_f32 v122, v224, v225
	v_cvt_pk_bf16_f32 v123, v226, v227
	v_cvt_pk_bf16_f32 v124, v228, v229
	v_cvt_pk_bf16_f32 v125, v230, v231
	v_cvt_pk_bf16_f32 v126, v232, v233
	v_cvt_pk_bf16_f32 v127, v234, v235
	global_store_dwordx4 v172, v[112:115], s[90:91] nt
	global_store_dwordx4 v172, v[116:119], s[90:91] offset:16 nt
	global_store_dwordx4 v172, v[120:123], s[90:91] offset:32 nt
	global_store_dwordx4 v172, v[124:127], s[90:91] offset:48 nt
	s_barrier
	s_cmp_eq_u32 s37, 0
	s_cbranch_scc1 .Latt_unit
	s_waitcnt vmcnt(0)
	s_branch .LBB0_365
